# attnbr + strategy 7 (instruction selection): drop the 0+x add in attention row sums; second V staging write uses first write's address + offset:8192 (one v_add_u32 less per tile)
# baseline (speedup 1.0000x reference)
; #define SBAR() __builtin_amdgcn_sched_barrier(0)
; __device__ __forceinline__ void finishSM(f32x16& p0, f32x16& p1, float alpha, float& l_reg, bf16x8& pa0, bf16x8& pa1, bf16x8& pa2, bf16x8& pa3) {
; #pragma unroll
;   for (int r = 0; r < 16; ++r) p1[r] = __builtin_amdgcn_exp2f(p1[r]);
;   float ps = 0;
; #pragma unroll
;   for (int r = 0; r < 16; ++r) ps += p0[r];
; #pragma unroll
;   for (int r = 0; r < 16; ++r) ps += p1[r];
;   { auto rr = __builtin_amdgcn_permlane32_swap(__float_as_uint(ps), __float_as_uint(ps), false, false);
;     ps = __uint_as_float(rr[0]) + __uint_as_float(rr[1]); }
;   l_reg = l_reg * alpha + ps;
;     ...
;   PK4(p0, 0, pa0); PK4(p0, 8, pa1); PK4(p1, 0, pa2); PK4(p1, 8, pa3);
;     ...
; }
; __device__ __forceinline__ void qkt(f32x16& p0, f32x16& p1, const char* Ks, const bf16x8* qr, int r32, int hi) {
;   bf16x8 ka[4], kb[4];
; #pragma unroll
;   for (int d0 = 0; d0 < 4; ++d0) { const int cb = (d0 * 16 + hi * 8) * 2;
;     ka[d0] = *reinterpret_cast<const bf16x8*>(Ks + KSWZ64(r32, cb)); kb[d0] = *reinterpret_cast<const bf16x8*>(Ks + KSWZ64(32 + r32, cb)); }
;   asm volatile("s_waitcnt lgkmcnt(0)" ::: "memory"); SBAR();
;   p0 = f32x16{}; p1 = f32x16{};
; #pragma unroll
;   for (int d0 = 0; d0 < 4; ++d0) {
;     p0 = __builtin_amdgcn_mfma_f32_32x32x16_bf16(ka[d0], qr[d0], p0, 0, 0, 0);
;     p1 = __builtin_amdgcn_mfma_f32_32x32x16_bf16(kb[d0], qr[d0], p1, 0, 0, 0); }
.LBB0_301:
	s_mov_b32 s68, s64
	s_mov_b32 s64, s0
	v_add_f32_e32 v96, v143, v141
	v_add_f32_e32 v96, v139, v96
	v_add_f32_e32 v96, v142, v96
	v_add_f32_e32 v96, v137, v96
	v_add_f32_e32 v96, v140, v96
	v_add_f32_e32 v96, v136, v96
	v_add_f32_e32 v96, v138, v96
	v_add_f32_e32 v96, v133, v96
	v_add_f32_e32 v96, v135, v96
	v_add_f32_e32 v96, v131, v96
	v_add_f32_e32 v96, v134, v96
	v_exp_f32_e32 v80, v80
	v_add_f32_e32 v96, v129, v96
	v_exp_f32_e32 v81, v81
	v_add_f32_e32 v96, v132, v96
	v_exp_f32_e32 v82, v82
	v_add_f32_e32 v96, v128, v96
	v_exp_f32_e32 v83, v83
	v_add_f32_e32 v96, v130, v96
	v_exp_f32_e32 v84, v84
	v_add_f32_e32 v96, v80, v96
	v_exp_f32_e32 v85, v85
	v_add_f32_e32 v96, v81, v96
	v_exp_f32_e32 v86, v86
	v_add_f32_e32 v96, v82, v96
	v_exp_f32_e32 v87, v87
	v_add_f32_e32 v96, v83, v96
	v_exp_f32_e32 v88, v88
	v_add_f32_e32 v96, v84, v96
	v_exp_f32_e32 v89, v89
	v_add_f32_e32 v96, v85, v96
	v_exp_f32_e32 v90, v90
	v_add_f32_e32 v96, v86, v96
	v_exp_f32_e32 v91, v91
	v_add_f32_e32 v96, v87, v96
	v_exp_f32_e32 v92, v92
	v_add_f32_e32 v96, v88, v96
	v_exp_f32_e32 v93, v93
	v_add_f32_e32 v96, v89, v96
	v_exp_f32_e32 v94, v94
	v_add_f32_e32 v96, v90, v96
	v_exp_f32_e32 v95, v95
	v_add_f32_e32 v96, v91, v96
	v_add_f32_e32 v96, v92, v96
	v_add_f32_e32 v96, v93, v96
	v_add_f32_e32 v96, v94, v96
	v_add_f32_e32 v241, v95, v96
	v_mov_b32_e32 v242, v241
	v_cvt_pk_bf16_f32 v180, v141, v143
	v_cvt_pk_bf16_f32 v181, v139, v142
	v_cvt_pk_bf16_f32 v182, v137, v140
	v_cvt_pk_bf16_f32 v183, v136, v138
	v_cvt_pk_bf16_f32 v184, v133, v135
	v_cvt_pk_bf16_f32 v185, v131, v134
	v_cvt_pk_bf16_f32 v186, v129, v132
	v_cvt_pk_bf16_f32 v187, v128, v130
	v_cvt_pk_bf16_f32 v188, v80, v81
	v_cvt_pk_bf16_f32 v189, v82, v83
	v_cvt_pk_bf16_f32 v190, v84, v85
	v_cvt_pk_bf16_f32 v191, v86, v87
	v_cvt_pk_bf16_f32 v192, v88, v89
	v_cvt_pk_bf16_f32 v193, v90, v91
	v_cvt_pk_bf16_f32 v194, v92, v93
	v_cvt_pk_bf16_f32 v195, v94, v95
	s_nop 1
	v_permlane32_swap_b32_e32 v241, v242
	v_permlane32_swap_b32_e32 v180, v182
	v_permlane32_swap_b32_e32 v181, v183
	v_permlane32_swap_b32_e32 v184, v186
	v_permlane32_swap_b32_e32 v185, v187
	v_permlane32_swap_b32_e32 v188, v190
	v_permlane32_swap_b32_e32 v189, v191
	v_permlane32_swap_b32_e32 v192, v194
	v_permlane32_swap_b32_e32 v193, v195
	s_lshl_b32 s0, s68, 13
	s_add_i32 s4, s0, 0
	v_add_u32_e32 v84, s4, v224
	v_add_u32_e32 v92, s4, v227
	v_add_u32_e32 v96, s4, v229
	ds_read_b128 v[80:83], v84 offset:49152
	ds_read_b128 v[84:87], v84 offset:53248
	ds_read_b128 v[88:91], v92 offset:49152
	ds_read_b128 v[92:95], v92 offset:53248
	ds_read_b128 v[128:131], v96 offset:49152
	ds_read_b128 v[132:135], v96 offset:53248
	v_add_u32_e32 v96, s4, v230
	ds_read_b128 v[136:139], v96 offset:49152
	ds_read_b128 v[140:143], v96 offset:53248
	s_waitcnt lgkmcnt(0)
	s_waitcnt lgkmcnt(7)
	v_mfma_f32_32x32x16_bf16 v[112:127], v[80:83], v[164:167], 0
	s_waitcnt lgkmcnt(6)
	v_mfma_f32_32x32x16_bf16 v[96:111], v[84:87], v[164:167], 0
	s_waitcnt lgkmcnt(5)
	v_mfma_f32_32x32x16_bf16 v[112:127], v[88:91], v[160:163], v[112:127]
	s_waitcnt lgkmcnt(4)
	v_mfma_f32_32x32x16_bf16 v[96:111], v[92:95], v[160:163], v[96:111]
	s_waitcnt lgkmcnt(3)
	v_mfma_f32_32x32x16_bf16 v[112:127], v[128:131], v[156:159], v[112:127]
	s_waitcnt lgkmcnt(2)
	v_mfma_f32_32x32x16_bf16 v[96:111], v[132:135], v[156:159], v[96:111]
	s_waitcnt lgkmcnt(1)
	v_mfma_f32_32x32x16_bf16 v[112:127], v[136:139], v[152:155], v[112:127]
	s_waitcnt lgkmcnt(0)
	v_mfma_f32_32x32x16_bf16 v[96:111], v[140:143], v[152:155], v[96:111]
	s_add_u32 s74, s70, s15
	s_addc_u32 s75, s71, 0
	global_load_dwordx4 v[168:171], v202, s[74:75] offset:2048
	s_add_u32 s74, s70, 0x18dc0000
	s_addc_u32 s75, s71, 0
	global_load_dwordx4 v[172:175], v202, s[74:75] offset:2048
	s_add_u32 s74, s72, 0x18d80000
	s_addc_u32 s75, s73, 0
	global_load_dwordx4 v[176:179], v204, s[74:75] offset:1024
	s_add_i32 s0, s65, 0xffffff47
	s_cmp_gt_u32 s0, 0xfffffeec
	s_mov_b64 s[0:1], -1
	s_cbranch_scc0 .Lfastp_9
; __device__ __forceinline__ void partialSM(f32x16& p0, f32x16& p1, float& m_reg, float& mn, float& alpha, int kt0, int qpos, int qw, int hi, const float* tb2, float cL, float cR) {
;     ...
;     const float* tp = tb2 + (kt0 - qpos + 192 + 4 * hi);
; #pragma unroll
;     for (int r4 = 0; r4 < 4; ++r4) {
;       float ta[4], tb[4];
; #pragma unroll
;       for (int i = 0; i < 4; ++i) { ta[i] = tp[8 * r4 + i] - m_reg; tb[i] = tp[32 + 8 * r4 + i] - m_reg; }
; #pragma unroll
;       for (int i = 0; i < 4; ++i) { p0[4 * r4 + i] = fmaf(p0[4 * r4 + i], C1, ta[i]); p1[4 * r4 + i] = fmaf(p1[4 * r4 + i], C1, tb[i]); }
;       asm volatile("" ::: "memory");
;     }
	ds_read2_b32 v[80:81], v240 offset1:1
	ds_read2_b32 v[82:83], v240 offset0:32 offset1:33
	ds_read2_b32 v[84:85], v240 offset0:34 offset1:35
	ds_read2_b32 v[86:87], v240 offset0:2 offset1:3
	ds_read2_b32 v[88:89], v240 offset0:8 offset1:9
	ds_read2_b32 v[90:91], v240 offset0:40 offset1:41
	ds_read2_b32 v[92:93], v240 offset0:42 offset1:43
	ds_read2_b32 v[94:95], v240 offset0:10 offset1:11
	ds_read2_b32 v[128:129], v240 offset0:16 offset1:17
	ds_read2_b32 v[244:245], v240 offset0:48 offset1:49
	ds_read2_b32 v[246:247], v240 offset0:50 offset1:51
	ds_read2_b32 v[130:131], v240 offset0:18 offset1:19
	s_waitcnt lgkmcnt(11)
	v_sub_f32_e32 v81, v81, v1
	v_sub_f32_e32 v80, v80, v0
	ds_read2_b32 v[132:133], v240 offset0:24 offset1:25
	ds_read2_b32 v[134:135], v240 offset0:26 offset1:27
	ds_read2_b32 v[248:249], v240 offset0:56 offset1:57
	s_waitcnt lgkmcnt(6)
	v_sub_f32_e32 v137, v129, v75
	v_sub_f32_e32 v136, v128, v72
	v_pk_fma_f32 v[128:129], v[112:113], s[6:7], v[80:81] op_sel_hi:[1,0,1]
	ds_read2_b32 v[80:81], v240 offset0:58 offset1:59
	v_sub_f32_e32 v89, v89, v69
	v_sub_f32_e32 v88, v88, v68
	v_sub_f32_e32 v95, v95, v71
	v_sub_f32_e32 v94, v94, v70
	v_sub_f32_e32 v87, v87, v67
	v_sub_f32_e32 v86, v86, v66
	s_waitcnt lgkmcnt(3)
	v_sub_f32_e32 v141, v133, v79
	v_sub_f32_e32 v140, v132, v78
	s_waitcnt lgkmcnt(2)
	v_sub_f32_e32 v143, v135, v77
	v_sub_f32_e32 v142, v134, v76
	v_sub_f32_e32 v139, v131, v73
	v_sub_f32_e32 v138, v130, v74
	v_pk_fma_f32 v[130:131], v[114:115], s[6:7], v[86:87] op_sel_hi:[1,0,1]
	v_pk_fma_f32 v[134:135], v[118:119], s[6:7], v[94:95] op_sel_hi:[1,0,1]
	v_pk_fma_f32 v[132:133], v[116:117], s[6:7], v[88:89] op_sel_hi:[1,0,1]
	s_waitcnt lgkmcnt(1)
	v_sub_f32_e32 v249, v249, v79
	v_sub_f32_e32 v248, v248, v78
	s_waitcnt lgkmcnt(0)
	v_sub_f32_e32 v95, v81, v77
	v_sub_f32_e32 v94, v80, v76
	v_sub_f32_e32 v89, v245, v75
	v_sub_f32_e32 v88, v244, v72
	v_sub_f32_e32 v245, v247, v73
	v_sub_f32_e32 v244, v246, v74
	v_sub_f32_e32 v91, v91, v69
	v_sub_f32_e32 v90, v90, v68
	v_sub_f32_e32 v87, v93, v71
	v_sub_f32_e32 v86, v92, v70
	v_sub_f32_e32 v81, v83, v1
	v_sub_f32_e32 v80, v82, v0
	v_sub_f32_e32 v83, v85, v67
	v_sub_f32_e32 v82, v84, v66
	v_pk_fma_f32 v[138:139], v[122:123], s[6:7], v[138:139] op_sel_hi:[1,0,1]
	v_pk_fma_f32 v[136:137], v[120:121], s[6:7], v[136:137] op_sel_hi:[1,0,1]
	v_pk_fma_f32 v[142:143], v[126:127], s[6:7], v[142:143] op_sel_hi:[1,0,1]
	v_pk_fma_f32 v[140:141], v[124:125], s[6:7], v[140:141] op_sel_hi:[1,0,1]
	v_pk_fma_f32 v[82:83], v[98:99], s[6:7], v[82:83] op_sel_hi:[1,0,1]
	v_pk_fma_f32 v[80:81], v[96:97], s[6:7], v[80:81] op_sel_hi:[1,0,1]
	v_pk_fma_f32 v[86:87], v[102:103], s[6:7], v[86:87] op_sel_hi:[1,0,1]
	v_pk_fma_f32 v[84:85], v[100:101], s[6:7], v[90:91] op_sel_hi:[1,0,1]
	v_pk_fma_f32 v[90:91], v[106:107], s[6:7], v[244:245] op_sel_hi:[1,0,1]
	v_pk_fma_f32 v[88:89], v[104:105], s[6:7], v[88:89] op_sel_hi:[1,0,1]
	v_pk_fma_f32 v[94:95], v[110:111], s[6:7], v[94:95] op_sel_hi:[1,0,1]
	v_pk_fma_f32 v[92:93], v[108:109], s[6:7], v[248:249] op_sel_hi:[1,0,1]
	s_mov_b64 s[0:1], 0

; #define SBAR() __builtin_amdgcn_sched_barrier(0)
; __device__ __forceinline__ void partialSM(f32x16& p0, f32x16& p1, float& m_reg, float& mn, float& alpha, int kt0, int qpos, int qw, int hi, const float* tb2, float cL, float cR) {
;     ...
;   for (int r = 0; r < 16; ++r) p0[r] = __builtin_amdgcn_exp2f(p0[r]);
; template <int D0> __device__ __forceinline__ void pv_one(f32x16& od, int vb, bf16x8 pa0, bf16x8 pa1, bf16x8 pa2, bf16x8 pa3) {
;   const s16x4 l0 = tr_read<v_rd_off(D0, 0, 0)>(vb), h0 = tr_read<v_rd_off(D0, 0, 1)>(vb), l1 = tr_read<v_rd_off(D0, 1, 0)>(vb), h1 = tr_read<v_rd_off(D0, 1, 1)>(vb);
;   const s16x4 l2 = tr_read<v_rd_off(D0, 2, 0)>(vb), h2 = tr_read<v_rd_off(D0, 2, 1)>(vb), l3 = tr_read<v_rd_off(D0, 3, 0)>(vb), h3 = tr_read<v_rd_off(D0, 3, 1)>(vb);
;   asm volatile("s_waitcnt lgkmcnt(0)" ::: "memory"); SBAR();
;     ...
;   od = __builtin_amdgcn_mfma_f32_32x32x16_bf16(pa0, PK(l0, h0), od, 0, 0, 0);
;   od = __builtin_amdgcn_mfma_f32_32x32x16_bf16(pa1, PK(l1, h1), od, 0, 0, 0);
;   od = __builtin_amdgcn_mfma_f32_32x32x16_bf16(pa2, PK(l2, h2), od, 0, 0, 0);
;   od = __builtin_amdgcn_mfma_f32_32x32x16_bf16(pa3, PK(l3, h3), od, 0, 0, 0);
;     ...
; }
; __device__ __forceinline__ void pv_d0(f32x16* o, int vb, bf16x8 pa0, bf16x8 pa1, bf16x8 pa2, bf16x8 pa3) {
;   pv_one<0>(o[0], vb, pa0, pa1, pa2, pa3); pv_one<1>(o[1], vb, pa0, pa1, pa2, pa3); pv_one<2>(o[2], vb, pa0, pa1, pa2, pa3); pv_one<3>(o[3], vb, pa0, pa1, pa2, pa3);
.LBB0_305:
	v_exp_f32_e32 v112, v128
	v_exp_f32_e32 v113, v129
	v_exp_f32_e32 v114, v130
	v_exp_f32_e32 v115, v131
	v_exp_f32_e32 v116, v132
	v_exp_f32_e32 v117, v133
	v_exp_f32_e32 v118, v134
	v_exp_f32_e32 v119, v135
	v_exp_f32_e32 v120, v136
	v_exp_f32_e32 v121, v137
	v_exp_f32_e32 v122, v138
	v_exp_f32_e32 v123, v139
	v_exp_f32_e32 v124, v140
	v_exp_f32_e32 v125, v141
	v_exp_f32_e32 v126, v142
	v_exp_f32_e32 v127, v143
	s_lshl_b32 s0, s64, 14
	v_add_u32_e32 v128, s0, v220
	ds_read_b64_tr_b16 v[96:97], v128 offset:0
	ds_read_b64_tr_b16 v[98:99], v128 offset:0x800
	ds_read_b64_tr_b16 v[100:101], v128 offset:0x1000
	ds_read_b64_tr_b16 v[102:103], v128 offset:0x1800
	ds_read_b64_tr_b16 v[104:105], v128 offset:0x2000
	ds_read_b64_tr_b16 v[106:107], v128 offset:0x2800
	ds_read_b64_tr_b16 v[108:109], v128 offset:0x3000
	ds_read_b64_tr_b16 v[110:111], v128 offset:0x3800
	s_waitcnt lgkmcnt(0)
	s_nop 0
	v_mfma_f32_32x32x16_bf16 v[2:17], v[180:183], v[96:99], v[2:17]
	ds_read_b64_tr_b16 v[96:97], v128 offset:0x200
	ds_read_b64_tr_b16 v[98:99], v128 offset:0xa00
	v_mfma_f32_32x32x16_bf16 v[2:17], v[184:187], v[100:103], v[2:17]
	ds_read_b64_tr_b16 v[100:101], v128 offset:0x1200
	ds_read_b64_tr_b16 v[102:103], v128 offset:0x1a00
	v_mfma_f32_32x32x16_bf16 v[2:17], v[188:191], v[104:107], v[2:17]
	ds_read_b64_tr_b16 v[104:105], v128 offset:0x2200
	ds_read_b64_tr_b16 v[106:107], v128 offset:0x2a00
	v_mfma_f32_32x32x16_bf16 v[2:17], v[192:195], v[108:111], v[2:17]
	ds_read_b64_tr_b16 v[108:109], v128 offset:0x3200
	ds_read_b64_tr_b16 v[110:111], v128 offset:0x3a00
	s_waitcnt lgkmcnt(0)
	v_mfma_f32_32x32x16_bf16 v[18:33], v[180:183], v[96:99], v[18:33]
	ds_read_b64_tr_b16 v[96:97], v128 offset:0x400
	ds_read_b64_tr_b16 v[98:99], v128 offset:0xc00
	v_mfma_f32_32x32x16_bf16 v[18:33], v[184:187], v[100:103], v[18:33]
	ds_read_b64_tr_b16 v[100:101], v128 offset:0x1400
	ds_read_b64_tr_b16 v[102:103], v128 offset:0x1c00
	v_mfma_f32_32x32x16_bf16 v[18:33], v[188:191], v[104:107], v[18:33]
	ds_read_b64_tr_b16 v[104:105], v128 offset:0x2400
	ds_read_b64_tr_b16 v[106:107], v128 offset:0x2c00
	v_mfma_f32_32x32x16_bf16 v[18:33], v[192:195], v[108:111], v[18:33]
	ds_read_b64_tr_b16 v[108:109], v128 offset:0x3400
	ds_read_b64_tr_b16 v[110:111], v128 offset:0x3c00
	s_waitcnt lgkmcnt(0)
	v_mfma_f32_32x32x16_bf16 v[34:49], v[180:183], v[96:99], v[34:49]
	ds_read_b64_tr_b16 v[96:97], v128 offset:0x600
	ds_read_b64_tr_b16 v[98:99], v128 offset:0xe00
	v_mfma_f32_32x32x16_bf16 v[34:49], v[184:187], v[100:103], v[34:49]
	ds_read_b64_tr_b16 v[100:101], v128 offset:0x1600
	ds_read_b64_tr_b16 v[102:103], v128 offset:0x1e00
	v_mfma_f32_32x32x16_bf16 v[34:49], v[188:191], v[104:107], v[34:49]
	ds_read_b64_tr_b16 v[104:105], v128 offset:0x2600
	ds_read_b64_tr_b16 v[106:107], v128 offset:0x2e00
	v_mfma_f32_32x32x16_bf16 v[34:49], v[192:195], v[108:111], v[34:49]
	ds_read_b64_tr_b16 v[108:109], v128 offset:0x3600
	ds_read_b64_tr_b16 v[110:111], v128 offset:0x3e00
	s_waitcnt lgkmcnt(0)
	v_mfma_f32_32x32x16_bf16 v[50:65], v[180:183], v[96:99], v[50:65]
	s_add_i32 s0, s0, 0
	v_add_u32_e32 v96, s0, v201
	s_barrier
; #define SBAR() __builtin_amdgcn_sched_barrier(0)
; __device__ __forceinline__ void finishSM(f32x16& p0, f32x16& p1, float alpha, float& l_reg, bf16x8& pa0, bf16x8& pa1, bf16x8& pa2, bf16x8& pa3) {
; #pragma unroll
;   for (int r = 0; r < 16; ++r) p1[r] = __builtin_amdgcn_exp2f(p1[r]);
;   float ps = 0;
; #pragma unroll
;   for (int r = 0; r < 16; ++r) ps += p0[r];
; #pragma unroll
;   for (int r = 0; r < 16; ++r) ps += p1[r];
;   { auto rr = __builtin_amdgcn_permlane32_swap(__float_as_uint(ps), __float_as_uint(ps), false, false);
;     ps = __uint_as_float(rr[0]) + __uint_as_float(rr[1]); }
;   l_reg = l_reg * alpha + ps;
;     ...
;   PK4(p0, 0, pa0); PK4(p0, 8, pa1); PK4(p1, 0, pa2); PK4(p1, 8, pa3);
;     ...
; }
; __device__ __forceinline__ void qkt(f32x16& p0, f32x16& p1, const char* Ks, const bf16x8* qr, int r32, int hi) {
;   bf16x8 ka[4], kb[4];
; #pragma unroll
;   for (int d0 = 0; d0 < 4; ++d0) { const int cb = (d0 * 16 + hi * 8) * 2;
;     ka[d0] = *reinterpret_cast<const bf16x8*>(Ks + KSWZ64(r32, cb)); kb[d0] = *reinterpret_cast<const bf16x8*>(Ks + KSWZ64(32 + r32, cb)); }
;   asm volatile("s_waitcnt lgkmcnt(0)" ::: "memory"); SBAR();
;   p0 = f32x16{}; p1 = f32x16{};
; #pragma unroll
;   for (int d0 = 0; d0 < 4; ++d0) {
;     p0 = __builtin_amdgcn_mfma_f32_32x32x16_bf16(ka[d0], qr[d0], p0, 0, 0, 0);
;     p1 = __builtin_amdgcn_mfma_f32_32x32x16_bf16(kb[d0], qr[d0], p1, 0, 0, 0); }
	s_waitcnt vmcnt(2)
	ds_write_b128 v96, v[168:171]
	v_mfma_f32_32x32x16_bf16 v[50:65], v[184:187], v[100:103], v[50:65]
	s_waitcnt vmcnt(1)
	ds_write_b128 v96, v[172:175] offset:8192
	v_lshl_add_u32 v96, s64, 13, v222
	s_waitcnt vmcnt(0)
	ds_write_b128 v96, v[176:179] offset:49152
	v_mfma_f32_32x32x16_bf16 v[50:65], v[188:191], v[104:107], v[50:65]
	v_mfma_f32_32x32x16_bf16 v[50:65], v[192:195], v[108:111], v[50:65]
	v_add_f32_e32 v96, v113, v112
	v_add_f32_e32 v96, v114, v96
	v_add_f32_e32 v96, v115, v96
	v_add_f32_e32 v96, v116, v96
	v_add_f32_e32 v96, v117, v96
	v_add_f32_e32 v96, v118, v96
	v_add_f32_e32 v96, v119, v96
	v_add_f32_e32 v96, v120, v96
	v_add_f32_e32 v96, v121, v96
	v_add_f32_e32 v96, v122, v96
	v_add_f32_e32 v96, v123, v96
	v_exp_f32_e32 v80, v80
	v_add_f32_e32 v96, v124, v96
	v_exp_f32_e32 v81, v81
	v_add_f32_e32 v96, v125, v96
	v_exp_f32_e32 v82, v82
	v_add_f32_e32 v96, v126, v96
	v_exp_f32_e32 v83, v83
	v_add_f32_e32 v96, v127, v96
	v_exp_f32_e32 v84, v84
	v_add_f32_e32 v96, v80, v96
	v_exp_f32_e32 v85, v85
	v_add_f32_e32 v96, v81, v96
	v_exp_f32_e32 v86, v86
	v_add_f32_e32 v96, v82, v96
	v_exp_f32_e32 v87, v87
	v_add_f32_e32 v96, v83, v96
	v_exp_f32_e32 v88, v88
	v_add_f32_e32 v96, v84, v96
	v_exp_f32_e32 v89, v89
	v_add_f32_e32 v96, v85, v96
	v_exp_f32_e32 v90, v90
	v_add_f32_e32 v96, v86, v96
	v_exp_f32_e32 v91, v91
	v_add_f32_e32 v96, v87, v96
	v_exp_f32_e32 v92, v92
	v_add_f32_e32 v96, v88, v96
	v_exp_f32_e32 v93, v93
	v_add_f32_e32 v96, v89, v96
	v_exp_f32_e32 v94, v94
	v_add_f32_e32 v96, v90, v96
	v_exp_f32_e32 v95, v95
	v_add_f32_e32 v96, v91, v96
	v_add_f32_e32 v96, v92, v96
	v_add_f32_e32 v96, v93, v96
	v_add_f32_e32 v96, v94, v96
	v_add_f32_e32 v243, v95, v96
	v_mov_b32_e32 v244, v243
	v_cvt_pk_bf16_f32 v180, v112, v113
	v_cvt_pk_bf16_f32 v181, v114, v115
	v_cvt_pk_bf16_f32 v182, v116, v117
	v_cvt_pk_bf16_f32 v183, v118, v119
	v_cvt_pk_bf16_f32 v188, v120, v121
	v_cvt_pk_bf16_f32 v189, v122, v123
	v_cvt_pk_bf16_f32 v190, v124, v125
	v_cvt_pk_bf16_f32 v191, v126, v127
	v_cvt_pk_bf16_f32 v192, v80, v81
	v_cvt_pk_bf16_f32 v193, v82, v83
	v_cvt_pk_bf16_f32 v194, v84, v85
	v_cvt_pk_bf16_f32 v195, v86, v87
	v_cvt_pk_bf16_f32 v184, v88, v89
	v_cvt_pk_bf16_f32 v185, v90, v91
	v_cvt_pk_bf16_f32 v186, v92, v93
	v_cvt_pk_bf16_f32 v187, v94, v95
	s_nop 1
	v_permlane32_swap_b32_e32 v243, v244
	v_permlane32_swap_b32_e32 v180, v182
	v_permlane32_swap_b32_e32 v181, v183
	v_permlane32_swap_b32_e32 v188, v190
	v_permlane32_swap_b32_e32 v189, v191
	v_permlane32_swap_b32_e32 v192, v194
	v_permlane32_swap_b32_e32 v193, v195
	v_permlane32_swap_b32_e32 v184, v186
	v_permlane32_swap_b32_e32 v185, v187
	s_lshl_b32 s0, s66, 13
	s_add_i32 s0, s0, 0
	v_add_u32_e32 v84, s0, v224
	v_add_u32_e32 v92, s0, v227
	v_add_u32_e32 v100, s0, v229
	v_add_u32_e32 v108, s0, v230
	ds_read_b128 v[80:83], v84 offset:49152
	ds_read_b128 v[84:87], v84 offset:53248
	ds_read_b128 v[88:91], v92 offset:49152
	ds_read_b128 v[92:95], v92 offset:53248
	ds_read_b128 v[96:99], v100 offset:49152
	ds_read_b128 v[100:103], v100 offset:53248
	ds_read_b128 v[104:107], v108 offset:49152
	ds_read_b128 v[108:111], v108 offset:53248
	s_waitcnt lgkmcnt(0)
	s_waitcnt lgkmcnt(7)
	v_mfma_f32_32x32x16_bf16 v[128:143], v[80:83], v[164:167], 0
	s_waitcnt lgkmcnt(6)
	v_mfma_f32_32x32x16_bf16 v[112:127], v[84:87], v[164:167], 0
	s_waitcnt lgkmcnt(5)
	v_mfma_f32_32x32x16_bf16 v[128:143], v[88:91], v[160:163], v[128:143]
	s_waitcnt lgkmcnt(4)
	v_mfma_f32_32x32x16_bf16 v[112:127], v[92:95], v[160:163], v[112:127]
	s_waitcnt lgkmcnt(3)
	v_mfma_f32_32x32x16_bf16 v[128:143], v[96:99], v[156:159], v[128:143]
	s_waitcnt lgkmcnt(2)
	v_mfma_f32_32x32x16_bf16 v[112:127], v[100:103], v[156:159], v[112:127]
	s_waitcnt lgkmcnt(1)
	v_mfma_f32_32x32x16_bf16 v[128:143], v[104:107], v[152:155], v[128:143]
	s_waitcnt lgkmcnt(0)
	v_mfma_f32_32x32x16_bf16 v[112:127], v[108:111], v[152:155], v[112:127]
	s_cmp_lt_u32 s67, 61
	s_cselect_b64 s[0:1], -1, 0
	s_cmp_gt_u32 s67, 60
	s_cbranch_scc1 .LBB0_307
	s_add_u32 s74, s70, 0x18e00000
	s_addc_u32 s75, s71, 0
	global_load_dwordx4 v[168:171], v202, s[74:75] offset:2048
	s_add_u32 s74, s70, 0x18e40000
	s_addc_u32 s75, s71, 0
	global_load_dwordx4 v[172:175], v202, s[74:75] offset:2048
	s_add_u32 s74, s72, 0x18e00000
	s_addc_u32 s75, s73, 0
	global_load_dwordx4 v[176:179], v204, s[74:75] offset:1024

; #define SBAR() __builtin_amdgcn_sched_barrier(0)
; template <int D0> __device__ __forceinline__ void pv_one(f32x16& od, int vb, bf16x8 pa0, bf16x8 pa1, bf16x8 pa2, bf16x8 pa3) {
;   const s16x4 l0 = tr_read<v_rd_off(D0, 0, 0)>(vb), h0 = tr_read<v_rd_off(D0, 0, 1)>(vb), l1 = tr_read<v_rd_off(D0, 1, 0)>(vb), h1 = tr_read<v_rd_off(D0, 1, 1)>(vb);
;   const s16x4 l2 = tr_read<v_rd_off(D0, 2, 0)>(vb), h2 = tr_read<v_rd_off(D0, 2, 1)>(vb), l3 = tr_read<v_rd_off(D0, 3, 0)>(vb), h3 = tr_read<v_rd_off(D0, 3, 1)>(vb);
;   asm volatile("s_waitcnt lgkmcnt(0)" ::: "memory"); SBAR();
;     ...
;   od = __builtin_amdgcn_mfma_f32_32x32x16_bf16(pa0, PK(l0, h0), od, 0, 0, 0);
;   od = __builtin_amdgcn_mfma_f32_32x32x16_bf16(pa1, PK(l1, h1), od, 0, 0, 0);
;   od = __builtin_amdgcn_mfma_f32_32x32x16_bf16(pa2, PK(l2, h2), od, 0, 0, 0);
;   od = __builtin_amdgcn_mfma_f32_32x32x16_bf16(pa3, PK(l3, h3), od, 0, 0, 0);
;     ...
; }
; __device__ __forceinline__ void pv_d0(f32x16* o, int vb, bf16x8 pa0, bf16x8 pa1, bf16x8 pa2, bf16x8 pa3) {
;   pv_one<0>(o[0], vb, pa0, pa1, pa2, pa3); pv_one<1>(o[1], vb, pa0, pa1, pa2, pa3); pv_one<2>(o[2], vb, pa0, pa1, pa2, pa3); pv_one<3>(o[3], vb, pa0, pa1, pa2, pa3);
.LBB0_311:
	s_lshl_b32 s8, s68, 14
	v_add_u32_e32 v128, s8, v220
	ds_read_b64_tr_b16 v[112:113], v128 offset:0
	ds_read_b64_tr_b16 v[114:115], v128 offset:0x800
	ds_read_b64_tr_b16 v[116:117], v128 offset:0x1000
	ds_read_b64_tr_b16 v[118:119], v128 offset:0x1800
	ds_read_b64_tr_b16 v[120:121], v128 offset:0x2000
	ds_read_b64_tr_b16 v[122:123], v128 offset:0x2800
	ds_read_b64_tr_b16 v[124:125], v128 offset:0x3000
	ds_read_b64_tr_b16 v[126:127], v128 offset:0x3800
	s_waitcnt lgkmcnt(0)
	s_nop 0
	v_mfma_f32_32x32x16_bf16 v[2:17], v[180:183], v[112:115], v[2:17]
	ds_read_b64_tr_b16 v[112:113], v128 offset:0x200
	ds_read_b64_tr_b16 v[114:115], v128 offset:0xa00
	v_mfma_f32_32x32x16_bf16 v[2:17], v[188:191], v[116:119], v[2:17]
	ds_read_b64_tr_b16 v[116:117], v128 offset:0x1200
	ds_read_b64_tr_b16 v[118:119], v128 offset:0x1a00
	v_mfma_f32_32x32x16_bf16 v[2:17], v[192:195], v[120:123], v[2:17]
	ds_read_b64_tr_b16 v[120:121], v128 offset:0x2200
	ds_read_b64_tr_b16 v[122:123], v128 offset:0x2a00
	v_mfma_f32_32x32x16_bf16 v[2:17], v[184:187], v[124:127], v[2:17]
	ds_read_b64_tr_b16 v[124:125], v128 offset:0x3200
	ds_read_b64_tr_b16 v[126:127], v128 offset:0x3a00
	s_waitcnt lgkmcnt(0)
	v_mfma_f32_32x32x16_bf16 v[18:33], v[180:183], v[112:115], v[18:33]
	ds_read_b64_tr_b16 v[112:113], v128 offset:0x400
	ds_read_b64_tr_b16 v[114:115], v128 offset:0xc00
	v_mfma_f32_32x32x16_bf16 v[18:33], v[188:191], v[116:119], v[18:33]
	ds_read_b64_tr_b16 v[116:117], v128 offset:0x1400
	ds_read_b64_tr_b16 v[118:119], v128 offset:0x1c00
	v_mfma_f32_32x32x16_bf16 v[18:33], v[192:195], v[120:123], v[18:33]
	ds_read_b64_tr_b16 v[120:121], v128 offset:0x2400
	ds_read_b64_tr_b16 v[122:123], v128 offset:0x2c00
	v_mfma_f32_32x32x16_bf16 v[18:33], v[184:187], v[124:127], v[18:33]
	ds_read_b64_tr_b16 v[124:125], v128 offset:0x3400
	ds_read_b64_tr_b16 v[126:127], v128 offset:0x3c00
	s_waitcnt lgkmcnt(0)
	v_mfma_f32_32x32x16_bf16 v[34:49], v[180:183], v[112:115], v[34:49]
	ds_read_b64_tr_b16 v[112:113], v128 offset:0x600
	ds_read_b64_tr_b16 v[114:115], v128 offset:0xe00
	v_mfma_f32_32x32x16_bf16 v[34:49], v[188:191], v[116:119], v[34:49]
	ds_read_b64_tr_b16 v[116:117], v128 offset:0x1600
	ds_read_b64_tr_b16 v[118:119], v128 offset:0x1e00
	v_mfma_f32_32x32x16_bf16 v[34:49], v[192:195], v[120:123], v[34:49]
	ds_read_b64_tr_b16 v[120:121], v128 offset:0x2600
	ds_read_b64_tr_b16 v[122:123], v128 offset:0x2e00
	v_mfma_f32_32x32x16_bf16 v[34:49], v[184:187], v[124:127], v[34:49]
	ds_read_b64_tr_b16 v[124:125], v128 offset:0x3600
	ds_read_b64_tr_b16 v[126:127], v128 offset:0x3e00
	s_waitcnt lgkmcnt(0)
	v_mfma_f32_32x32x16_bf16 v[50:65], v[180:183], v[112:115], v[50:65]
	s_mov_b64 s[54:55], -1
	s_andn2_b64 vcc, exec, s[0:1]
	s_barrier
	v_mfma_f32_32x32x16_bf16 v[50:65], v[188:191], v[116:119], v[50:65]
	v_mfma_f32_32x32x16_bf16 v[50:65], v[192:195], v[120:123], v[50:65]
	v_mfma_f32_32x32x16_bf16 v[50:65], v[184:187], v[124:127], v[50:65]
	s_cbranch_vccnz .LBB0_313
	s_add_i32 s0, s8, 0
	v_add_u32_e32 v114, s0, v201
	s_add_u32 s70, s70, s16
	s_addc_u32 s71, s71, s17
	s_add_u32 s72, s72, s16
	s_addc_u32 s73, s73, s17
	s_addk_i32 s65, 0x80
	v_add_u32_e32 v240, 0x200, v240
	s_add_i32 s67, s67, 2
	s_mov_b64 s[54:55], 0
	v_add_u32_e32 v112, s4, v218
	s_waitcnt vmcnt(2)
	ds_write_b128 v114, v[168:171]
	s_waitcnt vmcnt(1)
	ds_write_b128 v114, v[172:175] offset:8192
	s_waitcnt vmcnt(0)
	ds_write_b128 v112, v[176:179] offset:49152

; #define SBAR() __builtin_amdgcn_sched_barrier(0)
; __device__ __forceinline__ void finishSM(f32x16& p0, f32x16& p1, float alpha, float& l_reg, bf16x8& pa0, bf16x8& pa1, bf16x8& pa2, bf16x8& pa3) {
; #pragma unroll
;   for (int r = 0; r < 16; ++r) p1[r] = __builtin_amdgcn_exp2f(p1[r]);
;   float ps = 0;
; #pragma unroll
;   for (int r = 0; r < 16; ++r) ps += p0[r];
; #pragma unroll
;   for (int r = 0; r < 16; ++r) ps += p1[r];
;   { auto rr = __builtin_amdgcn_permlane32_swap(__float_as_uint(ps), __float_as_uint(ps), false, false);
;     ps = __uint_as_float(rr[0]) + __uint_as_float(rr[1]); }
;   l_reg = l_reg * alpha + ps;
;     ...
;   PK4(p0, 0, pa0); PK4(p0, 8, pa1); PK4(p1, 0, pa2); PK4(p1, 8, pa3);
;     ...
; }
; __device__ __forceinline__ void qkt(f32x16& p0, f32x16& p1, const char* Ks, const bf16x8* qr, int r32, int hi) {
;   bf16x8 ka[4], kb[4];
; #pragma unroll
;   for (int d0 = 0; d0 < 4; ++d0) { const int cb = (d0 * 16 + hi * 8) * 2;
;     ka[d0] = *reinterpret_cast<const bf16x8*>(Ks + KSWZ64(r32, cb)); kb[d0] = *reinterpret_cast<const bf16x8*>(Ks + KSWZ64(32 + r32, cb)); }
;   asm volatile("s_waitcnt lgkmcnt(0)" ::: "memory"); SBAR();
;   p0 = f32x16{}; p1 = f32x16{};
; #pragma unroll
;   for (int d0 = 0; d0 < 4; ++d0) {
;     p0 = __builtin_amdgcn_mfma_f32_32x32x16_bf16(ka[d0], qr[d0], p0, 0, 0, 0);
;     p1 = __builtin_amdgcn_mfma_f32_32x32x16_bf16(kb[d0], qr[d0], p1, 0, 0, 0); }
; template <bool GRPB> __device__ __forceinline__ void attn_pass(const float mbK, const float bmax2, const int pass, float* __restrict__ scr, bf16* __restrict__ mixrow, const float lam, const float* __restrict__ gsub, const float one_m_li, ...
;     ...
;   SBAR(); qkt(pB0, pB1, K_lds + b0 * SHM_K, qr, r32, hi);
;   finishSM(pA0, pA1, alA, l_reg, pa0, pa1, pa2, pa3); SBAR();
;   pv_d0(o, vb0 + bm1 * SHM_V, pa0, pa1, pa2, pa3); partialSM(pB0, pB1, m_reg, mnB, alB, (NT - 1) * KVBLK, qpos, qw, hi, tb2, cL, cR);
.LBB0_315:
	ds_read_b128 v[96:99], v223 offset:49152
	ds_read_b128 v[100:103], v223 offset:53248
	s_waitcnt vmcnt(2)
	ds_read_b128 v[168:171], v225 offset:49152
	s_waitcnt vmcnt(1)
	ds_read_b128 v[172:175], v225 offset:53248
	s_waitcnt vmcnt(0)
	ds_read_b128 v[176:179], v226 offset:49152
	ds_read_b128 v[180:183], v226 offset:53248
	ds_read_b128 v[184:187], v228 offset:49152
	ds_read_b128 v[188:191], v228 offset:53248
	s_waitcnt lgkmcnt(0)
	v_exp_f32_e32 v192, v80
	v_add_f32_e32 v80, v143, v141
	s_waitcnt lgkmcnt(7)
	v_mfma_f32_32x32x16_bf16 v[112:127], v[96:99], v[164:167], 0
	v_add_f32_e32 v80, v139, v80
	v_add_f32_e32 v80, v142, v80
	v_add_f32_e32 v80, v137, v80
	v_add_f32_e32 v80, v140, v80
	v_add_f32_e32 v80, v136, v80
	v_add_f32_e32 v80, v138, v80
	v_add_f32_e32 v80, v133, v80
	s_waitcnt lgkmcnt(6)
	v_mfma_f32_32x32x16_bf16 v[96:111], v[100:103], v[164:167], 0
	v_add_f32_e32 v80, v135, v80
	v_add_f32_e32 v80, v131, v80
	v_add_f32_e32 v80, v134, v80
	v_add_f32_e32 v80, v129, v80
	v_exp_f32_e32 v193, v81
	v_add_f32_e32 v80, v132, v80
	v_exp_f32_e32 v194, v82
	s_waitcnt lgkmcnt(5)
	v_mfma_f32_32x32x16_bf16 v[112:127], v[168:171], v[160:163], v[112:127]
	v_add_f32_e32 v80, v128, v80
	v_exp_f32_e32 v195, v83
	v_add_f32_e32 v80, v130, v80
	v_exp_f32_e32 v201, v84
	v_add_f32_e32 v80, v192, v80
	v_exp_f32_e32 v202, v85
	v_add_f32_e32 v80, v193, v80
	s_waitcnt lgkmcnt(4)
	v_mfma_f32_32x32x16_bf16 v[96:111], v[172:175], v[160:163], v[96:111]
	v_exp_f32_e32 v203, v86
	v_add_f32_e32 v80, v194, v80
	v_exp_f32_e32 v204, v87
	v_add_f32_e32 v80, v195, v80
	v_exp_f32_e32 v205, v88
	v_add_f32_e32 v80, v201, v80
	v_exp_f32_e32 v206, v89
	s_waitcnt lgkmcnt(3)
	v_mfma_f32_32x32x16_bf16 v[112:127], v[176:179], v[156:159], v[112:127]
	v_add_f32_e32 v80, v202, v80
	v_exp_f32_e32 v207, v90
	v_add_f32_e32 v80, v203, v80
	v_exp_f32_e32 v208, v91
	v_add_f32_e32 v80, v204, v80
	v_exp_f32_e32 v209, v92
	v_add_f32_e32 v80, v205, v80
	s_waitcnt lgkmcnt(2)
	v_mfma_f32_32x32x16_bf16 v[96:111], v[180:183], v[156:159], v[96:111]
	v_exp_f32_e32 v164, v93
	v_add_f32_e32 v80, v206, v80
	v_exp_f32_e32 v165, v94
	v_add_f32_e32 v80, v207, v80
	v_exp_f32_e32 v95, v95
	v_add_f32_e32 v80, v208, v80
	v_add_f32_e32 v80, v209, v80
	s_waitcnt lgkmcnt(1)
	v_mfma_f32_32x32x16_bf16 v[112:127], v[184:187], v[152:155], v[112:127]
	v_add_f32_e32 v80, v164, v80
	v_add_f32_e32 v80, v165, v80
	v_add_f32_e32 v156, v95, v80
	v_mov_b32_e32 v157, v156
	v_cvt_pk_bf16_f32 v80, v141, v143
	v_cvt_pk_bf16_f32 v81, v139, v142
	v_cvt_pk_bf16_f32 v82, v137, v140
	s_waitcnt lgkmcnt(0)
	v_mfma_f32_32x32x16_bf16 v[96:111], v[188:191], v[152:155], v[96:111]
	v_cvt_pk_bf16_f32 v83, v136, v138
	v_cvt_pk_bf16_f32 v84, v133, v135
	v_cvt_pk_bf16_f32 v85, v131, v134
	v_cvt_pk_bf16_f32 v86, v129, v132
	v_cvt_pk_bf16_f32 v87, v128, v130
	v_cvt_pk_bf16_f32 v88, v192, v193
	v_cvt_pk_bf16_f32 v89, v194, v195
	v_cvt_pk_bf16_f32 v90, v201, v202
	v_cvt_pk_bf16_f32 v91, v203, v204
	v_cvt_pk_bf16_f32 v92, v205, v206
	v_cvt_pk_bf16_f32 v93, v207, v208
	v_cvt_pk_bf16_f32 v94, v209, v164
	v_cvt_pk_bf16_f32 v95, v165, v95
	v_permlane32_swap_b32_e32 v156, v157
	v_permlane32_swap_b32_e32 v80, v82
	v_permlane32_swap_b32_e32 v81, v83
	v_permlane32_swap_b32_e32 v84, v86
	v_permlane32_swap_b32_e32 v85, v87
	v_permlane32_swap_b32_e32 v88, v90
	v_permlane32_swap_b32_e32 v89, v91
	v_permlane32_swap_b32_e32 v92, v94
	v_permlane32_swap_b32_e32 v93, v95
	s_cmp_lg_u32 0, -1
	s_cselect_b32 s0, 0, 0
	s_add_i32 s0, s0, 0x8000
	v_add_u32_e32 v152, s0, v231
	ds_read_b64_tr_b16 v[128:129], v152 offset:0
	ds_read_b64_tr_b16 v[130:131], v152 offset:0x800
	ds_read_b64_tr_b16 v[132:133], v152 offset:0x1000
	ds_read_b64_tr_b16 v[134:135], v152 offset:0x1800
	ds_read_b64_tr_b16 v[136:137], v152 offset:0x2000
	ds_read_b64_tr_b16 v[138:139], v152 offset:0x2800
	ds_read_b64_tr_b16 v[140:141], v152 offset:0x3000
	ds_read_b64_tr_b16 v[142:143], v152 offset:0x3800
	s_waitcnt lgkmcnt(0)
	s_nop 0
	v_mfma_f32_32x32x16_bf16 v[2:17], v[80:83], v[128:131], v[2:17]
	ds_read_b64_tr_b16 v[128:129], v152 offset:0x200
	ds_read_b64_tr_b16 v[130:131], v152 offset:0xa00
	v_mfma_f32_32x32x16_bf16 v[2:17], v[84:87], v[132:135], v[2:17]
	ds_read_b64_tr_b16 v[132:133], v152 offset:0x1200
	ds_read_b64_tr_b16 v[134:135], v152 offset:0x1a00
	v_mfma_f32_32x32x16_bf16 v[2:17], v[88:91], v[136:139], v[2:17]
	ds_read_b64_tr_b16 v[136:137], v152 offset:0x2200
	ds_read_b64_tr_b16 v[138:139], v152 offset:0x2a00
	v_mfma_f32_32x32x16_bf16 v[2:17], v[92:95], v[140:143], v[2:17]
	ds_read_b64_tr_b16 v[140:141], v152 offset:0x3200
	ds_read_b64_tr_b16 v[142:143], v152 offset:0x3a00
	s_waitcnt lgkmcnt(0)
	v_mfma_f32_32x32x16_bf16 v[18:33], v[80:83], v[128:131], v[18:33]
	ds_read_b64_tr_b16 v[128:129], v152 offset:0x400
	ds_read_b64_tr_b16 v[130:131], v152 offset:0xc00
	v_mfma_f32_32x32x16_bf16 v[18:33], v[84:87], v[132:135], v[18:33]
	ds_read_b64_tr_b16 v[132:133], v152 offset:0x1400
	ds_read_b64_tr_b16 v[134:135], v152 offset:0x1c00
	v_mfma_f32_32x32x16_bf16 v[18:33], v[88:91], v[136:139], v[18:33]
	ds_read_b64_tr_b16 v[136:137], v152 offset:0x2400
	ds_read_b64_tr_b16 v[138:139], v152 offset:0x2c00
	v_mfma_f32_32x32x16_bf16 v[18:33], v[92:95], v[140:143], v[18:33]
	ds_read_b64_tr_b16 v[140:141], v152 offset:0x3400
	ds_read_b64_tr_b16 v[142:143], v152 offset:0x3c00
	s_waitcnt lgkmcnt(0)
	v_mfma_f32_32x32x16_bf16 v[34:49], v[80:83], v[128:131], v[34:49]
	ds_read_b64_tr_b16 v[128:129], v152 offset:0x600
	ds_read_b64_tr_b16 v[130:131], v152 offset:0xe00
	v_mfma_f32_32x32x16_bf16 v[34:49], v[84:87], v[132:135], v[34:49]
	ds_read_b64_tr_b16 v[132:133], v152 offset:0x1600
	ds_read_b64_tr_b16 v[134:135], v152 offset:0x1e00
	v_mfma_f32_32x32x16_bf16 v[34:49], v[88:91], v[136:139], v[34:49]
	ds_read_b64_tr_b16 v[136:137], v152 offset:0x2600
	ds_read_b64_tr_b16 v[138:139], v152 offset:0x2e00
	v_mfma_f32_32x32x16_bf16 v[34:49], v[92:95], v[140:143], v[34:49]
	ds_read_b64_tr_b16 v[140:141], v152 offset:0x3600
	ds_read_b64_tr_b16 v[142:143], v152 offset:0x3e00
	s_waitcnt lgkmcnt(0)
	v_mfma_f32_32x32x16_bf16 v[50:65], v[80:83], v[128:131], v[50:65]
	s_add_i32 s4, s63, 0xffffefa6
	s_mov_b64 s[0:1], -1
	s_cmp_gt_u32 s4, 0xfffffeec
	v_mfma_f32_32x32x16_bf16 v[50:65], v[84:87], v[132:135], v[50:65]
	v_mfma_f32_32x32x16_bf16 v[50:65], v[88:91], v[136:139], v[50:65]
	v_mfma_f32_32x32x16_bf16 v[50:65], v[92:95], v[140:143], v[50:65]
	s_cbranch_scc0 .Lfastp_7
; __device__ __forceinline__ void partialSM(f32x16& p0, f32x16& p1, float& m_reg, float& mn, float& alpha, int kt0, int qpos, int qw, int hi, const float* tb2, float cL, float cR) {
;     ...
;     const float* tp = tb2 + (kt0 - qpos + 192 + 4 * hi);
; #pragma unroll
;     for (int r4 = 0; r4 < 4; ++r4) {
;       float ta[4], tb[4];
; #pragma unroll
;       for (int i = 0; i < 4; ++i) { ta[i] = tp[8 * r4 + i] - m_reg; tb[i] = tp[32 + 8 * r4 + i] - m_reg; }
; #pragma unroll
;       for (int i = 0; i < 4; ++i) { p0[4 * r4 + i] = fmaf(p0[4 * r4 + i], C1, ta[i]); p1[4 * r4 + i] = fmaf(p1[4 * r4 + i], C1, tb[i]); }
	v_sub_u32_e32 v80, 0xfc0, v215
	s_add_i32 s0, 0, 0x12b00
	v_lshlrev_b32_e32 v80, 2, v80
	v_add3_u32 v140, s0, v200, v80
	ds_read2_b32 v[80:81], v140 offset1:1
	ds_read2_b32 v[128:129], v140 offset0:32 offset1:33
	ds_read2_b32 v[130:131], v140 offset0:34 offset1:35
	ds_read2_b32 v[82:83], v140 offset0:2 offset1:3
	ds_read2_b32 v[84:85], v140 offset0:8 offset1:9
	ds_read2_b32 v[132:133], v140 offset0:40 offset1:41
	ds_read2_b32 v[134:135], v140 offset0:42 offset1:43
	ds_read2_b32 v[86:87], v140 offset0:10 offset1:11
	ds_read2_b32 v[88:89], v140 offset0:16 offset1:17
	ds_read2_b32 v[136:137], v140 offset0:48 offset1:49
	ds_read2_b32 v[138:139], v140 offset0:50 offset1:51
	ds_read2_b32 v[90:91], v140 offset0:18 offset1:19
	ds_read2_b32 v[92:93], v140 offset0:24 offset1:25
	ds_read2_b32 v[94:95], v140 offset0:56 offset1:57
	s_waitcnt lgkmcnt(5)
	v_sub_f32_e32 v89, v89, v75
	s_waitcnt lgkmcnt(4)
	v_sub_f32_e32 v137, v137, v75
	v_sub_f32_e32 v88, v88, v72
	s_waitcnt lgkmcnt(1)
	v_sub_f32_e32 v93, v93, v79
	s_waitcnt lgkmcnt(0)
	v_sub_f32_e32 v79, v95, v79
	v_sub_f32_e32 v92, v92, v78
	v_sub_f32_e32 v78, v94, v78
	ds_read2_b32 v[94:95], v140 offset0:26 offset1:27
	ds_read2_b32 v[140:141], v140 offset0:58 offset1:59
	v_sub_f32_e32 v91, v91, v73
	v_sub_f32_e32 v90, v90, v74
	s_waitcnt lgkmcnt(1)
	v_sub_f32_e32 v95, v95, v77
	s_waitcnt lgkmcnt(0)
	v_sub_f32_e32 v77, v141, v77
	v_sub_f32_e32 v94, v94, v76
	v_sub_f32_e32 v76, v140, v76
	v_sub_f32_e32 v85, v85, v69
	v_sub_f32_e32 v84, v84, v68
	v_sub_f32_e32 v87, v87, v71
	v_sub_f32_e32 v86, v86, v70
	v_sub_f32_e32 v81, v81, v1
	v_sub_f32_e32 v80, v80, v0
	v_sub_f32_e32 v83, v83, v67
	v_sub_f32_e32 v82, v82, v66
	v_sub_f32_e32 v136, v136, v72
	v_sub_f32_e32 v73, v139, v73
	v_sub_f32_e32 v72, v138, v74
	v_sub_f32_e32 v69, v133, v69
	v_sub_f32_e32 v68, v132, v68
	v_sub_f32_e32 v71, v135, v71
	v_sub_f32_e32 v70, v134, v70
	v_sub_f32_e32 v75, v129, v1
	v_sub_f32_e32 v74, v128, v0
	v_sub_f32_e32 v67, v131, v67
	v_sub_f32_e32 v66, v130, v66
	v_pk_fma_f32 v[82:83], v[114:115], s[6:7], v[82:83] op_sel_hi:[1,0,1]
	v_pk_fma_f32 v[80:81], v[112:113], s[6:7], v[80:81] op_sel_hi:[1,0,1]
	v_pk_fma_f32 v[86:87], v[118:119], s[6:7], v[86:87] op_sel_hi:[1,0,1]
	v_pk_fma_f32 v[84:85], v[116:117], s[6:7], v[84:85] op_sel_hi:[1,0,1]
	v_pk_fma_f32 v[90:91], v[122:123], s[6:7], v[90:91] op_sel_hi:[1,0,1]
	v_pk_fma_f32 v[88:89], v[120:121], s[6:7], v[88:89] op_sel_hi:[1,0,1]
	v_pk_fma_f32 v[94:95], v[126:127], s[6:7], v[94:95] op_sel_hi:[1,0,1]
	v_pk_fma_f32 v[92:93], v[124:125], s[6:7], v[92:93] op_sel_hi:[1,0,1]
	v_pk_fma_f32 v[130:131], v[98:99], s[6:7], v[66:67] op_sel_hi:[1,0,1]
	v_pk_fma_f32 v[128:129], v[96:97], s[6:7], v[74:75] op_sel_hi:[1,0,1]
	v_pk_fma_f32 v[134:135], v[102:103], s[6:7], v[70:71] op_sel_hi:[1,0,1]
	v_pk_fma_f32 v[132:133], v[100:101], s[6:7], v[68:69] op_sel_hi:[1,0,1]
	v_pk_fma_f32 v[138:139], v[106:107], s[6:7], v[72:73] op_sel_hi:[1,0,1]
	v_pk_fma_f32 v[136:137], v[104:105], s[6:7], v[136:137] op_sel_hi:[1,0,1]
	v_pk_fma_f32 v[142:143], v[110:111], s[6:7], v[76:77] op_sel_hi:[1,0,1]
	v_pk_fma_f32 v[140:141], v[108:109], s[6:7], v[78:79] op_sel_hi:[1,0,1]
	s_mov_b64 s[0:1], 0

; #define SBAR() __builtin_amdgcn_sched_barrier(0)
; __device__ __forceinline__ void finishSM(f32x16& p0, f32x16& p1, float alpha, float& l_reg, bf16x8& pa0, bf16x8& pa1, bf16x8& pa2, bf16x8& pa3) {
; #pragma unroll
;   for (int r = 0; r < 16; ++r) p1[r] = __builtin_amdgcn_exp2f(p1[r]);
;   float ps = 0;
; #pragma unroll
;   for (int r = 0; r < 16; ++r) ps += p0[r];
; #pragma unroll
;   for (int r = 0; r < 16; ++r) ps += p1[r];
;   { auto rr = __builtin_amdgcn_permlane32_swap(__float_as_uint(ps), __float_as_uint(ps), false, false);
;     ps = __uint_as_float(rr[0]) + __uint_as_float(rr[1]); }
;   l_reg = l_reg * alpha + ps;
;     ...
;   PK4(p0, 0, pa0); PK4(p0, 8, pa1); PK4(p1, 0, pa2); PK4(p1, 8, pa3);
;     ...
; }
; __device__ __forceinline__ void qkt(f32x16& p0, f32x16& p1, const char* Ks, const bf16x8* qr, int r32, int hi) {
;   bf16x8 ka[4], kb[4];
; #pragma unroll
;   for (int d0 = 0; d0 < 4; ++d0) { const int cb = (d0 * 16 + hi * 8) * 2;
;     ka[d0] = *reinterpret_cast<const bf16x8*>(Ks + KSWZ64(r32, cb)); kb[d0] = *reinterpret_cast<const bf16x8*>(Ks + KSWZ64(32 + r32, cb)); }
;   asm volatile("s_waitcnt lgkmcnt(0)" ::: "memory"); SBAR();
;   p0 = f32x16{}; p1 = f32x16{};
; #pragma unroll
;   for (int d0 = 0; d0 < 4; ++d0) {
;     p0 = __builtin_amdgcn_mfma_f32_32x32x16_bf16(ka[d0], qr[d0], p0, 0, 0, 0);
;     p1 = __builtin_amdgcn_mfma_f32_32x32x16_bf16(kb[d0], qr[d0], p1, 0, 0, 0); }
.LBB0_326:
	s_mov_b32 s68, s65
	s_mov_b32 s65, s0
	v_add_f32_e32 v96, v143, v141
	v_add_f32_e32 v96, v139, v96
	v_add_f32_e32 v96, v142, v96
	v_add_f32_e32 v96, v137, v96
	v_add_f32_e32 v96, v140, v96
	v_add_f32_e32 v96, v136, v96
	v_add_f32_e32 v96, v138, v96
	v_add_f32_e32 v96, v133, v96
	v_add_f32_e32 v96, v135, v96
	v_add_f32_e32 v96, v131, v96
	v_add_f32_e32 v96, v134, v96
	v_exp_f32_e32 v80, v80
	v_add_f32_e32 v96, v129, v96
	v_exp_f32_e32 v81, v81
	v_add_f32_e32 v96, v132, v96
	v_exp_f32_e32 v82, v82
	v_add_f32_e32 v96, v128, v96
	v_exp_f32_e32 v83, v83
	v_add_f32_e32 v96, v130, v96
	v_exp_f32_e32 v84, v84
	v_add_f32_e32 v96, v80, v96
	v_exp_f32_e32 v85, v85
	v_add_f32_e32 v96, v81, v96
	v_exp_f32_e32 v86, v86
	v_add_f32_e32 v96, v82, v96
	v_exp_f32_e32 v87, v87
	v_add_f32_e32 v96, v83, v96
	v_exp_f32_e32 v88, v88
	v_add_f32_e32 v96, v84, v96
	v_exp_f32_e32 v89, v89
	v_add_f32_e32 v96, v85, v96
	v_exp_f32_e32 v90, v90
	v_add_f32_e32 v96, v86, v96
	v_exp_f32_e32 v91, v91
	v_add_f32_e32 v96, v87, v96
	v_exp_f32_e32 v92, v92
	v_add_f32_e32 v96, v88, v96
	v_exp_f32_e32 v93, v93
	v_add_f32_e32 v96, v89, v96
	v_exp_f32_e32 v94, v94
	v_add_f32_e32 v96, v90, v96
	v_exp_f32_e32 v95, v95
	v_add_f32_e32 v96, v91, v96
	v_add_f32_e32 v96, v92, v96
	v_add_f32_e32 v96, v93, v96
	v_add_f32_e32 v96, v94, v96
	v_add_f32_e32 v243, v95, v96
	v_mov_b32_e32 v244, v243
	v_cvt_pk_bf16_f32 v180, v141, v143
	v_cvt_pk_bf16_f32 v181, v139, v142
	v_cvt_pk_bf16_f32 v182, v137, v140
	v_cvt_pk_bf16_f32 v183, v136, v138
	v_cvt_pk_bf16_f32 v184, v133, v135
	v_cvt_pk_bf16_f32 v185, v131, v134
	v_cvt_pk_bf16_f32 v186, v129, v132
	v_cvt_pk_bf16_f32 v187, v128, v130
	v_cvt_pk_bf16_f32 v188, v80, v81
	v_cvt_pk_bf16_f32 v189, v82, v83
	v_cvt_pk_bf16_f32 v190, v84, v85
	v_cvt_pk_bf16_f32 v191, v86, v87
	v_cvt_pk_bf16_f32 v192, v88, v89
	v_cvt_pk_bf16_f32 v193, v90, v91
	v_cvt_pk_bf16_f32 v194, v92, v93
	v_cvt_pk_bf16_f32 v195, v94, v95
	s_nop 1
	v_permlane32_swap_b32_e32 v243, v244
	v_permlane32_swap_b32_e32 v180, v182
	v_permlane32_swap_b32_e32 v181, v183
	v_permlane32_swap_b32_e32 v184, v186
	v_permlane32_swap_b32_e32 v185, v187
	v_permlane32_swap_b32_e32 v188, v190
	v_permlane32_swap_b32_e32 v189, v191
	v_permlane32_swap_b32_e32 v192, v194
	v_permlane32_swap_b32_e32 v193, v195
	s_lshl_b32 s0, s68, 13
	s_add_i32 s4, s0, 0
	v_add_u32_e32 v84, s4, v226
	v_add_u32_e32 v92, s4, v229
	v_add_u32_e32 v96, s4, v231
	ds_read_b128 v[80:83], v84 offset:49152
	ds_read_b128 v[84:87], v84 offset:53248
	ds_read_b128 v[88:91], v92 offset:49152
	ds_read_b128 v[92:95], v92 offset:53248
	ds_read_b128 v[128:131], v96 offset:49152
	ds_read_b128 v[132:135], v96 offset:53248
	v_add_u32_e32 v96, s4, v240
	ds_read_b128 v[136:139], v96 offset:49152
	ds_read_b128 v[140:143], v96 offset:53248
	s_waitcnt lgkmcnt(0)
	s_waitcnt lgkmcnt(7)
	v_mfma_f32_32x32x16_bf16 v[112:127], v[80:83], v[164:167], 0
	s_waitcnt lgkmcnt(6)
	v_mfma_f32_32x32x16_bf16 v[96:111], v[84:87], v[164:167], 0
	s_waitcnt lgkmcnt(5)
	v_mfma_f32_32x32x16_bf16 v[112:127], v[88:91], v[160:163], v[112:127]
	s_waitcnt lgkmcnt(4)
	v_mfma_f32_32x32x16_bf16 v[96:111], v[92:95], v[160:163], v[96:111]
	s_waitcnt lgkmcnt(3)
	v_mfma_f32_32x32x16_bf16 v[112:127], v[128:131], v[152:155], v[112:127]
	s_waitcnt lgkmcnt(2)
	v_mfma_f32_32x32x16_bf16 v[96:111], v[132:135], v[152:155], v[96:111]
	s_waitcnt lgkmcnt(1)
	v_mfma_f32_32x32x16_bf16 v[112:127], v[136:139], v[156:159], v[112:127]
	s_waitcnt lgkmcnt(0)
	v_mfma_f32_32x32x16_bf16 v[96:111], v[140:143], v[156:159], v[96:111]
	s_add_u32 s74, s70, s15
	s_addc_u32 s75, s71, 0
	global_load_dwordx4 v[168:171], v202, s[74:75] offset:2048
	s_add_u32 s74, s70, 0x18dc0000
	s_addc_u32 s75, s71, 0
	global_load_dwordx4 v[172:175], v202, s[74:75] offset:2048
	s_add_u32 s74, s72, 0x18d80000
	s_addc_u32 s75, s73, 0
	global_load_dwordx4 v[176:179], v204, s[74:75] offset:1152
	s_add_i32 s0, s66, 0xffffff47
	s_cmp_gt_u32 s0, 0xfffffeec
	s_mov_b64 s[0:1], -1
	s_cbranch_scc0 .Lfastp_6
; __device__ __forceinline__ void partialSM(f32x16& p0, f32x16& p1, float& m_reg, float& mn, float& alpha, int kt0, int qpos, int qw, int hi, const float* tb2, float cL, float cR) {
;     ...
;     const float* tp = tb2 + (kt0 - qpos + 192 + 4 * hi);
; #pragma unroll
;     for (int r4 = 0; r4 < 4; ++r4) {
;       float ta[4], tb[4];
; #pragma unroll
;       for (int i = 0; i < 4; ++i) { ta[i] = tp[8 * r4 + i] - m_reg; tb[i] = tp[32 + 8 * r4 + i] - m_reg; }
; #pragma unroll
;       for (int i = 0; i < 4; ++i) { p0[4 * r4 + i] = fmaf(p0[4 * r4 + i], C1, ta[i]); p1[4 * r4 + i] = fmaf(p1[4 * r4 + i], C1, tb[i]); }
	ds_read2_b32 v[80:81], v242 offset1:1
	ds_read2_b32 v[82:83], v242 offset0:32 offset1:33
	ds_read2_b32 v[84:85], v242 offset0:34 offset1:35
	ds_read2_b32 v[86:87], v242 offset0:2 offset1:3
	ds_read2_b32 v[88:89], v242 offset0:8 offset1:9
	ds_read2_b32 v[90:91], v242 offset0:40 offset1:41
	ds_read2_b32 v[92:93], v242 offset0:42 offset1:43
	ds_read2_b32 v[94:95], v242 offset0:10 offset1:11
	ds_read2_b32 v[128:129], v242 offset0:16 offset1:17
	ds_read2_b32 v[246:247], v242 offset0:48 offset1:49
	ds_read2_b32 v[248:249], v242 offset0:50 offset1:51
	ds_read2_b32 v[130:131], v242 offset0:18 offset1:19
	s_waitcnt lgkmcnt(11)
	v_sub_f32_e32 v81, v81, v65
	v_sub_f32_e32 v80, v80, v64
	ds_read2_b32 v[132:133], v242 offset0:24 offset1:25
	ds_read2_b32 v[134:135], v242 offset0:26 offset1:27
	ds_read2_b32 v[250:251], v242 offset0:56 offset1:57
	s_waitcnt lgkmcnt(6)
	v_sub_f32_e32 v137, v129, v75
	v_sub_f32_e32 v136, v128, v72
	v_pk_fma_f32 v[128:129], v[112:113], s[6:7], v[80:81] op_sel_hi:[1,0,1]
	ds_read2_b32 v[80:81], v242 offset0:58 offset1:59
	v_sub_f32_e32 v89, v89, v69
	v_sub_f32_e32 v88, v88, v68
	v_sub_f32_e32 v95, v95, v71
	v_sub_f32_e32 v94, v94, v70
	v_sub_f32_e32 v87, v87, v67
	v_sub_f32_e32 v86, v86, v66
	s_waitcnt lgkmcnt(3)
	v_sub_f32_e32 v141, v133, v79
	v_sub_f32_e32 v140, v132, v78
	s_waitcnt lgkmcnt(2)
	v_sub_f32_e32 v143, v135, v77
	v_sub_f32_e32 v142, v134, v76
	v_sub_f32_e32 v139, v131, v73
	v_sub_f32_e32 v138, v130, v74
	v_pk_fma_f32 v[130:131], v[114:115], s[6:7], v[86:87] op_sel_hi:[1,0,1]
	v_pk_fma_f32 v[134:135], v[118:119], s[6:7], v[94:95] op_sel_hi:[1,0,1]
	v_pk_fma_f32 v[132:133], v[116:117], s[6:7], v[88:89] op_sel_hi:[1,0,1]
	s_waitcnt lgkmcnt(1)
	v_sub_f32_e32 v251, v251, v79
	v_sub_f32_e32 v250, v250, v78
	s_waitcnt lgkmcnt(0)
	v_sub_f32_e32 v95, v81, v77
	v_sub_f32_e32 v94, v80, v76
	v_sub_f32_e32 v89, v247, v75
	v_sub_f32_e32 v88, v246, v72
	v_sub_f32_e32 v247, v249, v73
	v_sub_f32_e32 v246, v248, v74
	v_sub_f32_e32 v91, v91, v69
	v_sub_f32_e32 v90, v90, v68
	v_sub_f32_e32 v87, v93, v71
	v_sub_f32_e32 v86, v92, v70
	v_sub_f32_e32 v81, v83, v65
	v_sub_f32_e32 v80, v82, v64
	v_sub_f32_e32 v83, v85, v67
	v_sub_f32_e32 v82, v84, v66
	v_pk_fma_f32 v[138:139], v[122:123], s[6:7], v[138:139] op_sel_hi:[1,0,1]
	v_pk_fma_f32 v[136:137], v[120:121], s[6:7], v[136:137] op_sel_hi:[1,0,1]
	v_pk_fma_f32 v[142:143], v[126:127], s[6:7], v[142:143] op_sel_hi:[1,0,1]
	v_pk_fma_f32 v[140:141], v[124:125], s[6:7], v[140:141] op_sel_hi:[1,0,1]
	v_pk_fma_f32 v[82:83], v[98:99], s[6:7], v[82:83] op_sel_hi:[1,0,1]
	v_pk_fma_f32 v[80:81], v[96:97], s[6:7], v[80:81] op_sel_hi:[1,0,1]
	v_pk_fma_f32 v[86:87], v[102:103], s[6:7], v[86:87] op_sel_hi:[1,0,1]
	v_pk_fma_f32 v[84:85], v[100:101], s[6:7], v[90:91] op_sel_hi:[1,0,1]
	v_pk_fma_f32 v[90:91], v[106:107], s[6:7], v[246:247] op_sel_hi:[1,0,1]
	v_pk_fma_f32 v[88:89], v[104:105], s[6:7], v[88:89] op_sel_hi:[1,0,1]
	v_pk_fma_f32 v[94:95], v[110:111], s[6:7], v[94:95] op_sel_hi:[1,0,1]
	v_pk_fma_f32 v[92:93], v[108:109], s[6:7], v[250:251] op_sel_hi:[1,0,1]
	s_mov_b64 s[0:1], 0

; #define SBAR() __builtin_amdgcn_sched_barrier(0)
; __device__ __forceinline__ void partialSM(f32x16& p0, f32x16& p1, float& m_reg, float& mn, float& alpha, int kt0, int qpos, int qw, int hi, const float* tb2, float cL, float cR) {
;     ...
; #pragma unroll
;   for (int r = 0; r < 16; ++r) p0[r] = __builtin_amdgcn_exp2f(p0[r]);
; template <int D0> __device__ __forceinline__ void pv_one(f32x16& od, int vb, bf16x8 pa0, bf16x8 pa1, bf16x8 pa2, bf16x8 pa3) {
;   const s16x4 l0 = tr_read<v_rd_off(D0, 0, 0)>(vb), h0 = tr_read<v_rd_off(D0, 0, 1)>(vb), l1 = tr_read<v_rd_off(D0, 1, 0)>(vb), h1 = tr_read<v_rd_off(D0, 1, 1)>(vb);
;   const s16x4 l2 = tr_read<v_rd_off(D0, 2, 0)>(vb), h2 = tr_read<v_rd_off(D0, 2, 1)>(vb), l3 = tr_read<v_rd_off(D0, 3, 0)>(vb), h3 = tr_read<v_rd_off(D0, 3, 1)>(vb);
;   asm volatile("s_waitcnt lgkmcnt(0)" ::: "memory"); SBAR();
;     ...
;   od = __builtin_amdgcn_mfma_f32_32x32x16_bf16(pa0, PK(l0, h0), od, 0, 0, 0);
;   od = __builtin_amdgcn_mfma_f32_32x32x16_bf16(pa1, PK(l1, h1), od, 0, 0, 0);
;   od = __builtin_amdgcn_mfma_f32_32x32x16_bf16(pa2, PK(l2, h2), od, 0, 0, 0);
;   od = __builtin_amdgcn_mfma_f32_32x32x16_bf16(pa3, PK(l3, h3), od, 0, 0, 0);
;     ...
; }
; __device__ __forceinline__ void pv_d0(f32x16* o, int vb, bf16x8 pa0, bf16x8 pa1, bf16x8 pa2, bf16x8 pa3) {
;   pv_one<0>(o[0], vb, pa0, pa1, pa2, pa3); pv_one<1>(o[1], vb, pa0, pa1, pa2, pa3); pv_one<2>(o[2], vb, pa0, pa1, pa2, pa3); pv_one<3>(o[3], vb, pa0, pa1, pa2, pa3);
.LBB0_330:
	v_exp_f32_e32 v112, v128
	v_exp_f32_e32 v113, v129
	v_exp_f32_e32 v114, v130
	v_exp_f32_e32 v115, v131
	v_exp_f32_e32 v116, v132
	v_exp_f32_e32 v117, v133
	v_exp_f32_e32 v118, v134
	v_exp_f32_e32 v119, v135
	v_exp_f32_e32 v120, v136
	v_exp_f32_e32 v121, v137
	v_exp_f32_e32 v122, v138
	v_exp_f32_e32 v123, v139
	v_exp_f32_e32 v124, v140
	v_exp_f32_e32 v125, v141
	v_exp_f32_e32 v126, v142
	v_exp_f32_e32 v127, v143
	s_lshl_b32 s0, s65, 14
	v_add_u32_e32 v128, s0, v219
	ds_read_b64_tr_b16 v[96:97], v128 offset:0
	ds_read_b64_tr_b16 v[98:99], v128 offset:0x800
	ds_read_b64_tr_b16 v[100:101], v128 offset:0x1000
	ds_read_b64_tr_b16 v[102:103], v128 offset:0x1800
	ds_read_b64_tr_b16 v[104:105], v128 offset:0x2000
	ds_read_b64_tr_b16 v[106:107], v128 offset:0x2800
	ds_read_b64_tr_b16 v[108:109], v128 offset:0x3000
	ds_read_b64_tr_b16 v[110:111], v128 offset:0x3800
	s_waitcnt lgkmcnt(0)
	s_nop 0
	v_mfma_f32_32x32x16_bf16 v[0:15], v[180:183], v[96:99], v[0:15]
	ds_read_b64_tr_b16 v[96:97], v128 offset:0x200
	ds_read_b64_tr_b16 v[98:99], v128 offset:0xa00
	v_mfma_f32_32x32x16_bf16 v[0:15], v[184:187], v[100:103], v[0:15]
	ds_read_b64_tr_b16 v[100:101], v128 offset:0x1200
	ds_read_b64_tr_b16 v[102:103], v128 offset:0x1a00
	v_mfma_f32_32x32x16_bf16 v[0:15], v[188:191], v[104:107], v[0:15]
	ds_read_b64_tr_b16 v[104:105], v128 offset:0x2200
	ds_read_b64_tr_b16 v[106:107], v128 offset:0x2a00
	v_mfma_f32_32x32x16_bf16 v[0:15], v[192:195], v[108:111], v[0:15]
	ds_read_b64_tr_b16 v[108:109], v128 offset:0x3200
	ds_read_b64_tr_b16 v[110:111], v128 offset:0x3a00
	s_waitcnt lgkmcnt(0)
	v_mfma_f32_32x32x16_bf16 v[16:31], v[180:183], v[96:99], v[16:31]
	ds_read_b64_tr_b16 v[96:97], v128 offset:0x400
	ds_read_b64_tr_b16 v[98:99], v128 offset:0xc00
	v_mfma_f32_32x32x16_bf16 v[16:31], v[184:187], v[100:103], v[16:31]
	ds_read_b64_tr_b16 v[100:101], v128 offset:0x1400
	ds_read_b64_tr_b16 v[102:103], v128 offset:0x1c00
	v_mfma_f32_32x32x16_bf16 v[16:31], v[188:191], v[104:107], v[16:31]
	ds_read_b64_tr_b16 v[104:105], v128 offset:0x2400
	ds_read_b64_tr_b16 v[106:107], v128 offset:0x2c00
	v_mfma_f32_32x32x16_bf16 v[16:31], v[192:195], v[108:111], v[16:31]
	ds_read_b64_tr_b16 v[108:109], v128 offset:0x3400
	ds_read_b64_tr_b16 v[110:111], v128 offset:0x3c00
	s_waitcnt lgkmcnt(0)
	v_mfma_f32_32x32x16_bf16 v[32:47], v[180:183], v[96:99], v[32:47]
	ds_read_b64_tr_b16 v[96:97], v128 offset:0x600
	ds_read_b64_tr_b16 v[98:99], v128 offset:0xe00
	v_mfma_f32_32x32x16_bf16 v[32:47], v[184:187], v[100:103], v[32:47]
	ds_read_b64_tr_b16 v[100:101], v128 offset:0x1600
	ds_read_b64_tr_b16 v[102:103], v128 offset:0x1e00
	v_mfma_f32_32x32x16_bf16 v[32:47], v[188:191], v[104:107], v[32:47]
	ds_read_b64_tr_b16 v[104:105], v128 offset:0x2600
	ds_read_b64_tr_b16 v[106:107], v128 offset:0x2e00
	v_mfma_f32_32x32x16_bf16 v[32:47], v[192:195], v[108:111], v[32:47]
	ds_read_b64_tr_b16 v[108:109], v128 offset:0x3600
	ds_read_b64_tr_b16 v[110:111], v128 offset:0x3e00
	s_waitcnt lgkmcnt(0)
	v_mfma_f32_32x32x16_bf16 v[48:63], v[180:183], v[96:99], v[48:63]
	s_add_i32 s0, s0, 0
	v_add_u32_e32 v96, s0, v221
	s_barrier
; #define SBAR() __builtin_amdgcn_sched_barrier(0)
; __device__ __forceinline__ void finishSM(f32x16& p0, f32x16& p1, float alpha, float& l_reg, bf16x8& pa0, bf16x8& pa1, bf16x8& pa2, bf16x8& pa3) {
; #pragma unroll
;   for (int r = 0; r < 16; ++r) p1[r] = __builtin_amdgcn_exp2f(p1[r]);
;   float ps = 0;
; #pragma unroll
;   for (int r = 0; r < 16; ++r) ps += p0[r];
; #pragma unroll
;   for (int r = 0; r < 16; ++r) ps += p1[r];
;   { auto rr = __builtin_amdgcn_permlane32_swap(__float_as_uint(ps), __float_as_uint(ps), false, false);
;     ps = __uint_as_float(rr[0]) + __uint_as_float(rr[1]); }
;   l_reg = l_reg * alpha + ps;
;     ...
;   PK4(p0, 0, pa0); PK4(p0, 8, pa1); PK4(p1, 0, pa2); PK4(p1, 8, pa3);
;     ...
; }
; __device__ __forceinline__ void qkt(f32x16& p0, f32x16& p1, const char* Ks, const bf16x8* qr, int r32, int hi) {
;   bf16x8 ka[4], kb[4];
; #pragma unroll
;   for (int d0 = 0; d0 < 4; ++d0) { const int cb = (d0 * 16 + hi * 8) * 2;
;     ka[d0] = *reinterpret_cast<const bf16x8*>(Ks + KSWZ64(r32, cb)); kb[d0] = *reinterpret_cast<const bf16x8*>(Ks + KSWZ64(32 + r32, cb)); }
;   asm volatile("s_waitcnt lgkmcnt(0)" ::: "memory"); SBAR();
;   p0 = f32x16{}; p1 = f32x16{};
; #pragma unroll
;   for (int d0 = 0; d0 < 4; ++d0) {
;     p0 = __builtin_amdgcn_mfma_f32_32x32x16_bf16(ka[d0], qr[d0], p0, 0, 0, 0);
;     p1 = __builtin_amdgcn_mfma_f32_32x32x16_bf16(kb[d0], qr[d0], p1, 0, 0, 0); }
	s_waitcnt vmcnt(2)
	ds_write_b128 v96, v[168:171]
	v_mfma_f32_32x32x16_bf16 v[48:63], v[184:187], v[100:103], v[48:63]
	s_waitcnt vmcnt(1)
	ds_write_b128 v96, v[172:175] offset:8192
	v_lshl_add_u32 v96, s65, 13, v224
	s_waitcnt vmcnt(0)
	ds_write_b128 v96, v[176:179] offset:49152
	v_mfma_f32_32x32x16_bf16 v[48:63], v[188:191], v[104:107], v[48:63]
	v_mfma_f32_32x32x16_bf16 v[48:63], v[192:195], v[108:111], v[48:63]
	v_add_f32_e32 v96, v113, v112
	v_add_f32_e32 v96, v114, v96
	v_add_f32_e32 v96, v115, v96
	v_add_f32_e32 v96, v116, v96
	v_add_f32_e32 v96, v117, v96
	v_add_f32_e32 v96, v118, v96
	v_add_f32_e32 v96, v119, v96
	v_add_f32_e32 v96, v120, v96
	v_add_f32_e32 v96, v121, v96
	v_add_f32_e32 v96, v122, v96
	v_add_f32_e32 v96, v123, v96
	v_exp_f32_e32 v80, v80
	v_add_f32_e32 v96, v124, v96
	v_exp_f32_e32 v81, v81
	v_add_f32_e32 v96, v125, v96
	v_exp_f32_e32 v82, v82
	v_add_f32_e32 v96, v126, v96
	v_exp_f32_e32 v83, v83
	v_add_f32_e32 v96, v127, v96
	v_exp_f32_e32 v84, v84
	v_add_f32_e32 v96, v80, v96
	v_exp_f32_e32 v85, v85
	v_add_f32_e32 v96, v81, v96
	v_exp_f32_e32 v86, v86
	v_add_f32_e32 v96, v82, v96
	v_exp_f32_e32 v87, v87
	v_add_f32_e32 v96, v83, v96
	v_exp_f32_e32 v88, v88
	v_add_f32_e32 v96, v84, v96
	v_exp_f32_e32 v89, v89
	v_add_f32_e32 v96, v85, v96
	v_exp_f32_e32 v90, v90
	v_add_f32_e32 v96, v86, v96
	v_exp_f32_e32 v91, v91
	v_add_f32_e32 v96, v87, v96
	v_exp_f32_e32 v92, v92
	v_add_f32_e32 v96, v88, v96
	v_exp_f32_e32 v93, v93
	v_add_f32_e32 v96, v89, v96
	v_exp_f32_e32 v94, v94
	v_add_f32_e32 v96, v90, v96
	v_exp_f32_e32 v95, v95
	v_add_f32_e32 v96, v91, v96
	v_add_f32_e32 v96, v92, v96
	v_add_f32_e32 v96, v93, v96
	v_add_f32_e32 v96, v94, v96
	v_add_f32_e32 v245, v95, v96
	v_mov_b32_e32 v246, v245
	v_cvt_pk_bf16_f32 v180, v112, v113
	v_cvt_pk_bf16_f32 v181, v114, v115
	v_cvt_pk_bf16_f32 v182, v116, v117
	v_cvt_pk_bf16_f32 v183, v118, v119
	v_cvt_pk_bf16_f32 v188, v120, v121
	v_cvt_pk_bf16_f32 v189, v122, v123
	v_cvt_pk_bf16_f32 v190, v124, v125
	v_cvt_pk_bf16_f32 v191, v126, v127
	v_cvt_pk_bf16_f32 v192, v80, v81
	v_cvt_pk_bf16_f32 v193, v82, v83
	v_cvt_pk_bf16_f32 v194, v84, v85
	v_cvt_pk_bf16_f32 v195, v86, v87
	v_cvt_pk_bf16_f32 v184, v88, v89
	v_cvt_pk_bf16_f32 v185, v90, v91
	v_cvt_pk_bf16_f32 v186, v92, v93
	v_cvt_pk_bf16_f32 v187, v94, v95
	s_nop 1
	v_permlane32_swap_b32_e32 v245, v246
	v_permlane32_swap_b32_e32 v180, v182
	v_permlane32_swap_b32_e32 v181, v183
	v_permlane32_swap_b32_e32 v188, v190
	v_permlane32_swap_b32_e32 v189, v191
	v_permlane32_swap_b32_e32 v192, v194
	v_permlane32_swap_b32_e32 v193, v195
	v_permlane32_swap_b32_e32 v184, v186
	v_permlane32_swap_b32_e32 v185, v187
	s_lshl_b32 s0, s67, 13
	s_add_i32 s0, s0, 0
	v_add_u32_e32 v84, s0, v226
	v_add_u32_e32 v92, s0, v229
	v_add_u32_e32 v100, s0, v231
	v_add_u32_e32 v108, s0, v240
	ds_read_b128 v[80:83], v84 offset:49152
	ds_read_b128 v[84:87], v84 offset:53248
	ds_read_b128 v[88:91], v92 offset:49152
	ds_read_b128 v[92:95], v92 offset:53248
	ds_read_b128 v[96:99], v100 offset:49152
	ds_read_b128 v[100:103], v100 offset:53248
	ds_read_b128 v[104:107], v108 offset:49152
	ds_read_b128 v[108:111], v108 offset:53248
	s_waitcnt lgkmcnt(0)
	s_waitcnt lgkmcnt(7)
	v_mfma_f32_32x32x16_bf16 v[128:143], v[80:83], v[164:167], 0
	s_waitcnt lgkmcnt(6)
	v_mfma_f32_32x32x16_bf16 v[112:127], v[84:87], v[164:167], 0
	s_waitcnt lgkmcnt(5)
	v_mfma_f32_32x32x16_bf16 v[128:143], v[88:91], v[160:163], v[128:143]
	s_waitcnt lgkmcnt(4)
	v_mfma_f32_32x32x16_bf16 v[112:127], v[92:95], v[160:163], v[112:127]
	s_waitcnt lgkmcnt(3)
	v_mfma_f32_32x32x16_bf16 v[128:143], v[96:99], v[152:155], v[128:143]
	s_waitcnt lgkmcnt(2)
	v_mfma_f32_32x32x16_bf16 v[112:127], v[100:103], v[152:155], v[112:127]
	s_waitcnt lgkmcnt(1)
	v_mfma_f32_32x32x16_bf16 v[128:143], v[104:107], v[156:159], v[128:143]
	s_waitcnt lgkmcnt(0)
	v_mfma_f32_32x32x16_bf16 v[112:127], v[108:111], v[156:159], v[112:127]
	s_cmp_lt_u32 s60, 61
	s_cselect_b64 s[0:1], -1, 0
	s_cmp_gt_u32 s60, 60
	s_cbranch_scc1 .LBB0_332
	s_add_u32 s74, s70, 0x18e00000
	s_addc_u32 s75, s71, 0
	global_load_dwordx4 v[168:171], v202, s[74:75] offset:2048
	s_add_u32 s74, s70, 0x18e40000
	s_addc_u32 s75, s71, 0
	global_load_dwordx4 v[172:175], v202, s[74:75] offset:2048
	s_add_u32 s74, s72, 0x18e00000
	s_addc_u32 s75, s73, 0
	global_load_dwordx4 v[176:179], v204, s[74:75] offset:1152

; #define SBAR() __builtin_amdgcn_sched_barrier(0)
; template <int D0> __device__ __forceinline__ void pv_one(f32x16& od, int vb, bf16x8 pa0, bf16x8 pa1, bf16x8 pa2, bf16x8 pa3) {
;   const s16x4 l0 = tr_read<v_rd_off(D0, 0, 0)>(vb), h0 = tr_read<v_rd_off(D0, 0, 1)>(vb), l1 = tr_read<v_rd_off(D0, 1, 0)>(vb), h1 = tr_read<v_rd_off(D0, 1, 1)>(vb);
;   const s16x4 l2 = tr_read<v_rd_off(D0, 2, 0)>(vb), h2 = tr_read<v_rd_off(D0, 2, 1)>(vb), l3 = tr_read<v_rd_off(D0, 3, 0)>(vb), h3 = tr_read<v_rd_off(D0, 3, 1)>(vb);
;   asm volatile("s_waitcnt lgkmcnt(0)" ::: "memory"); SBAR();
;     ...
;   od = __builtin_amdgcn_mfma_f32_32x32x16_bf16(pa0, PK(l0, h0), od, 0, 0, 0);
;   od = __builtin_amdgcn_mfma_f32_32x32x16_bf16(pa1, PK(l1, h1), od, 0, 0, 0);
;   od = __builtin_amdgcn_mfma_f32_32x32x16_bf16(pa2, PK(l2, h2), od, 0, 0, 0);
;   od = __builtin_amdgcn_mfma_f32_32x32x16_bf16(pa3, PK(l3, h3), od, 0, 0, 0);
;     ...
; }
; __device__ __forceinline__ void pv_d0(f32x16* o, int vb, bf16x8 pa0, bf16x8 pa1, bf16x8 pa2, bf16x8 pa3) {
;   pv_one<0>(o[0], vb, pa0, pa1, pa2, pa3); pv_one<1>(o[1], vb, pa0, pa1, pa2, pa3); pv_one<2>(o[2], vb, pa0, pa1, pa2, pa3); pv_one<3>(o[3], vb, pa0, pa1, pa2, pa3);
.LBB0_336:
	s_lshl_b32 s8, s68, 14
	v_add_u32_e32 v128, s8, v219
	ds_read_b64_tr_b16 v[112:113], v128 offset:0
	ds_read_b64_tr_b16 v[114:115], v128 offset:0x800
	ds_read_b64_tr_b16 v[116:117], v128 offset:0x1000
	ds_read_b64_tr_b16 v[118:119], v128 offset:0x1800
	ds_read_b64_tr_b16 v[120:121], v128 offset:0x2000
	ds_read_b64_tr_b16 v[122:123], v128 offset:0x2800
	ds_read_b64_tr_b16 v[124:125], v128 offset:0x3000
	ds_read_b64_tr_b16 v[126:127], v128 offset:0x3800
	s_waitcnt lgkmcnt(0)
	s_nop 0
	v_mfma_f32_32x32x16_bf16 v[0:15], v[180:183], v[112:115], v[0:15]
	ds_read_b64_tr_b16 v[112:113], v128 offset:0x200
	ds_read_b64_tr_b16 v[114:115], v128 offset:0xa00
	v_mfma_f32_32x32x16_bf16 v[0:15], v[188:191], v[116:119], v[0:15]
	ds_read_b64_tr_b16 v[116:117], v128 offset:0x1200
	ds_read_b64_tr_b16 v[118:119], v128 offset:0x1a00
	v_mfma_f32_32x32x16_bf16 v[0:15], v[192:195], v[120:123], v[0:15]
	ds_read_b64_tr_b16 v[120:121], v128 offset:0x2200
	ds_read_b64_tr_b16 v[122:123], v128 offset:0x2a00
	v_mfma_f32_32x32x16_bf16 v[0:15], v[184:187], v[124:127], v[0:15]
	ds_read_b64_tr_b16 v[124:125], v128 offset:0x3200
	ds_read_b64_tr_b16 v[126:127], v128 offset:0x3a00
	s_waitcnt lgkmcnt(0)
	v_mfma_f32_32x32x16_bf16 v[16:31], v[180:183], v[112:115], v[16:31]
	ds_read_b64_tr_b16 v[112:113], v128 offset:0x400
	ds_read_b64_tr_b16 v[114:115], v128 offset:0xc00
	v_mfma_f32_32x32x16_bf16 v[16:31], v[188:191], v[116:119], v[16:31]
	ds_read_b64_tr_b16 v[116:117], v128 offset:0x1400
	ds_read_b64_tr_b16 v[118:119], v128 offset:0x1c00
	v_mfma_f32_32x32x16_bf16 v[16:31], v[192:195], v[120:123], v[16:31]
	ds_read_b64_tr_b16 v[120:121], v128 offset:0x2400
	ds_read_b64_tr_b16 v[122:123], v128 offset:0x2c00
	v_mfma_f32_32x32x16_bf16 v[16:31], v[184:187], v[124:127], v[16:31]
	ds_read_b64_tr_b16 v[124:125], v128 offset:0x3400
	ds_read_b64_tr_b16 v[126:127], v128 offset:0x3c00
	s_waitcnt lgkmcnt(0)
	v_mfma_f32_32x32x16_bf16 v[32:47], v[180:183], v[112:115], v[32:47]
	ds_read_b64_tr_b16 v[112:113], v128 offset:0x600
	ds_read_b64_tr_b16 v[114:115], v128 offset:0xe00
	v_mfma_f32_32x32x16_bf16 v[32:47], v[188:191], v[116:119], v[32:47]
	ds_read_b64_tr_b16 v[116:117], v128 offset:0x1600
	ds_read_b64_tr_b16 v[118:119], v128 offset:0x1e00
	v_mfma_f32_32x32x16_bf16 v[32:47], v[192:195], v[120:123], v[32:47]
	ds_read_b64_tr_b16 v[120:121], v128 offset:0x2600
	ds_read_b64_tr_b16 v[122:123], v128 offset:0x2e00
	v_mfma_f32_32x32x16_bf16 v[32:47], v[184:187], v[124:127], v[32:47]
	ds_read_b64_tr_b16 v[124:125], v128 offset:0x3600
	ds_read_b64_tr_b16 v[126:127], v128 offset:0x3e00
	s_waitcnt lgkmcnt(0)
	v_mfma_f32_32x32x16_bf16 v[48:63], v[180:183], v[112:115], v[48:63]
	s_mov_b64 s[54:55], -1
	s_andn2_b64 vcc, exec, s[0:1]
	s_barrier
	v_mfma_f32_32x32x16_bf16 v[48:63], v[188:191], v[116:119], v[48:63]
	v_mfma_f32_32x32x16_bf16 v[48:63], v[192:195], v[120:123], v[48:63]
	v_mfma_f32_32x32x16_bf16 v[48:63], v[184:187], v[124:127], v[48:63]
	s_cbranch_vccnz .LBB0_338
	s_add_i32 s0, s8, 0
	v_add_u32_e32 v114, s0, v221
	s_add_u32 s70, s70, s16
	s_addc_u32 s71, s71, s17
	s_add_u32 s72, s72, s16
	s_addc_u32 s73, s73, s17
	s_addk_i32 s66, 0x80
	v_add_u32_e32 v242, 0x200, v242
	s_add_i32 s60, s60, 2
	s_mov_b64 s[54:55], 0
	v_add_u32_e32 v112, s4, v223
	s_waitcnt vmcnt(2)
	ds_write_b128 v114, v[168:171]
	s_waitcnt vmcnt(1)
	ds_write_b128 v114, v[172:175] offset:8192
	s_waitcnt vmcnt(0)
	ds_write_b128 v112, v[176:179] offset:49152

; __device__ __forceinline__ void finishSM(f32x16& p0, f32x16& p1, float alpha, float& l_reg, bf16x8& pa0, bf16x8& pa1, bf16x8& pa2, bf16x8& pa3) {
; #pragma unroll
;   for (int r = 0; r < 16; ++r) p1[r] = __builtin_amdgcn_exp2f(p1[r]);
;   float ps = 0;
; #pragma unroll
;   for (int r = 0; r < 16; ++r) ps += p0[r];
; #pragma unroll
;   for (int r = 0; r < 16; ++r) ps += p1[r];
;   { auto rr = __builtin_amdgcn_permlane32_swap(__float_as_uint(ps), __float_as_uint(ps), false, false);
;     ps = __uint_as_float(rr[0]) + __uint_as_float(rr[1]); }
;   l_reg = l_reg * alpha + ps;
;     ...
;   PK4(p0, 0, pa0); PK4(p0, 8, pa1); PK4(p1, 0, pa2); PK4(p1, 8, pa3);
;     ...
; }
; __device__ __forceinline__ void qkt(f32x16& p0, f32x16& p1, const char* Ks, const bf16x8* qr, int r32, int hi) {
;   bf16x8 ka[4], kb[4];
; #pragma unroll
;   for (int d0 = 0; d0 < 4; ++d0) { const int cb = (d0 * 16 + hi * 8) * 2;
;     ka[d0] = *reinterpret_cast<const bf16x8*>(Ks + KSWZ64(r32, cb)); kb[d0] = *reinterpret_cast<const bf16x8*>(Ks + KSWZ64(32 + r32, cb)); }
;   asm volatile("s_waitcnt lgkmcnt(0)" ::: "memory"); SBAR();
;   p0 = f32x16{}; p1 = f32x16{};
; #pragma unroll
;   for (int d0 = 0; d0 < 4; ++d0) {
;     p0 = __builtin_amdgcn_mfma_f32_32x32x16_bf16(ka[d0], qr[d0], p0, 0, 0, 0);
;     p1 = __builtin_amdgcn_mfma_f32_32x32x16_bf16(kb[d0], qr[d0], p1, 0, 0, 0); }
; }
; __device__ __forceinline__ int v_st(int k, int c) { const int kk = (k & ~0xC) | ((k & 4) << 1) | ((k & 8) >> 1); return ((kk >> 3) * 4 + (c >> 5)) * 512 + ((kk & 7) * 32 + (c & 31)) * 2; }
; __device__ __forceinline__ int v_rd_base(int lane) { return ((lane & 3) << 3) | (((lane >> 2) & 3) << 6) | (((lane >> 4) & 1) << 5) | (((lane >> 5) & 1) << 8); }
; template <int OFF> __device__ __forceinline__ s16x4 tr_read(int vb) {
;   s16x4 r; asm volatile("ds_read_b64_tr_b16 %0, %1 offset:%2" : "=&v"(r) : "v"(vb), "i"(OFF) : "memory"); return r;
; }
; template <int D0> __device__ __forceinline__ void pv_one(f32x16& od, int vb, bf16x8 pa0, bf16x8 pa1, bf16x8 pa2, bf16x8 pa3) {
;   const s16x4 l0 = tr_read<v_rd_off(D0, 0, 0)>(vb), h0 = tr_read<v_rd_off(D0, 0, 1)>(vb), l1 = tr_read<v_rd_off(D0, 1, 0)>(vb), h1 = tr_read<v_rd_off(D0, 1, 1)>(vb);
;   const s16x4 l2 = tr_read<v_rd_off(D0, 2, 0)>(vb), h2 = tr_read<v_rd_off(D0, 2, 1)>(vb), l3 = tr_read<v_rd_off(D0, 3, 0)>(vb), h3 = tr_read<v_rd_off(D0, 3, 1)>(vb);
.LBB0_340:
	ds_read_b128 v[96:99], v225 offset:49152
	ds_read_b128 v[100:103], v225 offset:53248
	s_waitcnt vmcnt(2)
	ds_read_b128 v[168:171], v227 offset:49152
	s_waitcnt vmcnt(1)
	ds_read_b128 v[172:175], v227 offset:53248
	s_waitcnt vmcnt(0)
	ds_read_b128 v[176:179], v228 offset:49152
	ds_read_b128 v[180:183], v228 offset:53248
	ds_read_b128 v[184:187], v230 offset:49152
	ds_read_b128 v[188:191], v230 offset:53248
	s_waitcnt lgkmcnt(0)
	v_exp_f32_e32 v192, v80
	v_add_f32_e32 v80, v143, v141
	s_waitcnt lgkmcnt(7)
	v_mfma_f32_32x32x16_bf16 v[112:127], v[96:99], v[164:167], 0
	v_add_f32_e32 v80, v139, v80
	v_add_f32_e32 v80, v142, v80
	v_add_f32_e32 v80, v137, v80
	v_add_f32_e32 v80, v140, v80
	v_add_f32_e32 v80, v136, v80
	v_add_f32_e32 v80, v138, v80
	v_add_f32_e32 v80, v133, v80
	s_waitcnt lgkmcnt(6)
	v_mfma_f32_32x32x16_bf16 v[96:111], v[100:103], v[164:167], 0
	v_add_f32_e32 v80, v135, v80
	v_add_f32_e32 v80, v131, v80
	v_add_f32_e32 v80, v134, v80
	v_add_f32_e32 v80, v129, v80
	v_exp_f32_e32 v193, v81
	v_add_f32_e32 v80, v132, v80
	v_exp_f32_e32 v194, v82
	s_waitcnt lgkmcnt(5)
	v_mfma_f32_32x32x16_bf16 v[112:127], v[168:171], v[160:163], v[112:127]
	v_add_f32_e32 v80, v128, v80
	v_exp_f32_e32 v195, v83
	v_add_f32_e32 v80, v130, v80
	v_exp_f32_e32 v202, v84
	v_add_f32_e32 v80, v192, v80
	v_exp_f32_e32 v203, v85
	v_add_f32_e32 v80, v193, v80
	s_waitcnt lgkmcnt(4)
	v_mfma_f32_32x32x16_bf16 v[96:111], v[172:175], v[160:163], v[96:111]
	v_exp_f32_e32 v204, v86
	v_add_f32_e32 v80, v194, v80
	v_exp_f32_e32 v205, v87
	v_add_f32_e32 v80, v195, v80
	v_exp_f32_e32 v206, v88
	v_add_f32_e32 v80, v202, v80
	v_exp_f32_e32 v207, v89
	s_waitcnt lgkmcnt(3)
	v_mfma_f32_32x32x16_bf16 v[112:127], v[176:179], v[152:155], v[112:127]
	v_add_f32_e32 v80, v203, v80
	v_exp_f32_e32 v208, v90
	v_add_f32_e32 v80, v204, v80
	v_exp_f32_e32 v209, v91
	v_add_f32_e32 v80, v205, v80
	v_exp_f32_e32 v221, v92
	v_add_f32_e32 v80, v206, v80
	s_waitcnt lgkmcnt(2)
	v_mfma_f32_32x32x16_bf16 v[96:111], v[180:183], v[152:155], v[96:111]
	v_exp_f32_e32 v164, v93
	v_add_f32_e32 v80, v207, v80
	v_exp_f32_e32 v165, v94
	v_add_f32_e32 v80, v208, v80
	v_exp_f32_e32 v95, v95
	v_add_f32_e32 v80, v209, v80
	v_add_f32_e32 v80, v221, v80
	s_waitcnt lgkmcnt(1)
	v_mfma_f32_32x32x16_bf16 v[112:127], v[184:187], v[156:159], v[112:127]
	v_add_f32_e32 v80, v164, v80
	v_add_f32_e32 v80, v165, v80
	v_add_f32_e32 v152, v95, v80
	v_mov_b32_e32 v153, v152
	v_cvt_pk_bf16_f32 v80, v141, v143
	v_cvt_pk_bf16_f32 v81, v139, v142
	v_cvt_pk_bf16_f32 v82, v137, v140
	s_waitcnt lgkmcnt(0)
	v_mfma_f32_32x32x16_bf16 v[96:111], v[188:191], v[156:159], v[96:111]
	v_cvt_pk_bf16_f32 v83, v136, v138
	v_cvt_pk_bf16_f32 v84, v133, v135
	v_cvt_pk_bf16_f32 v85, v131, v134
	v_cvt_pk_bf16_f32 v86, v129, v132
	v_cvt_pk_bf16_f32 v87, v128, v130
	v_cvt_pk_bf16_f32 v88, v192, v193
	v_cvt_pk_bf16_f32 v89, v194, v195
	v_cvt_pk_bf16_f32 v90, v202, v203
	v_cvt_pk_bf16_f32 v91, v204, v205
	v_cvt_pk_bf16_f32 v92, v206, v207
	v_cvt_pk_bf16_f32 v93, v208, v209
	v_cvt_pk_bf16_f32 v94, v221, v164
	v_cvt_pk_bf16_f32 v95, v165, v95
	v_permlane32_swap_b32_e32 v152, v153
	v_permlane32_swap_b32_e32 v80, v82
	v_permlane32_swap_b32_e32 v81, v83
	v_permlane32_swap_b32_e32 v84, v86
	v_permlane32_swap_b32_e32 v85, v87
	v_permlane32_swap_b32_e32 v88, v90
	v_permlane32_swap_b32_e32 v89, v91
	v_permlane32_swap_b32_e32 v92, v94
	v_permlane32_swap_b32_e32 v93, v95
	s_cmp_lg_u32 0, -1
	s_cselect_b32 s0, 0, 0
	s_add_i32 s0, s0, 0x8000
	v_add_u32_e32 v154, s0, v241
	ds_read_b64_tr_b16 v[128:129], v154 offset:0
	ds_read_b64_tr_b16 v[130:131], v154 offset:0x800
	ds_read_b64_tr_b16 v[132:133], v154 offset:0x1000
	ds_read_b64_tr_b16 v[134:135], v154 offset:0x1800
	ds_read_b64_tr_b16 v[136:137], v154 offset:0x2000
	ds_read_b64_tr_b16 v[138:139], v154 offset:0x2800
	ds_read_b64_tr_b16 v[140:141], v154 offset:0x3000
	ds_read_b64_tr_b16 v[142:143], v154 offset:0x3800
	s_waitcnt lgkmcnt(0)
	s_nop 0
	v_mfma_f32_32x32x16_bf16 v[0:15], v[80:83], v[128:131], v[0:15]
	ds_read_b64_tr_b16 v[128:129], v154 offset:0x200
	ds_read_b64_tr_b16 v[130:131], v154 offset:0xa00
	v_mfma_f32_32x32x16_bf16 v[0:15], v[84:87], v[132:135], v[0:15]
	ds_read_b64_tr_b16 v[132:133], v154 offset:0x1200
	ds_read_b64_tr_b16 v[134:135], v154 offset:0x1a00
	v_mfma_f32_32x32x16_bf16 v[0:15], v[88:91], v[136:139], v[0:15]
	ds_read_b64_tr_b16 v[136:137], v154 offset:0x2200
	ds_read_b64_tr_b16 v[138:139], v154 offset:0x2a00
	v_mfma_f32_32x32x16_bf16 v[0:15], v[92:95], v[140:143], v[0:15]
	ds_read_b64_tr_b16 v[140:141], v154 offset:0x3200
	ds_read_b64_tr_b16 v[142:143], v154 offset:0x3a00
	s_waitcnt lgkmcnt(0)
	v_mfma_f32_32x32x16_bf16 v[16:31], v[80:83], v[128:131], v[16:31]
	ds_read_b64_tr_b16 v[128:129], v154 offset:0x400
	ds_read_b64_tr_b16 v[130:131], v154 offset:0xc00
	v_mfma_f32_32x32x16_bf16 v[16:31], v[84:87], v[132:135], v[16:31]
	ds_read_b64_tr_b16 v[132:133], v154 offset:0x1400
	ds_read_b64_tr_b16 v[134:135], v154 offset:0x1c00
	v_mfma_f32_32x32x16_bf16 v[16:31], v[88:91], v[136:139], v[16:31]
	ds_read_b64_tr_b16 v[136:137], v154 offset:0x2400
	ds_read_b64_tr_b16 v[138:139], v154 offset:0x2c00
	v_mfma_f32_32x32x16_bf16 v[16:31], v[92:95], v[140:143], v[16:31]
	ds_read_b64_tr_b16 v[140:141], v154 offset:0x3400
	ds_read_b64_tr_b16 v[142:143], v154 offset:0x3c00
	s_waitcnt lgkmcnt(0)
	v_mfma_f32_32x32x16_bf16 v[32:47], v[80:83], v[128:131], v[32:47]
	ds_read_b64_tr_b16 v[128:129], v154 offset:0x600
	ds_read_b64_tr_b16 v[130:131], v154 offset:0xe00
	v_mfma_f32_32x32x16_bf16 v[32:47], v[84:87], v[132:135], v[32:47]
	ds_read_b64_tr_b16 v[132:133], v154 offset:0x1600
	ds_read_b64_tr_b16 v[134:135], v154 offset:0x1e00
	v_mfma_f32_32x32x16_bf16 v[32:47], v[88:91], v[136:139], v[32:47]
	ds_read_b64_tr_b16 v[136:137], v154 offset:0x2600
	ds_read_b64_tr_b16 v[138:139], v154 offset:0x2e00
	v_mfma_f32_32x32x16_bf16 v[32:47], v[92:95], v[140:143], v[32:47]
	ds_read_b64_tr_b16 v[140:141], v154 offset:0x3600
	ds_read_b64_tr_b16 v[142:143], v154 offset:0x3e00
	s_waitcnt lgkmcnt(0)
	v_mfma_f32_32x32x16_bf16 v[48:63], v[80:83], v[128:131], v[48:63]
	s_add_i32 s2, s64, 0xffffefa6
	s_mov_b64 s[0:1], -1
	s_cmp_gt_u32 s2, 0xfffffeec
	v_mfma_f32_32x32x16_bf16 v[48:63], v[84:87], v[132:135], v[48:63]
	v_mfma_f32_32x32x16_bf16 v[48:63], v[88:91], v[136:139], v[48:63]
	v_mfma_f32_32x32x16_bf16 v[48:63], v[92:95], v[140:143], v[48:63]
	s_cbranch_scc0 .LBB0_342
; __device__ __forceinline__ void partialSM(f32x16& p0, f32x16& p1, float& m_reg, float& mn, float& alpha, int kt0, int qpos, int qw, int hi, const float* tb2, float cL, float cR) {
;     ...
;     const float* tp = tb2 + (kt0 - qpos + 192 + 4 * hi);
; #pragma unroll
;     for (int r4 = 0; r4 < 4; ++r4) {
;       float ta[4], tb[4];
; #pragma unroll
;       for (int i = 0; i < 4; ++i) { ta[i] = tp[8 * r4 + i] - m_reg; tb[i] = tp[32 + 8 * r4 + i] - m_reg; }
; #pragma unroll
;       for (int i = 0; i < 4; ++i) { p0[4 * r4 + i] = fmaf(p0[4 * r4 + i], C1, ta[i]); p1[4 * r4 + i] = fmaf(p1[4 * r4 + i], C1, tb[i]); }
	v_sub_u32_e32 v80, 0xfc0, v147
	s_add_i32 s0, 0, 0x12b00
	v_lshlrev_b32_e32 v80, 2, v80
	v_add3_u32 v140, s0, v200, v80
	ds_read2_b32 v[80:81], v140 offset1:1
	ds_read2_b32 v[128:129], v140 offset0:32 offset1:33
	ds_read2_b32 v[130:131], v140 offset0:34 offset1:35
	ds_read2_b32 v[82:83], v140 offset0:2 offset1:3
	ds_read2_b32 v[84:85], v140 offset0:8 offset1:9
	ds_read2_b32 v[132:133], v140 offset0:40 offset1:41
	ds_read2_b32 v[134:135], v140 offset0:42 offset1:43
	ds_read2_b32 v[86:87], v140 offset0:10 offset1:11
	ds_read2_b32 v[88:89], v140 offset0:16 offset1:17
	ds_read2_b32 v[136:137], v140 offset0:48 offset1:49
	ds_read2_b32 v[138:139], v140 offset0:50 offset1:51
	ds_read2_b32 v[90:91], v140 offset0:18 offset1:19
	ds_read2_b32 v[92:93], v140 offset0:24 offset1:25
	ds_read2_b32 v[94:95], v140 offset0:56 offset1:57
	s_waitcnt lgkmcnt(5)
	v_sub_f32_e32 v89, v89, v75
	s_waitcnt lgkmcnt(4)
	v_sub_f32_e32 v137, v137, v75
	v_sub_f32_e32 v88, v88, v72
	s_waitcnt lgkmcnt(1)
	v_sub_f32_e32 v93, v93, v79
	s_waitcnt lgkmcnt(0)
	v_sub_f32_e32 v79, v95, v79
	v_sub_f32_e32 v92, v92, v78
	v_sub_f32_e32 v78, v94, v78
	ds_read2_b32 v[94:95], v140 offset0:26 offset1:27
	ds_read2_b32 v[140:141], v140 offset0:58 offset1:59
	v_sub_f32_e32 v91, v91, v73
	v_sub_f32_e32 v90, v90, v74
	s_waitcnt lgkmcnt(1)
	v_sub_f32_e32 v95, v95, v77
	s_waitcnt lgkmcnt(0)
	v_sub_f32_e32 v77, v141, v77
	v_sub_f32_e32 v94, v94, v76
	v_sub_f32_e32 v76, v140, v76
	v_sub_f32_e32 v85, v85, v69
	v_sub_f32_e32 v84, v84, v68
	v_sub_f32_e32 v87, v87, v71
	v_sub_f32_e32 v86, v86, v70
	v_sub_f32_e32 v81, v81, v65
	v_sub_f32_e32 v80, v80, v64
	v_sub_f32_e32 v83, v83, v67
	v_sub_f32_e32 v82, v82, v66
	v_sub_f32_e32 v136, v136, v72
	v_sub_f32_e32 v73, v139, v73
	v_sub_f32_e32 v72, v138, v74
	v_sub_f32_e32 v69, v133, v69
	v_sub_f32_e32 v68, v132, v68
	v_sub_f32_e32 v71, v135, v71
	v_sub_f32_e32 v70, v134, v70
	v_sub_f32_e32 v75, v129, v65
	v_sub_f32_e32 v74, v128, v64
	v_sub_f32_e32 v67, v131, v67
	v_sub_f32_e32 v66, v130, v66
	v_pk_fma_f32 v[82:83], v[114:115], s[6:7], v[82:83] op_sel_hi:[1,0,1]
	v_pk_fma_f32 v[80:81], v[112:113], s[6:7], v[80:81] op_sel_hi:[1,0,1]
	v_pk_fma_f32 v[86:87], v[118:119], s[6:7], v[86:87] op_sel_hi:[1,0,1]
	v_pk_fma_f32 v[84:85], v[116:117], s[6:7], v[84:85] op_sel_hi:[1,0,1]
	v_pk_fma_f32 v[90:91], v[122:123], s[6:7], v[90:91] op_sel_hi:[1,0,1]
	v_pk_fma_f32 v[88:89], v[120:121], s[6:7], v[88:89] op_sel_hi:[1,0,1]
	v_pk_fma_f32 v[94:95], v[126:127], s[6:7], v[94:95] op_sel_hi:[1,0,1]
	v_pk_fma_f32 v[92:93], v[124:125], s[6:7], v[92:93] op_sel_hi:[1,0,1]
	v_pk_fma_f32 v[130:131], v[98:99], s[6:7], v[66:67] op_sel_hi:[1,0,1]
	v_pk_fma_f32 v[128:129], v[96:97], s[6:7], v[74:75] op_sel_hi:[1,0,1]
	v_pk_fma_f32 v[134:135], v[102:103], s[6:7], v[70:71] op_sel_hi:[1,0,1]
	v_pk_fma_f32 v[132:133], v[100:101], s[6:7], v[68:69] op_sel_hi:[1,0,1]
	v_pk_fma_f32 v[138:139], v[106:107], s[6:7], v[72:73] op_sel_hi:[1,0,1]
	v_pk_fma_f32 v[136:137], v[104:105], s[6:7], v[136:137] op_sel_hi:[1,0,1]
	v_pk_fma_f32 v[142:143], v[110:111], s[6:7], v[76:77] op_sel_hi:[1,0,1]
	v_pk_fma_f32 v[140:141], v[108:109], s[6:7], v[78:79] op_sel_hi:[1,0,1]
	s_mov_b64 s[0:1], 0

; __device__ __forceinline__ void finishSM(f32x16& p0, f32x16& p1, float alpha, float& l_reg, bf16x8& pa0, bf16x8& pa1, bf16x8& pa2, bf16x8& pa3) {
; #pragma unroll
;   for (int r = 0; r < 16; ++r) p1[r] = __builtin_amdgcn_exp2f(p1[r]);
;   float ps = 0;
; #pragma unroll
;   for (int r = 0; r < 16; ++r) ps += p0[r];
; #pragma unroll
;   for (int r = 0; r < 16; ++r) ps += p1[r];
;   { auto rr = __builtin_amdgcn_permlane32_swap(__float_as_uint(ps), __float_as_uint(ps), false, false);
;     ps = __uint_as_float(rr[0]) + __uint_as_float(rr[1]); }
;   l_reg = l_reg * alpha + ps;
;     ...
;   PK4(p0, 0, pa0); PK4(p0, 8, pa1); PK4(p1, 0, pa2); PK4(p1, 8, pa3);
;     ...
; }
; __device__ __forceinline__ void qkt(f32x16& p0, f32x16& p1, const char* Ks, const bf16x8* qr, int r32, int hi) {
;   bf16x8 ka[4], kb[4];
; #pragma unroll
;   for (int d0 = 0; d0 < 4; ++d0) { const int cb = (d0 * 16 + hi * 8) * 2;
;     ka[d0] = *reinterpret_cast<const bf16x8*>(Ks + KSWZ64(r32, cb)); kb[d0] = *reinterpret_cast<const bf16x8*>(Ks + KSWZ64(32 + r32, cb)); }
;   asm volatile("s_waitcnt lgkmcnt(0)" ::: "memory"); SBAR();
;   p0 = f32x16{}; p1 = f32x16{};
; #pragma unroll
;   for (int d0 = 0; d0 < 4; ++d0) {
;     p0 = __builtin_amdgcn_mfma_f32_32x32x16_bf16(ka[d0], qr[d0], p0, 0, 0, 0);
;     p1 = __builtin_amdgcn_mfma_f32_32x32x16_bf16(kb[d0], qr[d0], p1, 0, 0, 0); }
; }
; __device__ __forceinline__ int v_st(int k, int c) { const int kk = (k & ~0xC) | ((k & 4) << 1) | ((k & 8) >> 1); return ((kk >> 3) * 4 + (c >> 5)) * 512 + ((kk & 7) * 32 + (c & 31)) * 2; }
; __device__ __forceinline__ int v_rd_base(int lane) { return ((lane & 3) << 3) | (((lane >> 2) & 3) << 6) | (((lane >> 4) & 1) << 5) | (((lane >> 5) & 1) << 8); }
; template <int OFF> __device__ __forceinline__ s16x4 tr_read(int vb) {
;   s16x4 r; asm volatile("ds_read_b64_tr_b16 %0, %1 offset:%2" : "=&v"(r) : "v"(vb), "i"(OFF) : "memory"); return r;
; }
; template <int D0> __device__ __forceinline__ void pv_one(f32x16& od, int vb, bf16x8 pa0, bf16x8 pa1, bf16x8 pa2, bf16x8 pa3) {
;   const s16x4 l0 = tr_read<v_rd_off(D0, 0, 0)>(vb), h0 = tr_read<v_rd_off(D0, 0, 1)>(vb), l1 = tr_read<v_rd_off(D0, 1, 0)>(vb), h1 = tr_read<v_rd_off(D0, 1, 1)>(vb);
;   const s16x4 l2 = tr_read<v_rd_off(D0, 2, 0)>(vb), h2 = tr_read<v_rd_off(D0, 2, 1)>(vb), l3 = tr_read<v_rd_off(D0, 3, 0)>(vb), h3 = tr_read<v_rd_off(D0, 3, 1)>(vb);
.LBB0_353:
	s_mov_b32 s65, s61
	s_mov_b32 s61, s0
	s_lshl_b32 s0, s65, 13
	s_add_i32 s36, s0, 0
	v_add_u32_e32 v100, s36, v202
	v_add_u32_e32 v104, s36, v205
	ds_read_b128 v[96:99], v100 offset:49152
	ds_read_b128 v[100:103], v100 offset:53248
	ds_read_b128 v[136:139], v104 offset:49152
	ds_read_b128 v[140:143], v104 offset:53248
	v_add_u32_e32 v104, s36, v207
	s_waitcnt vmcnt(0)
	ds_read_b128 v[176:179], v104 offset:49152
	ds_read_b128 v[186:189], v104 offset:53248
	v_add_u32_e32 v104, s36, v208
	ds_read_b128 v[218:221], v104 offset:49152
	ds_read_b128 v[222:225], v104 offset:53248
	s_waitcnt lgkmcnt(0)
	v_exp_f32_e32 v226, v80
	v_add_f32_e32 v80, v175, v173
	s_waitcnt lgkmcnt(7)
	v_mfma_f32_32x32x16_bf16 v[112:127], v[96:99], v[164:167], 0
	v_add_f32_e32 v80, v171, v80
	v_add_f32_e32 v80, v174, v80
	v_add_f32_e32 v80, v169, v80
	v_add_f32_e32 v80, v172, v80
	v_add_f32_e32 v80, v168, v80
	v_add_f32_e32 v80, v170, v80
	v_add_f32_e32 v80, v133, v80
	s_waitcnt lgkmcnt(6)
	v_mfma_f32_32x32x16_bf16 v[96:111], v[100:103], v[164:167], 0
	v_add_f32_e32 v80, v135, v80
	v_add_f32_e32 v80, v131, v80
	v_add_f32_e32 v80, v134, v80
	v_add_f32_e32 v80, v129, v80
	v_exp_f32_e32 v227, v81
	v_add_f32_e32 v80, v132, v80
	v_exp_f32_e32 v228, v82
	s_waitcnt lgkmcnt(5)
	v_mfma_f32_32x32x16_bf16 v[112:127], v[136:139], v[160:163], v[112:127]
	v_add_f32_e32 v80, v128, v80
	v_exp_f32_e32 v229, v83
	v_add_f32_e32 v80, v130, v80
	v_exp_f32_e32 v230, v84
	v_add_f32_e32 v80, v226, v80
	v_exp_f32_e32 v231, v85
	v_add_f32_e32 v80, v227, v80
	s_waitcnt lgkmcnt(4)
	v_mfma_f32_32x32x16_bf16 v[96:111], v[140:143], v[160:163], v[96:111]
	v_exp_f32_e32 v240, v86
	v_add_f32_e32 v80, v228, v80
	v_exp_f32_e32 v241, v87
	v_add_f32_e32 v80, v229, v80
	v_exp_f32_e32 v242, v88
	v_add_f32_e32 v80, v230, v80
	v_exp_f32_e32 v243, v89
	s_waitcnt lgkmcnt(3)
	v_mfma_f32_32x32x16_bf16 v[112:127], v[176:179], v[156:159], v[112:127]
	v_add_f32_e32 v80, v231, v80
	v_exp_f32_e32 v244, v90
	v_add_f32_e32 v80, v240, v80
	v_exp_f32_e32 v245, v91
	v_add_f32_e32 v80, v241, v80
	v_exp_f32_e32 v246, v92
	v_add_f32_e32 v80, v242, v80
	s_waitcnt lgkmcnt(2)
	v_mfma_f32_32x32x16_bf16 v[96:111], v[186:189], v[156:159], v[96:111]
	v_exp_f32_e32 v247, v93
	v_add_f32_e32 v80, v243, v80
	v_exp_f32_e32 v248, v94
	v_add_f32_e32 v80, v244, v80
	v_exp_f32_e32 v95, v95
	v_add_f32_e32 v80, v245, v80
	v_add_f32_e32 v80, v246, v80
	s_waitcnt lgkmcnt(1)
	v_mfma_f32_32x32x16_bf16 v[112:127], v[218:221], v[152:155], v[112:127]
	v_add_f32_e32 v80, v247, v80
	v_add_f32_e32 v80, v248, v80
	v_add_f32_e32 v216, v95, v80
	v_mov_b32_e32 v217, v216
	v_cvt_pk_bf16_f32 v80, v173, v175
	v_cvt_pk_bf16_f32 v81, v171, v174
	v_cvt_pk_bf16_f32 v82, v169, v172
	s_waitcnt lgkmcnt(0)
	v_mfma_f32_32x32x16_bf16 v[96:111], v[222:225], v[152:155], v[96:111]
	v_cvt_pk_bf16_f32 v83, v168, v170
	v_cvt_pk_bf16_f32 v84, v133, v135
	v_cvt_pk_bf16_f32 v85, v131, v134
	v_cvt_pk_bf16_f32 v86, v129, v132
	v_cvt_pk_bf16_f32 v87, v128, v130
	v_cvt_pk_bf16_f32 v88, v226, v227
	v_cvt_pk_bf16_f32 v89, v228, v229
	v_cvt_pk_bf16_f32 v90, v230, v231
	v_cvt_pk_bf16_f32 v91, v240, v241
	v_cvt_pk_bf16_f32 v92, v242, v243
	v_cvt_pk_bf16_f32 v93, v244, v245
	v_cvt_pk_bf16_f32 v94, v246, v247
	v_cvt_pk_bf16_f32 v95, v248, v95
	v_permlane32_swap_b32_e32 v216, v217
	v_permlane32_swap_b32_e32 v80, v82
	v_permlane32_swap_b32_e32 v81, v83
	v_permlane32_swap_b32_e32 v84, v86
	v_permlane32_swap_b32_e32 v85, v87
	v_permlane32_swap_b32_e32 v88, v90
	v_permlane32_swap_b32_e32 v89, v91
	v_permlane32_swap_b32_e32 v92, v94
	v_permlane32_swap_b32_e32 v93, v95
	s_mov_b32 s0, 0x18dc0000
	s_add_u32 s74, s70, s15
	s_addc_u32 s75, s71, 0
	global_load_dwordx4 v[168:171], v182, s[74:75] offset:2048
	s_add_u32 s74, s70, s0
	s_addc_u32 s75, s71, 0
	global_load_dwordx4 v[172:175], v182, s[74:75] offset:2048
	s_add_u32 s74, s72, s15
	s_addc_u32 s75, s73, 0
	global_load_dwordx4 v[176:179], v184, s[74:75] offset:1024
	s_lshl_b32 s4, s61, 14
	v_add_u32_e32 v218, s4, v194
	ds_read_b64_tr_b16 v[128:129], v218 offset:0
	ds_read_b64_tr_b16 v[130:131], v218 offset:0x800
	ds_read_b64_tr_b16 v[132:133], v218 offset:0x1000
	ds_read_b64_tr_b16 v[134:135], v218 offset:0x1800
	ds_read_b64_tr_b16 v[136:137], v218 offset:0x2000
	ds_read_b64_tr_b16 v[138:139], v218 offset:0x2800
	ds_read_b64_tr_b16 v[140:141], v218 offset:0x3000
	ds_read_b64_tr_b16 v[142:143], v218 offset:0x3800
	s_waitcnt lgkmcnt(0)
	s_nop 0
	v_mfma_f32_32x32x16_bf16 v[2:17], v[80:83], v[128:131], v[2:17]
	ds_read_b64_tr_b16 v[128:129], v218 offset:0x200
	ds_read_b64_tr_b16 v[130:131], v218 offset:0xa00
	v_mfma_f32_32x32x16_bf16 v[2:17], v[84:87], v[132:135], v[2:17]
	ds_read_b64_tr_b16 v[132:133], v218 offset:0x1200
	ds_read_b64_tr_b16 v[134:135], v218 offset:0x1a00
	v_mfma_f32_32x32x16_bf16 v[2:17], v[88:91], v[136:139], v[2:17]
	ds_read_b64_tr_b16 v[136:137], v218 offset:0x2200
	ds_read_b64_tr_b16 v[138:139], v218 offset:0x2a00
	v_mfma_f32_32x32x16_bf16 v[2:17], v[92:95], v[140:143], v[2:17]
	ds_read_b64_tr_b16 v[140:141], v218 offset:0x3200
	ds_read_b64_tr_b16 v[142:143], v218 offset:0x3a00
	s_waitcnt lgkmcnt(0)
	v_mfma_f32_32x32x16_bf16 v[18:33], v[80:83], v[128:131], v[18:33]
	ds_read_b64_tr_b16 v[128:129], v218 offset:0x400
	ds_read_b64_tr_b16 v[130:131], v218 offset:0xc00
	v_mfma_f32_32x32x16_bf16 v[18:33], v[84:87], v[132:135], v[18:33]
	ds_read_b64_tr_b16 v[132:133], v218 offset:0x1400
	ds_read_b64_tr_b16 v[134:135], v218 offset:0x1c00
	v_mfma_f32_32x32x16_bf16 v[18:33], v[88:91], v[136:139], v[18:33]
	ds_read_b64_tr_b16 v[136:137], v218 offset:0x2400
	ds_read_b64_tr_b16 v[138:139], v218 offset:0x2c00
	v_mfma_f32_32x32x16_bf16 v[18:33], v[92:95], v[140:143], v[18:33]
	ds_read_b64_tr_b16 v[140:141], v218 offset:0x3400
	ds_read_b64_tr_b16 v[142:143], v218 offset:0x3c00
	s_waitcnt lgkmcnt(0)
	v_mfma_f32_32x32x16_bf16 v[34:49], v[80:83], v[128:131], v[34:49]
	ds_read_b64_tr_b16 v[128:129], v218 offset:0x600
	ds_read_b64_tr_b16 v[130:131], v218 offset:0xe00
	v_mfma_f32_32x32x16_bf16 v[34:49], v[84:87], v[132:135], v[34:49]
	ds_read_b64_tr_b16 v[132:133], v218 offset:0x1600
	ds_read_b64_tr_b16 v[134:135], v218 offset:0x1e00
	v_mfma_f32_32x32x16_bf16 v[34:49], v[88:91], v[136:139], v[34:49]
	ds_read_b64_tr_b16 v[136:137], v218 offset:0x2600
	ds_read_b64_tr_b16 v[138:139], v218 offset:0x2e00
	v_mfma_f32_32x32x16_bf16 v[34:49], v[92:95], v[140:143], v[34:49]
	ds_read_b64_tr_b16 v[140:141], v218 offset:0x3600
	ds_read_b64_tr_b16 v[142:143], v218 offset:0x3e00
	s_waitcnt lgkmcnt(0)
	v_mfma_f32_32x32x16_bf16 v[50:65], v[80:83], v[128:131], v[50:65]
	s_add_i32 s5, s62, 0xffffff47
	s_mov_b64 s[0:1], -1
	s_cmp_gt_u32 s5, 0xfffffeec
	v_mfma_f32_32x32x16_bf16 v[50:65], v[84:87], v[132:135], v[50:65]
	v_mfma_f32_32x32x16_bf16 v[50:65], v[88:91], v[136:139], v[50:65]
	v_mfma_f32_32x32x16_bf16 v[50:65], v[92:95], v[140:143], v[50:65]
	s_cbranch_scc0 .Lfastp_4
; __device__ __forceinline__ void partialSM(f32x16& p0, f32x16& p1, float& m_reg, float& mn, float& alpha, int kt0, int qpos, int qw, int hi, const float* tb2, float cL, float cR) {
;     ...
;     const float* tp = tb2 + (kt0 - qpos + 192 + 4 * hi);
; #pragma unroll
;     for (int r4 = 0; r4 < 4; ++r4) {
;       float ta[4], tb[4];
; #pragma unroll
;       for (int i = 0; i < 4; ++i) { ta[i] = tp[8 * r4 + i] - m_reg; tb[i] = tp[32 + 8 * r4 + i] - m_reg; }
; #pragma unroll
;       for (int i = 0; i < 4; ++i) { p0[4 * r4 + i] = fmaf(p0[4 * r4 + i], C1, ta[i]); p1[4 * r4 + i] = fmaf(p1[4 * r4 + i], C1, tb[i]); }
	ds_read2_b32 v[80:81], v215 offset1:1
	ds_read2_b32 v[128:129], v215 offset0:32 offset1:33
	ds_read2_b32 v[130:131], v215 offset0:34 offset1:35
	ds_read2_b32 v[82:83], v215 offset0:2 offset1:3
	ds_read2_b32 v[84:85], v215 offset0:8 offset1:9
	ds_read2_b32 v[132:133], v215 offset0:40 offset1:41
	ds_read2_b32 v[134:135], v215 offset0:42 offset1:43
	ds_read2_b32 v[86:87], v215 offset0:10 offset1:11
	ds_read2_b32 v[88:89], v215 offset0:16 offset1:17
	ds_read2_b32 v[136:137], v215 offset0:48 offset1:49
	ds_read2_b32 v[138:139], v215 offset0:50 offset1:51
	ds_read2_b32 v[90:91], v215 offset0:18 offset1:19
	ds_read2_b32 v[92:93], v215 offset0:24 offset1:25
	ds_read2_b32 v[94:95], v215 offset0:26 offset1:27
	ds_read2_b32 v[140:141], v215 offset0:56 offset1:57
	ds_read2_b32 v[142:143], v215 offset0:58 offset1:59
	s_waitcnt lgkmcnt(3)
	v_sub_f32_e32 v93, v93, v79
	v_sub_f32_e32 v92, v92, v78
	s_waitcnt lgkmcnt(2)
	v_sub_f32_e32 v95, v95, v77
	v_sub_f32_e32 v94, v94, v76
	v_sub_f32_e32 v89, v89, v75
	v_sub_f32_e32 v88, v88, v72
	v_sub_f32_e32 v91, v91, v73
	v_sub_f32_e32 v90, v90, v74
	v_sub_f32_e32 v85, v85, v69
	v_sub_f32_e32 v84, v84, v68
	v_sub_f32_e32 v87, v87, v71
	v_sub_f32_e32 v86, v86, v70
	v_sub_f32_e32 v81, v81, v1
	v_sub_f32_e32 v80, v80, v0
	v_sub_f32_e32 v83, v83, v67
	v_sub_f32_e32 v82, v82, v66
	s_waitcnt lgkmcnt(1)
	v_sub_f32_e32 v141, v141, v79
	v_sub_f32_e32 v140, v140, v78
	s_waitcnt lgkmcnt(0)
	v_sub_f32_e32 v143, v143, v77
	v_sub_f32_e32 v142, v142, v76
	v_sub_f32_e32 v137, v137, v75
	v_sub_f32_e32 v136, v136, v72
	v_sub_f32_e32 v139, v139, v73
	v_sub_f32_e32 v138, v138, v74
	v_sub_f32_e32 v133, v133, v69
	v_sub_f32_e32 v132, v132, v68
	v_sub_f32_e32 v135, v135, v71
	v_sub_f32_e32 v134, v134, v70
	v_sub_f32_e32 v129, v129, v1
	v_sub_f32_e32 v128, v128, v0
	v_sub_f32_e32 v131, v131, v67
	v_sub_f32_e32 v130, v130, v66
	v_pk_fma_f32 v[82:83], v[114:115], s[6:7], v[82:83] op_sel_hi:[1,0,1]
	v_pk_fma_f32 v[80:81], v[112:113], s[6:7], v[80:81] op_sel_hi:[1,0,1]
	v_pk_fma_f32 v[86:87], v[118:119], s[6:7], v[86:87] op_sel_hi:[1,0,1]
	v_pk_fma_f32 v[84:85], v[116:117], s[6:7], v[84:85] op_sel_hi:[1,0,1]
	v_pk_fma_f32 v[90:91], v[122:123], s[6:7], v[90:91] op_sel_hi:[1,0,1]
	v_pk_fma_f32 v[88:89], v[120:121], s[6:7], v[88:89] op_sel_hi:[1,0,1]
	v_pk_fma_f32 v[94:95], v[126:127], s[6:7], v[94:95] op_sel_hi:[1,0,1]
	v_pk_fma_f32 v[92:93], v[124:125], s[6:7], v[92:93] op_sel_hi:[1,0,1]
	v_pk_fma_f32 v[130:131], v[98:99], s[6:7], v[130:131] op_sel_hi:[1,0,1]
	v_pk_fma_f32 v[128:129], v[96:97], s[6:7], v[128:129] op_sel_hi:[1,0,1]
	v_pk_fma_f32 v[134:135], v[102:103], s[6:7], v[134:135] op_sel_hi:[1,0,1]
	v_pk_fma_f32 v[132:133], v[100:101], s[6:7], v[132:133] op_sel_hi:[1,0,1]
	v_pk_fma_f32 v[138:139], v[106:107], s[6:7], v[138:139] op_sel_hi:[1,0,1]
	v_pk_fma_f32 v[136:137], v[104:105], s[6:7], v[136:137] op_sel_hi:[1,0,1]
	v_pk_fma_f32 v[142:143], v[110:111], s[6:7], v[142:143] op_sel_hi:[1,0,1]
	v_pk_fma_f32 v[140:141], v[108:109], s[6:7], v[140:141] op_sel_hi:[1,0,1]
	s_mov_b64 s[0:1], 0

; #define SBAR() __builtin_amdgcn_sched_barrier(0)
; __device__ __forceinline__ void partialSM(f32x16& p0, f32x16& p1, float& m_reg, float& mn, float& alpha, int kt0, int qpos, int qw, int hi, const float* tb2, float cL, float cR) {
;     ...
; #pragma unroll
;   for (int r = 0; r < 16; ++r) p0[r] = __builtin_amdgcn_exp2f(p0[r]);
; }
; __device__ __forceinline__ void finishSM(f32x16& p0, f32x16& p1, float alpha, float& l_reg, bf16x8& pa0, bf16x8& pa1, bf16x8& pa2, bf16x8& pa3) {
; #pragma unroll
;   for (int r = 0; r < 16; ++r) p1[r] = __builtin_amdgcn_exp2f(p1[r]);
;   float ps = 0;
; #pragma unroll
;   for (int r = 0; r < 16; ++r) ps += p0[r];
; #pragma unroll
;   for (int r = 0; r < 16; ++r) ps += p1[r];
;   { auto rr = __builtin_amdgcn_permlane32_swap(__float_as_uint(ps), __float_as_uint(ps), false, false);
;     ps = __uint_as_float(rr[0]) + __uint_as_float(rr[1]); }
;   l_reg = l_reg * alpha + ps;
;     ...
;   PK4(p0, 0, pa0); PK4(p0, 8, pa1); PK4(p1, 0, pa2); PK4(p1, 8, pa3);
;     ...
; }
; __device__ __forceinline__ void qkt(f32x16& p0, f32x16& p1, const char* Ks, const bf16x8* qr, int r32, int hi) {
;   bf16x8 ka[4], kb[4];
; #pragma unroll
;   for (int d0 = 0; d0 < 4; ++d0) { const int cb = (d0 * 16 + hi * 8) * 2;
;     ka[d0] = *reinterpret_cast<const bf16x8*>(Ks + KSWZ64(r32, cb)); kb[d0] = *reinterpret_cast<const bf16x8*>(Ks + KSWZ64(32 + r32, cb)); }
;   asm volatile("s_waitcnt lgkmcnt(0)" ::: "memory"); SBAR();
;   p0 = f32x16{}; p1 = f32x16{};
; #pragma unroll
;   for (int d0 = 0; d0 < 4; ++d0) {
;     p0 = __builtin_amdgcn_mfma_f32_32x32x16_bf16(ka[d0], qr[d0], p0, 0, 0, 0);
;     p1 = __builtin_amdgcn_mfma_f32_32x32x16_bf16(kb[d0], qr[d0], p1, 0, 0, 0); }
.LBB0_357:
	s_add_i32 s0, s4, 0
	v_exp_f32_e32 v230, v80
	v_add_u32_e32 v80, s0, v181
	s_barrier
	s_waitcnt vmcnt(2)
	ds_write_b128 v80, v[168:171]
	s_waitcnt vmcnt(1)
	ds_write_b128 v80, v[172:175] offset:8192
	v_lshl_add_u32 v80, s61, 13, v200
	v_exp_f32_e32 v231, v81
	v_exp_f32_e32 v244, v82
	v_exp_f32_e32 v245, v83
	v_exp_f32_e32 v246, v84
	v_exp_f32_e32 v247, v85
	v_exp_f32_e32 v248, v86
	v_exp_f32_e32 v249, v87
	v_exp_f32_e32 v250, v88
	v_exp_f32_e32 v251, v89
	v_exp_f32_e32 v235, v90
	v_exp_f32_e32 v237, v91
	v_exp_f32_e32 v238, v92
	v_exp_f32_e32 v234, v93
	v_exp_f32_e32 v196, v94
	v_exp_f32_e32 v197, v95
	s_waitcnt vmcnt(0)
	ds_write_b128 v80, v[176:179] offset:49152
	s_lshl_b32 s0, s63, 13
	s_add_i32 s0, s0, 0
	v_add_u32_e32 v84, s0, v202
	v_add_u32_e32 v92, s0, v205
	v_add_u32_e32 v96, s0, v207
	ds_read_b128 v[80:83], v84 offset:49152
	ds_read_b128 v[84:87], v84 offset:53248
	ds_read_b128 v[88:91], v92 offset:49152
	ds_read_b128 v[92:95], v92 offset:53248
	ds_read_b128 v[218:221], v96 offset:49152
	ds_read_b128 v[222:225], v96 offset:53248
	v_add_u32_e32 v96, s0, v208
	ds_read_b128 v[226:229], v96 offset:49152
	ds_read_b128 v[240:243], v96 offset:53248
	s_waitcnt lgkmcnt(0)
	s_waitcnt lgkmcnt(7)
	v_mfma_f32_32x32x16_bf16 v[112:127], v[80:83], v[164:167], 0
	v_add_f32_e32 v80, v231, v230
	v_add_f32_e32 v80, v244, v80
	v_add_f32_e32 v80, v245, v80
	v_add_f32_e32 v80, v246, v80
	v_add_f32_e32 v80, v247, v80
	v_add_f32_e32 v80, v248, v80
	s_waitcnt lgkmcnt(6)
	v_mfma_f32_32x32x16_bf16 v[96:111], v[84:87], v[164:167], 0
	v_add_f32_e32 v80, v249, v80
	v_add_f32_e32 v80, v250, v80
	v_add_f32_e32 v80, v251, v80
	v_add_f32_e32 v80, v235, v80
	v_add_f32_e32 v80, v237, v80
	v_exp_f32_e32 v128, v128
	v_add_f32_e32 v80, v238, v80
	s_waitcnt lgkmcnt(5)
	v_mfma_f32_32x32x16_bf16 v[112:127], v[88:91], v[160:163], v[112:127]
	v_exp_f32_e32 v129, v129
	v_add_f32_e32 v80, v234, v80
	v_exp_f32_e32 v130, v130
	v_add_f32_e32 v80, v196, v80
	v_exp_f32_e32 v131, v131
	v_add_f32_e32 v80, v197, v80
	v_exp_f32_e32 v132, v132
	s_waitcnt lgkmcnt(4)
	v_mfma_f32_32x32x16_bf16 v[96:111], v[92:95], v[160:163], v[96:111]
	v_add_f32_e32 v80, v128, v80
	v_exp_f32_e32 v133, v133
	v_add_f32_e32 v80, v129, v80
	v_exp_f32_e32 v134, v134
	v_add_f32_e32 v80, v130, v80
	v_exp_f32_e32 v135, v135
	v_add_f32_e32 v80, v131, v80
	s_waitcnt lgkmcnt(3)
	v_mfma_f32_32x32x16_bf16 v[112:127], v[218:221], v[156:159], v[112:127]
	v_exp_f32_e32 v136, v136
	v_add_f32_e32 v80, v132, v80
	v_exp_f32_e32 v137, v137
	v_add_f32_e32 v80, v133, v80
	v_exp_f32_e32 v138, v138
	v_add_f32_e32 v80, v134, v80
	v_exp_f32_e32 v139, v139
	s_waitcnt lgkmcnt(2)
	v_mfma_f32_32x32x16_bf16 v[96:111], v[222:225], v[156:159], v[96:111]
	v_add_f32_e32 v80, v135, v80
	v_exp_f32_e32 v140, v140
	v_add_f32_e32 v80, v136, v80
	v_exp_f32_e32 v141, v141
	v_add_f32_e32 v80, v137, v80
	v_exp_f32_e32 v142, v142
	v_add_f32_e32 v80, v138, v80
	s_waitcnt lgkmcnt(1)
	v_mfma_f32_32x32x16_bf16 v[112:127], v[226:229], v[152:155], v[112:127]
	v_exp_f32_e32 v143, v143
	v_add_f32_e32 v80, v139, v80
	v_add_f32_e32 v80, v140, v80
	v_add_f32_e32 v80, v141, v80
	v_add_f32_e32 v80, v142, v80
	v_add_f32_e32 v218, v143, v80
	v_mov_b32_e32 v219, v218
	s_waitcnt lgkmcnt(0)
	v_mfma_f32_32x32x16_bf16 v[96:111], v[240:243], v[152:155], v[96:111]
	v_cvt_pk_bf16_f32 v80, v230, v231
	v_cvt_pk_bf16_f32 v81, v244, v245
	v_cvt_pk_bf16_f32 v82, v246, v247
	v_cvt_pk_bf16_f32 v83, v248, v249
	v_cvt_pk_bf16_f32 v84, v250, v251
	v_cvt_pk_bf16_f32 v85, v235, v237
	v_cvt_pk_bf16_f32 v86, v238, v234
	v_cvt_pk_bf16_f32 v87, v196, v197
	v_cvt_pk_bf16_f32 v88, v128, v129
	v_cvt_pk_bf16_f32 v89, v130, v131
	v_cvt_pk_bf16_f32 v90, v132, v133
	v_cvt_pk_bf16_f32 v91, v134, v135
	v_cvt_pk_bf16_f32 v92, v136, v137
	v_cvt_pk_bf16_f32 v93, v138, v139
	v_cvt_pk_bf16_f32 v94, v140, v141
	v_cvt_pk_bf16_f32 v95, v142, v143
	v_permlane32_swap_b32_e32 v218, v219
	v_permlane32_swap_b32_e32 v80, v82
	v_permlane32_swap_b32_e32 v81, v83
	v_permlane32_swap_b32_e32 v84, v86
	v_permlane32_swap_b32_e32 v85, v87
	v_permlane32_swap_b32_e32 v88, v90
	v_permlane32_swap_b32_e32 v89, v91
	v_permlane32_swap_b32_e32 v92, v94
	v_permlane32_swap_b32_e32 v93, v95
	s_cmp_lt_u32 s64, 61
	s_cselect_b64 s[0:1], -1, 0
	s_cmp_gt_u32 s64, 60
	s_cbranch_scc1 .LBB0_359
	s_add_u32 s74, s70, 0x18e00000
	s_addc_u32 s75, s71, 0
	global_load_dwordx4 v[168:171], v182, s[74:75] offset:2048
	s_add_u32 s74, s70, 0x18e40000
	s_addc_u32 s75, s71, 0
	global_load_dwordx4 v[172:175], v182, s[74:75] offset:2048
	s_add_u32 s74, s72, 0x18e00000
	s_addc_u32 s75, s73, 0
	global_load_dwordx4 v[176:179], v184, s[74:75] offset:1024

.LBB0_363:
	s_andn2_b64 vcc, exec, s[0:1]
	s_mov_b64 s[0:1], -1
	s_barrier
	s_cbranch_vccnz .LBB0_365
	s_add_i32 s0, s4, 0
	v_add_u32_e32 v98, s0, v181
	s_add_u32 s70, s70, s16
	s_addc_u32 s71, s71, s17
	s_add_u32 s72, s72, s16
	s_addc_u32 s73, s73, s17
	s_addk_i32 s62, 0x80
	v_add_u32_e32 v215, 0x200, v215
	s_add_i32 s64, s64, 2
	s_mov_b64 s[0:1], 0
	v_add_u32_e32 v96, s36, v192
	s_waitcnt vmcnt(2)
	ds_write_b128 v98, v[168:171]
	s_waitcnt vmcnt(1)
	ds_write_b128 v98, v[172:175] offset:8192
	s_waitcnt vmcnt(0)
	ds_write_b128 v96, v[176:179] offset:49152

; __device__ __forceinline__ void finishSM(f32x16& p0, f32x16& p1, float alpha, float& l_reg, bf16x8& pa0, bf16x8& pa1, bf16x8& pa2, bf16x8& pa3) {
; #pragma unroll
;   for (int r = 0; r < 16; ++r) p1[r] = __builtin_amdgcn_exp2f(p1[r]);
;   float ps = 0;
; #pragma unroll
;   for (int r = 0; r < 16; ++r) ps += p0[r];
; #pragma unroll
;   for (int r = 0; r < 16; ++r) ps += p1[r];
;   { auto rr = __builtin_amdgcn_permlane32_swap(__float_as_uint(ps), __float_as_uint(ps), false, false);
;     ps = __uint_as_float(rr[0]) + __uint_as_float(rr[1]); }
;   l_reg = l_reg * alpha + ps;
;     ...
;   PK4(p0, 0, pa0); PK4(p0, 8, pa1); PK4(p1, 0, pa2); PK4(p1, 8, pa3);
;     ...
; }
; __device__ __forceinline__ void qkt(f32x16& p0, f32x16& p1, const char* Ks, const bf16x8* qr, int r32, int hi) {
;   bf16x8 ka[4], kb[4];
; #pragma unroll
;   for (int d0 = 0; d0 < 4; ++d0) { const int cb = (d0 * 16 + hi * 8) * 2;
;     ka[d0] = *reinterpret_cast<const bf16x8*>(Ks + KSWZ64(r32, cb)); kb[d0] = *reinterpret_cast<const bf16x8*>(Ks + KSWZ64(32 + r32, cb)); }
;   asm volatile("s_waitcnt lgkmcnt(0)" ::: "memory"); SBAR();
;   p0 = f32x16{}; p1 = f32x16{};
; #pragma unroll
;   for (int d0 = 0; d0 < 4; ++d0) {
;     p0 = __builtin_amdgcn_mfma_f32_32x32x16_bf16(ka[d0], qr[d0], p0, 0, 0, 0);
;     p1 = __builtin_amdgcn_mfma_f32_32x32x16_bf16(kb[d0], qr[d0], p1, 0, 0, 0); }
; }
; __device__ __forceinline__ int v_st(int k, int c) { const int kk = (k & ~0xC) | ((k & 4) << 1) | ((k & 8) >> 1); return ((kk >> 3) * 4 + (c >> 5)) * 512 + ((kk & 7) * 32 + (c & 31)) * 2; }
; __device__ __forceinline__ int v_rd_base(int lane) { return ((lane & 3) << 3) | (((lane >> 2) & 3) << 6) | (((lane >> 4) & 1) << 5) | (((lane >> 5) & 1) << 8); }
; template <int OFF> __device__ __forceinline__ s16x4 tr_read(int vb) {
;   s16x4 r; asm volatile("ds_read_b64_tr_b16 %0, %1 offset:%2" : "=&v"(r) : "v"(vb), "i"(OFF) : "memory"); return r;
; }
; template <int D0> __device__ __forceinline__ void pv_one(f32x16& od, int vb, bf16x8 pa0, bf16x8 pa1, bf16x8 pa2, bf16x8 pa3) {
;   const s16x4 l0 = tr_read<v_rd_off(D0, 0, 0)>(vb), h0 = tr_read<v_rd_off(D0, 0, 1)>(vb), l1 = tr_read<v_rd_off(D0, 1, 0)>(vb), h1 = tr_read<v_rd_off(D0, 1, 1)>(vb);
;   const s16x4 l2 = tr_read<v_rd_off(D0, 2, 0)>(vb), h2 = tr_read<v_rd_off(D0, 2, 1)>(vb), l3 = tr_read<v_rd_off(D0, 3, 0)>(vb), h3 = tr_read<v_rd_off(D0, 3, 1)>(vb);
.LBB0_367:
	ds_read_b128 v[96:99], v201 offset:49152
	ds_read_b128 v[100:103], v201 offset:53248
	ds_read_b128 v[136:139], v203 offset:49152
	ds_read_b128 v[140:143], v203 offset:53248
	s_waitcnt vmcnt(0)
	ds_read_b128 v[176:179], v204 offset:49152
	ds_read_b128 v[182:185], v204 offset:53248
	ds_read_b128 v[186:189], v206 offset:49152
	ds_read_b128 v[200:203], v206 offset:53248
	s_waitcnt lgkmcnt(0)
	v_exp_f32_e32 v181, v80
	v_add_f32_e32 v80, v175, v173
	s_waitcnt lgkmcnt(7)
	v_mfma_f32_32x32x16_bf16 v[112:127], v[96:99], v[164:167], 0
	v_add_f32_e32 v80, v171, v80
	v_add_f32_e32 v80, v174, v80
	v_add_f32_e32 v80, v169, v80
	v_add_f32_e32 v80, v172, v80
	v_add_f32_e32 v80, v168, v80
	v_add_f32_e32 v80, v170, v80
	v_add_f32_e32 v80, v133, v80
	s_waitcnt lgkmcnt(6)
	v_mfma_f32_32x32x16_bf16 v[96:111], v[100:103], v[164:167], 0
	v_add_f32_e32 v80, v135, v80
	v_add_f32_e32 v80, v131, v80
	v_add_f32_e32 v80, v134, v80
	v_add_f32_e32 v80, v129, v80
	v_exp_f32_e32 v191, v81
	v_add_f32_e32 v80, v132, v80
	v_exp_f32_e32 v192, v82
	s_waitcnt lgkmcnt(5)
	v_mfma_f32_32x32x16_bf16 v[112:127], v[136:139], v[160:163], v[112:127]
	v_add_f32_e32 v80, v128, v80
	v_exp_f32_e32 v204, v83
	v_add_f32_e32 v80, v130, v80
	v_exp_f32_e32 v205, v84
	v_add_f32_e32 v80, v181, v80
	v_exp_f32_e32 v206, v85
	v_add_f32_e32 v80, v191, v80
	s_waitcnt lgkmcnt(4)
	v_mfma_f32_32x32x16_bf16 v[96:111], v[140:143], v[160:163], v[96:111]
	v_exp_f32_e32 v207, v86
	v_add_f32_e32 v80, v192, v80
	v_exp_f32_e32 v208, v87
	v_add_f32_e32 v80, v204, v80
	v_exp_f32_e32 v215, v88
	v_add_f32_e32 v80, v205, v80
	v_exp_f32_e32 v216, v89
	s_waitcnt lgkmcnt(3)
	v_mfma_f32_32x32x16_bf16 v[112:127], v[176:179], v[156:159], v[112:127]
	v_add_f32_e32 v80, v206, v80
	v_exp_f32_e32 v217, v90
	v_add_f32_e32 v80, v207, v80
	v_exp_f32_e32 v218, v91
	v_add_f32_e32 v80, v208, v80
	v_exp_f32_e32 v219, v92
	v_add_f32_e32 v80, v215, v80
	s_waitcnt lgkmcnt(2)
	v_mfma_f32_32x32x16_bf16 v[96:111], v[182:185], v[156:159], v[96:111]
	v_exp_f32_e32 v164, v93
	v_add_f32_e32 v80, v216, v80
	v_exp_f32_e32 v165, v94
	v_add_f32_e32 v80, v217, v80
	v_exp_f32_e32 v95, v95
	v_add_f32_e32 v80, v218, v80
	v_add_f32_e32 v80, v219, v80
	s_waitcnt lgkmcnt(1)
	v_mfma_f32_32x32x16_bf16 v[112:127], v[186:189], v[152:155], v[112:127]
	v_add_f32_e32 v80, v164, v80
	v_add_f32_e32 v80, v165, v80
	v_add_f32_e32 v156, v95, v80
	v_mov_b32_e32 v157, v156
	v_cvt_pk_bf16_f32 v80, v173, v175
	v_cvt_pk_bf16_f32 v81, v171, v174
	v_cvt_pk_bf16_f32 v82, v169, v172
	s_waitcnt lgkmcnt(0)
	v_mfma_f32_32x32x16_bf16 v[96:111], v[200:203], v[152:155], v[96:111]
	v_cvt_pk_bf16_f32 v83, v168, v170
	v_cvt_pk_bf16_f32 v84, v133, v135
	v_cvt_pk_bf16_f32 v85, v131, v134
	v_cvt_pk_bf16_f32 v86, v129, v132
	v_cvt_pk_bf16_f32 v87, v128, v130
	v_cvt_pk_bf16_f32 v88, v181, v191
	v_cvt_pk_bf16_f32 v89, v192, v204
	v_cvt_pk_bf16_f32 v90, v205, v206
	v_cvt_pk_bf16_f32 v91, v207, v208
	v_cvt_pk_bf16_f32 v92, v215, v216
	v_cvt_pk_bf16_f32 v93, v217, v218
	v_cvt_pk_bf16_f32 v94, v219, v164
	v_cvt_pk_bf16_f32 v95, v165, v95
	v_permlane32_swap_b32_e32 v156, v157
	v_permlane32_swap_b32_e32 v80, v82
	v_permlane32_swap_b32_e32 v81, v83
	v_permlane32_swap_b32_e32 v84, v86
	v_permlane32_swap_b32_e32 v85, v87
	v_permlane32_swap_b32_e32 v88, v90
	v_permlane32_swap_b32_e32 v89, v91
	v_permlane32_swap_b32_e32 v92, v94
	v_permlane32_swap_b32_e32 v93, v95
	s_cmp_lg_u32 0, -1
	s_cselect_b32 s0, 0, 0
	s_add_i32 s0, s0, 0x8000
	v_add_u32_e32 v152, s0, v209
	ds_read_b64_tr_b16 v[128:129], v152 offset:0
	ds_read_b64_tr_b16 v[130:131], v152 offset:0x800
	ds_read_b64_tr_b16 v[132:133], v152 offset:0x1000
	ds_read_b64_tr_b16 v[134:135], v152 offset:0x1800
	ds_read_b64_tr_b16 v[136:137], v152 offset:0x2000
	ds_read_b64_tr_b16 v[138:139], v152 offset:0x2800
	ds_read_b64_tr_b16 v[140:141], v152 offset:0x3000
	ds_read_b64_tr_b16 v[142:143], v152 offset:0x3800
	s_waitcnt lgkmcnt(0)
	s_nop 0
	v_mfma_f32_32x32x16_bf16 v[2:17], v[80:83], v[128:131], v[2:17]
	ds_read_b64_tr_b16 v[128:129], v152 offset:0x200
	ds_read_b64_tr_b16 v[130:131], v152 offset:0xa00
	v_mfma_f32_32x32x16_bf16 v[2:17], v[84:87], v[132:135], v[2:17]
	ds_read_b64_tr_b16 v[132:133], v152 offset:0x1200
	ds_read_b64_tr_b16 v[134:135], v152 offset:0x1a00
	v_mfma_f32_32x32x16_bf16 v[2:17], v[88:91], v[136:139], v[2:17]
	ds_read_b64_tr_b16 v[136:137], v152 offset:0x2200
	ds_read_b64_tr_b16 v[138:139], v152 offset:0x2a00
	v_mfma_f32_32x32x16_bf16 v[2:17], v[92:95], v[140:143], v[2:17]
	ds_read_b64_tr_b16 v[140:141], v152 offset:0x3200
	ds_read_b64_tr_b16 v[142:143], v152 offset:0x3a00
	s_waitcnt lgkmcnt(0)
	v_mfma_f32_32x32x16_bf16 v[18:33], v[80:83], v[128:131], v[18:33]
	ds_read_b64_tr_b16 v[128:129], v152 offset:0x400
	ds_read_b64_tr_b16 v[130:131], v152 offset:0xc00
	v_mfma_f32_32x32x16_bf16 v[18:33], v[84:87], v[132:135], v[18:33]
	ds_read_b64_tr_b16 v[132:133], v152 offset:0x1400
	ds_read_b64_tr_b16 v[134:135], v152 offset:0x1c00
	v_mfma_f32_32x32x16_bf16 v[18:33], v[88:91], v[136:139], v[18:33]
	ds_read_b64_tr_b16 v[136:137], v152 offset:0x2400
	ds_read_b64_tr_b16 v[138:139], v152 offset:0x2c00
	v_mfma_f32_32x32x16_bf16 v[18:33], v[92:95], v[140:143], v[18:33]
	ds_read_b64_tr_b16 v[140:141], v152 offset:0x3400
	ds_read_b64_tr_b16 v[142:143], v152 offset:0x3c00
	s_waitcnt lgkmcnt(0)
	v_mfma_f32_32x32x16_bf16 v[34:49], v[80:83], v[128:131], v[34:49]
	ds_read_b64_tr_b16 v[128:129], v152 offset:0x600
	ds_read_b64_tr_b16 v[130:131], v152 offset:0xe00
	v_mfma_f32_32x32x16_bf16 v[34:49], v[84:87], v[132:135], v[34:49]
	ds_read_b64_tr_b16 v[132:133], v152 offset:0x1600
	ds_read_b64_tr_b16 v[134:135], v152 offset:0x1e00
	v_mfma_f32_32x32x16_bf16 v[34:49], v[88:91], v[136:139], v[34:49]
	ds_read_b64_tr_b16 v[136:137], v152 offset:0x2600
	ds_read_b64_tr_b16 v[138:139], v152 offset:0x2e00
	v_mfma_f32_32x32x16_bf16 v[34:49], v[92:95], v[140:143], v[34:49]
	ds_read_b64_tr_b16 v[140:141], v152 offset:0x3600
	ds_read_b64_tr_b16 v[142:143], v152 offset:0x3e00
	s_waitcnt lgkmcnt(0)
	v_mfma_f32_32x32x16_bf16 v[50:65], v[80:83], v[128:131], v[50:65]
	s_add_i32 s4, s60, 0xffffefa6
	s_mov_b64 s[0:1], -1
	s_cmp_gt_u32 s4, 0xfffffeec
	v_mfma_f32_32x32x16_bf16 v[50:65], v[84:87], v[132:135], v[50:65]
	v_mfma_f32_32x32x16_bf16 v[50:65], v[88:91], v[136:139], v[50:65]
	v_mfma_f32_32x32x16_bf16 v[50:65], v[92:95], v[140:143], v[50:65]
	s_cbranch_scc0 .Lfastp_2
; __device__ __forceinline__ void partialSM(f32x16& p0, f32x16& p1, float& m_reg, float& mn, float& alpha, int kt0, int qpos, int qw, int hi, const float* tb2, float cL, float cR) {
;     ...
;     const float* tp = tb2 + (kt0 - qpos + 192 + 4 * hi);
; #pragma unroll
;     for (int r4 = 0; r4 < 4; ++r4) {
;       float ta[4], tb[4];
; #pragma unroll
;       for (int i = 0; i < 4; ++i) { ta[i] = tp[8 * r4 + i] - m_reg; tb[i] = tp[32 + 8 * r4 + i] - m_reg; }
; #pragma unroll
;       for (int i = 0; i < 4; ++i) { p0[4 * r4 + i] = fmaf(p0[4 * r4 + i], C1, ta[i]); p1[4 * r4 + i] = fmaf(p1[4 * r4 + i], C1, tb[i]); }
	v_sub_u32_e32 v80, 0xfc0, v190
	s_add_i32 s0, 0, 0x12b00
	v_lshlrev_b32_e32 v80, 2, v80
	v_add3_u32 v140, s0, v180, v80
	ds_read2_b32 v[80:81], v140 offset1:1
	ds_read2_b32 v[128:129], v140 offset0:32 offset1:33
	ds_read2_b32 v[130:131], v140 offset0:34 offset1:35
	ds_read2_b32 v[82:83], v140 offset0:2 offset1:3
	ds_read2_b32 v[84:85], v140 offset0:8 offset1:9
	ds_read2_b32 v[132:133], v140 offset0:40 offset1:41
	ds_read2_b32 v[134:135], v140 offset0:42 offset1:43
	ds_read2_b32 v[86:87], v140 offset0:10 offset1:11
	ds_read2_b32 v[88:89], v140 offset0:16 offset1:17
	ds_read2_b32 v[136:137], v140 offset0:48 offset1:49
	ds_read2_b32 v[138:139], v140 offset0:50 offset1:51
	ds_read2_b32 v[90:91], v140 offset0:18 offset1:19
	ds_read2_b32 v[92:93], v140 offset0:24 offset1:25
	ds_read2_b32 v[94:95], v140 offset0:56 offset1:57
	s_waitcnt lgkmcnt(5)
	v_sub_f32_e32 v89, v89, v75
	s_waitcnt lgkmcnt(4)
	v_sub_f32_e32 v137, v137, v75
	v_sub_f32_e32 v88, v88, v72
	s_waitcnt lgkmcnt(1)
	v_sub_f32_e32 v93, v93, v79
	s_waitcnt lgkmcnt(0)
	v_sub_f32_e32 v79, v95, v79
	v_sub_f32_e32 v92, v92, v78
	v_sub_f32_e32 v78, v94, v78
	ds_read2_b32 v[94:95], v140 offset0:26 offset1:27
	ds_read2_b32 v[140:141], v140 offset0:58 offset1:59
	v_sub_f32_e32 v91, v91, v73
	v_sub_f32_e32 v90, v90, v74
	s_waitcnt lgkmcnt(1)
	v_sub_f32_e32 v95, v95, v77
	s_waitcnt lgkmcnt(0)
	v_sub_f32_e32 v77, v141, v77
	v_sub_f32_e32 v94, v94, v76
	v_sub_f32_e32 v76, v140, v76
	v_sub_f32_e32 v85, v85, v69
	v_sub_f32_e32 v84, v84, v68
	v_sub_f32_e32 v87, v87, v71
	v_sub_f32_e32 v86, v86, v70
	v_sub_f32_e32 v81, v81, v1
	v_sub_f32_e32 v80, v80, v0
	v_sub_f32_e32 v83, v83, v67
	v_sub_f32_e32 v82, v82, v66
	v_sub_f32_e32 v136, v136, v72
	v_sub_f32_e32 v73, v139, v73
	v_sub_f32_e32 v72, v138, v74
	v_sub_f32_e32 v69, v133, v69
	v_sub_f32_e32 v68, v132, v68
	v_sub_f32_e32 v71, v135, v71
	v_sub_f32_e32 v70, v134, v70
	v_sub_f32_e32 v75, v129, v1
	v_sub_f32_e32 v74, v128, v0
	v_sub_f32_e32 v67, v131, v67
	v_sub_f32_e32 v66, v130, v66
	v_pk_fma_f32 v[82:83], v[114:115], s[6:7], v[82:83] op_sel_hi:[1,0,1]
	v_pk_fma_f32 v[80:81], v[112:113], s[6:7], v[80:81] op_sel_hi:[1,0,1]
	v_pk_fma_f32 v[86:87], v[118:119], s[6:7], v[86:87] op_sel_hi:[1,0,1]
	v_pk_fma_f32 v[84:85], v[116:117], s[6:7], v[84:85] op_sel_hi:[1,0,1]
	v_pk_fma_f32 v[90:91], v[122:123], s[6:7], v[90:91] op_sel_hi:[1,0,1]
	v_pk_fma_f32 v[88:89], v[120:121], s[6:7], v[88:89] op_sel_hi:[1,0,1]
	v_pk_fma_f32 v[94:95], v[126:127], s[6:7], v[94:95] op_sel_hi:[1,0,1]
	v_pk_fma_f32 v[92:93], v[124:125], s[6:7], v[92:93] op_sel_hi:[1,0,1]
	v_pk_fma_f32 v[130:131], v[98:99], s[6:7], v[66:67] op_sel_hi:[1,0,1]
	v_pk_fma_f32 v[128:129], v[96:97], s[6:7], v[74:75] op_sel_hi:[1,0,1]
	v_pk_fma_f32 v[134:135], v[102:103], s[6:7], v[70:71] op_sel_hi:[1,0,1]
	v_pk_fma_f32 v[132:133], v[100:101], s[6:7], v[68:69] op_sel_hi:[1,0,1]
	v_pk_fma_f32 v[138:139], v[106:107], s[6:7], v[72:73] op_sel_hi:[1,0,1]
	v_pk_fma_f32 v[136:137], v[104:105], s[6:7], v[136:137] op_sel_hi:[1,0,1]
	v_pk_fma_f32 v[142:143], v[110:111], s[6:7], v[76:77] op_sel_hi:[1,0,1]
	v_pk_fma_f32 v[140:141], v[108:109], s[6:7], v[78:79] op_sel_hi:[1,0,1]
	s_mov_b64 s[0:1], 0

; __device__ __forceinline__ void finishSM(f32x16& p0, f32x16& p1, float alpha, float& l_reg, bf16x8& pa0, bf16x8& pa1, bf16x8& pa2, bf16x8& pa3) {
; #pragma unroll
;   for (int r = 0; r < 16; ++r) p1[r] = __builtin_amdgcn_exp2f(p1[r]);
;   float ps = 0;
; #pragma unroll
;   for (int r = 0; r < 16; ++r) ps += p0[r];
; #pragma unroll
;   for (int r = 0; r < 16; ++r) ps += p1[r];
;   { auto rr = __builtin_amdgcn_permlane32_swap(__float_as_uint(ps), __float_as_uint(ps), false, false);
;     ps = __uint_as_float(rr[0]) + __uint_as_float(rr[1]); }
;   l_reg = l_reg * alpha + ps;
;     ...
;   PK4(p0, 0, pa0); PK4(p0, 8, pa1); PK4(p1, 0, pa2); PK4(p1, 8, pa3);
;     ...
; }
; __device__ __forceinline__ void qkt(f32x16& p0, f32x16& p1, const char* Ks, const bf16x8* qr, int r32, int hi) {
;   bf16x8 ka[4], kb[4];
; #pragma unroll
;   for (int d0 = 0; d0 < 4; ++d0) { const int cb = (d0 * 16 + hi * 8) * 2;
;     ka[d0] = *reinterpret_cast<const bf16x8*>(Ks + KSWZ64(r32, cb)); kb[d0] = *reinterpret_cast<const bf16x8*>(Ks + KSWZ64(32 + r32, cb)); }
;   asm volatile("s_waitcnt lgkmcnt(0)" ::: "memory"); SBAR();
;   p0 = f32x16{}; p1 = f32x16{};
; #pragma unroll
;   for (int d0 = 0; d0 < 4; ++d0) {
;     p0 = __builtin_amdgcn_mfma_f32_32x32x16_bf16(ka[d0], qr[d0], p0, 0, 0, 0);
;     p1 = __builtin_amdgcn_mfma_f32_32x32x16_bf16(kb[d0], qr[d0], p1, 0, 0, 0); }
; }
; __device__ __forceinline__ int v_st(int k, int c) { const int kk = (k & ~0xC) | ((k & 4) << 1) | ((k & 8) >> 1); return ((kk >> 3) * 4 + (c >> 5)) * 512 + ((kk & 7) * 32 + (c & 31)) * 2; }
; __device__ __forceinline__ int v_rd_base(int lane) { return ((lane & 3) << 3) | (((lane >> 2) & 3) << 6) | (((lane >> 4) & 1) << 5) | (((lane >> 5) & 1) << 8); }
; template <int OFF> __device__ __forceinline__ s16x4 tr_read(int vb) {
;   s16x4 r; asm volatile("ds_read_b64_tr_b16 %0, %1 offset:%2" : "=&v"(r) : "v"(vb), "i"(OFF) : "memory"); return r;
; }
; template <int D0> __device__ __forceinline__ void pv_one(f32x16& od, int vb, bf16x8 pa0, bf16x8 pa1, bf16x8 pa2, bf16x8 pa3) {
;   const s16x4 l0 = tr_read<v_rd_off(D0, 0, 0)>(vb), h0 = tr_read<v_rd_off(D0, 0, 1)>(vb), l1 = tr_read<v_rd_off(D0, 1, 0)>(vb), h1 = tr_read<v_rd_off(D0, 1, 1)>(vb);
;   const s16x4 l2 = tr_read<v_rd_off(D0, 2, 0)>(vb), h2 = tr_read<v_rd_off(D0, 2, 1)>(vb), l3 = tr_read<v_rd_off(D0, 3, 0)>(vb), h3 = tr_read<v_rd_off(D0, 3, 1)>(vb);
.LBB0_378:
	s_mov_b32 s51, s45
	s_mov_b32 s45, s0
	s_lshl_b32 s0, s51, 13
	s_add_i32 s36, s0, 0
	v_add_u32_e32 v100, s36, v203
	v_add_u32_e32 v104, s36, v206
	ds_read_b128 v[96:99], v100 offset:49152
	ds_read_b128 v[100:103], v100 offset:53248
	ds_read_b128 v[136:139], v104 offset:49152
	ds_read_b128 v[140:143], v104 offset:53248
	v_add_u32_e32 v104, s36, v208
	s_waitcnt vmcnt(0)
	ds_read_b128 v[176:179], v104 offset:49152
	ds_read_b128 v[186:189], v104 offset:53248
	v_add_u32_e32 v104, s36, v209
	ds_read_b128 v[218:221], v104 offset:49152
	ds_read_b128 v[222:225], v104 offset:53248
	s_waitcnt lgkmcnt(0)
	v_exp_f32_e32 v196, v80
	v_add_f32_e32 v80, v175, v173
	s_waitcnt lgkmcnt(7)
	v_mfma_f32_32x32x16_bf16 v[112:127], v[96:99], v[164:167], 0
	v_add_f32_e32 v80, v171, v80
	v_add_f32_e32 v80, v174, v80
	v_add_f32_e32 v80, v169, v80
	v_add_f32_e32 v80, v172, v80
	v_add_f32_e32 v80, v168, v80
	v_add_f32_e32 v80, v170, v80
	v_add_f32_e32 v80, v133, v80
	s_waitcnt lgkmcnt(6)
	v_mfma_f32_32x32x16_bf16 v[96:111], v[100:103], v[164:167], 0
	v_add_f32_e32 v80, v135, v80
	v_add_f32_e32 v80, v131, v80
	v_add_f32_e32 v80, v134, v80
	v_add_f32_e32 v80, v129, v80
	v_exp_f32_e32 v197, v81
	v_add_f32_e32 v80, v132, v80
	v_exp_f32_e32 v226, v82
	s_waitcnt lgkmcnt(5)
	v_mfma_f32_32x32x16_bf16 v[112:127], v[136:139], v[160:163], v[112:127]
	v_add_f32_e32 v80, v128, v80
	v_exp_f32_e32 v227, v83
	v_add_f32_e32 v80, v130, v80
	v_exp_f32_e32 v228, v84
	v_add_f32_e32 v80, v196, v80
	v_exp_f32_e32 v229, v85
	v_add_f32_e32 v80, v197, v80
	s_waitcnt lgkmcnt(4)
	v_mfma_f32_32x32x16_bf16 v[96:111], v[140:143], v[160:163], v[96:111]
	v_exp_f32_e32 v230, v86
	v_add_f32_e32 v80, v226, v80
	v_exp_f32_e32 v231, v87
	v_add_f32_e32 v80, v227, v80
	v_exp_f32_e32 v234, v88
	v_add_f32_e32 v80, v228, v80
	v_exp_f32_e32 v235, v89
	s_waitcnt lgkmcnt(3)
	v_mfma_f32_32x32x16_bf16 v[112:127], v[176:179], v[156:159], v[112:127]
	v_add_f32_e32 v80, v229, v80
	v_exp_f32_e32 v237, v90
	v_add_f32_e32 v80, v230, v80
	v_exp_f32_e32 v238, v91
	v_add_f32_e32 v80, v231, v80
	v_exp_f32_e32 v240, v92
	v_add_f32_e32 v80, v234, v80
	s_waitcnt lgkmcnt(2)
	v_mfma_f32_32x32x16_bf16 v[96:111], v[186:189], v[156:159], v[96:111]
	v_exp_f32_e32 v241, v93
	v_add_f32_e32 v80, v235, v80
	v_exp_f32_e32 v242, v94
	v_add_f32_e32 v80, v237, v80
	v_exp_f32_e32 v95, v95
	v_add_f32_e32 v80, v238, v80
	v_add_f32_e32 v80, v240, v80
	s_waitcnt lgkmcnt(1)
	v_mfma_f32_32x32x16_bf16 v[112:127], v[218:221], v[152:155], v[112:127]
	v_add_f32_e32 v80, v241, v80
	v_add_f32_e32 v80, v242, v80
	v_add_f32_e32 v217, v95, v80
	v_mov_b32_e32 v218, v217
	v_cvt_pk_bf16_f32 v80, v173, v175
	v_cvt_pk_bf16_f32 v81, v171, v174
	v_cvt_pk_bf16_f32 v82, v169, v172
	s_waitcnt lgkmcnt(0)
	v_mfma_f32_32x32x16_bf16 v[96:111], v[222:225], v[152:155], v[96:111]
	v_cvt_pk_bf16_f32 v83, v168, v170
	v_cvt_pk_bf16_f32 v84, v133, v135
	v_cvt_pk_bf16_f32 v85, v131, v134
	v_cvt_pk_bf16_f32 v86, v129, v132
	v_cvt_pk_bf16_f32 v87, v128, v130
	v_cvt_pk_bf16_f32 v88, v196, v197
	v_cvt_pk_bf16_f32 v89, v226, v227
	v_cvt_pk_bf16_f32 v90, v228, v229
	v_cvt_pk_bf16_f32 v91, v230, v231
	v_cvt_pk_bf16_f32 v92, v234, v235
	v_cvt_pk_bf16_f32 v93, v237, v238
	v_cvt_pk_bf16_f32 v94, v240, v241
	v_cvt_pk_bf16_f32 v95, v242, v95
	v_permlane32_swap_b32_e32 v217, v218
	v_permlane32_swap_b32_e32 v80, v82
	v_permlane32_swap_b32_e32 v81, v83
	v_permlane32_swap_b32_e32 v84, v86
	v_permlane32_swap_b32_e32 v85, v87
	v_permlane32_swap_b32_e32 v88, v90
	v_permlane32_swap_b32_e32 v89, v91
	v_permlane32_swap_b32_e32 v92, v94
	v_permlane32_swap_b32_e32 v93, v95
	s_mov_b32 s0, 0x18dc0000
	s_add_u32 s74, s70, s15
	s_addc_u32 s75, s71, 0
	global_load_dwordx4 v[168:171], v182, s[74:75] offset:2048
	s_add_u32 s74, s70, s0
	s_addc_u32 s75, s71, 0
	global_load_dwordx4 v[172:175], v182, s[74:75] offset:2048
	s_add_u32 s74, s72, s15
	s_addc_u32 s75, s73, 0
	global_load_dwordx4 v[176:179], v184, s[74:75] offset:1152
	s_lshl_b32 s4, s45, 14
	v_add_u32_e32 v196, s4, v147
	ds_read_b64_tr_b16 v[128:129], v196 offset:0
	ds_read_b64_tr_b16 v[130:131], v196 offset:0x800
	ds_read_b64_tr_b16 v[132:133], v196 offset:0x1000
	ds_read_b64_tr_b16 v[134:135], v196 offset:0x1800
	ds_read_b64_tr_b16 v[136:137], v196 offset:0x2000
	ds_read_b64_tr_b16 v[138:139], v196 offset:0x2800
	ds_read_b64_tr_b16 v[140:141], v196 offset:0x3000
	ds_read_b64_tr_b16 v[142:143], v196 offset:0x3800
	s_waitcnt lgkmcnt(0)
	s_nop 0
	v_mfma_f32_32x32x16_bf16 v[0:15], v[80:83], v[128:131], v[0:15]
	ds_read_b64_tr_b16 v[128:129], v196 offset:0x200
	ds_read_b64_tr_b16 v[130:131], v196 offset:0xa00
	v_mfma_f32_32x32x16_bf16 v[0:15], v[84:87], v[132:135], v[0:15]
	ds_read_b64_tr_b16 v[132:133], v196 offset:0x1200
	ds_read_b64_tr_b16 v[134:135], v196 offset:0x1a00
	v_mfma_f32_32x32x16_bf16 v[0:15], v[88:91], v[136:139], v[0:15]
	ds_read_b64_tr_b16 v[136:137], v196 offset:0x2200
	ds_read_b64_tr_b16 v[138:139], v196 offset:0x2a00
	v_mfma_f32_32x32x16_bf16 v[0:15], v[92:95], v[140:143], v[0:15]
	ds_read_b64_tr_b16 v[140:141], v196 offset:0x3200
	ds_read_b64_tr_b16 v[142:143], v196 offset:0x3a00
	s_waitcnt lgkmcnt(0)
	v_mfma_f32_32x32x16_bf16 v[16:31], v[80:83], v[128:131], v[16:31]
	ds_read_b64_tr_b16 v[128:129], v196 offset:0x400
	ds_read_b64_tr_b16 v[130:131], v196 offset:0xc00
	v_mfma_f32_32x32x16_bf16 v[16:31], v[84:87], v[132:135], v[16:31]
	ds_read_b64_tr_b16 v[132:133], v196 offset:0x1400
	ds_read_b64_tr_b16 v[134:135], v196 offset:0x1c00
	v_mfma_f32_32x32x16_bf16 v[16:31], v[88:91], v[136:139], v[16:31]
	ds_read_b64_tr_b16 v[136:137], v196 offset:0x2400
	ds_read_b64_tr_b16 v[138:139], v196 offset:0x2c00
	v_mfma_f32_32x32x16_bf16 v[16:31], v[92:95], v[140:143], v[16:31]
	ds_read_b64_tr_b16 v[140:141], v196 offset:0x3400
	ds_read_b64_tr_b16 v[142:143], v196 offset:0x3c00
	s_waitcnt lgkmcnt(0)
	v_mfma_f32_32x32x16_bf16 v[32:47], v[80:83], v[128:131], v[32:47]
	ds_read_b64_tr_b16 v[128:129], v196 offset:0x600
	ds_read_b64_tr_b16 v[130:131], v196 offset:0xe00
	v_mfma_f32_32x32x16_bf16 v[32:47], v[84:87], v[132:135], v[32:47]
	ds_read_b64_tr_b16 v[132:133], v196 offset:0x1600
	ds_read_b64_tr_b16 v[134:135], v196 offset:0x1e00
	v_mfma_f32_32x32x16_bf16 v[32:47], v[88:91], v[136:139], v[32:47]
	ds_read_b64_tr_b16 v[136:137], v196 offset:0x2600
	ds_read_b64_tr_b16 v[138:139], v196 offset:0x2e00
	v_mfma_f32_32x32x16_bf16 v[32:47], v[92:95], v[140:143], v[32:47]
	ds_read_b64_tr_b16 v[140:141], v196 offset:0x3600
	ds_read_b64_tr_b16 v[142:143], v196 offset:0x3e00
	s_waitcnt lgkmcnt(0)
	v_mfma_f32_32x32x16_bf16 v[48:63], v[80:83], v[128:131], v[48:63]
	s_add_i32 s5, s48, 0xffffff47
	s_mov_b64 s[0:1], -1
	s_cmp_gt_u32 s5, 0xfffffeec
	v_mfma_f32_32x32x16_bf16 v[48:63], v[84:87], v[132:135], v[48:63]
	v_mfma_f32_32x32x16_bf16 v[48:63], v[88:91], v[136:139], v[48:63]
	v_mfma_f32_32x32x16_bf16 v[48:63], v[92:95], v[140:143], v[48:63]
	s_cbranch_scc0 .Lfastp_1
; __device__ __forceinline__ void partialSM(f32x16& p0, f32x16& p1, float& m_reg, float& mn, float& alpha, int kt0, int qpos, int qw, int hi, const float* tb2, float cL, float cR) {
;     ...
;     const float* tp = tb2 + (kt0 - qpos + 192 + 4 * hi);
; #pragma unroll
;     for (int r4 = 0; r4 < 4; ++r4) {
;       float ta[4], tb[4];
; #pragma unroll
;       for (int i = 0; i < 4; ++i) { ta[i] = tp[8 * r4 + i] - m_reg; tb[i] = tp[32 + 8 * r4 + i] - m_reg; }
; #pragma unroll
;       for (int i = 0; i < 4; ++i) { p0[4 * r4 + i] = fmaf(p0[4 * r4 + i], C1, ta[i]); p1[4 * r4 + i] = fmaf(p1[4 * r4 + i], C1, tb[i]); }
	ds_read2_b32 v[80:81], v216 offset1:1
	ds_read2_b32 v[128:129], v216 offset0:32 offset1:33
	ds_read2_b32 v[130:131], v216 offset0:34 offset1:35
	ds_read2_b32 v[82:83], v216 offset0:2 offset1:3
	ds_read2_b32 v[84:85], v216 offset0:8 offset1:9
	ds_read2_b32 v[132:133], v216 offset0:40 offset1:41
	ds_read2_b32 v[134:135], v216 offset0:42 offset1:43
	ds_read2_b32 v[86:87], v216 offset0:10 offset1:11
	ds_read2_b32 v[88:89], v216 offset0:16 offset1:17
	ds_read2_b32 v[136:137], v216 offset0:48 offset1:49
	ds_read2_b32 v[138:139], v216 offset0:50 offset1:51
	ds_read2_b32 v[90:91], v216 offset0:18 offset1:19
	ds_read2_b32 v[92:93], v216 offset0:24 offset1:25
	ds_read2_b32 v[94:95], v216 offset0:26 offset1:27
	ds_read2_b32 v[140:141], v216 offset0:56 offset1:57
	ds_read2_b32 v[142:143], v216 offset0:58 offset1:59
	s_waitcnt lgkmcnt(3)
	v_sub_f32_e32 v93, v93, v79
	v_sub_f32_e32 v92, v92, v78
	s_waitcnt lgkmcnt(2)
	v_sub_f32_e32 v95, v95, v77
	v_sub_f32_e32 v94, v94, v76
	v_sub_f32_e32 v89, v89, v75
	v_sub_f32_e32 v88, v88, v72
	v_sub_f32_e32 v91, v91, v73
	v_sub_f32_e32 v90, v90, v74
	v_sub_f32_e32 v85, v85, v69
	v_sub_f32_e32 v84, v84, v68
	v_sub_f32_e32 v87, v87, v71
	v_sub_f32_e32 v86, v86, v70
	v_sub_f32_e32 v81, v81, v65
	v_sub_f32_e32 v80, v80, v64
	v_sub_f32_e32 v83, v83, v67
	v_sub_f32_e32 v82, v82, v66
	s_waitcnt lgkmcnt(1)
	v_sub_f32_e32 v141, v141, v79
	v_sub_f32_e32 v140, v140, v78
	s_waitcnt lgkmcnt(0)
	v_sub_f32_e32 v143, v143, v77
	v_sub_f32_e32 v142, v142, v76
	v_sub_f32_e32 v137, v137, v75
	v_sub_f32_e32 v136, v136, v72
	v_sub_f32_e32 v139, v139, v73
	v_sub_f32_e32 v138, v138, v74
	v_sub_f32_e32 v133, v133, v69
	v_sub_f32_e32 v132, v132, v68
	v_sub_f32_e32 v135, v135, v71
	v_sub_f32_e32 v134, v134, v70
	v_sub_f32_e32 v129, v129, v65
	v_sub_f32_e32 v128, v128, v64
	v_sub_f32_e32 v131, v131, v67
	v_sub_f32_e32 v130, v130, v66
	v_pk_fma_f32 v[82:83], v[114:115], s[6:7], v[82:83] op_sel_hi:[1,0,1]
	v_pk_fma_f32 v[80:81], v[112:113], s[6:7], v[80:81] op_sel_hi:[1,0,1]
	v_pk_fma_f32 v[86:87], v[118:119], s[6:7], v[86:87] op_sel_hi:[1,0,1]
	v_pk_fma_f32 v[84:85], v[116:117], s[6:7], v[84:85] op_sel_hi:[1,0,1]
	v_pk_fma_f32 v[90:91], v[122:123], s[6:7], v[90:91] op_sel_hi:[1,0,1]
	v_pk_fma_f32 v[88:89], v[120:121], s[6:7], v[88:89] op_sel_hi:[1,0,1]
	v_pk_fma_f32 v[94:95], v[126:127], s[6:7], v[94:95] op_sel_hi:[1,0,1]
	v_pk_fma_f32 v[92:93], v[124:125], s[6:7], v[92:93] op_sel_hi:[1,0,1]
	v_pk_fma_f32 v[130:131], v[98:99], s[6:7], v[130:131] op_sel_hi:[1,0,1]
	v_pk_fma_f32 v[128:129], v[96:97], s[6:7], v[128:129] op_sel_hi:[1,0,1]
	v_pk_fma_f32 v[134:135], v[102:103], s[6:7], v[134:135] op_sel_hi:[1,0,1]
	v_pk_fma_f32 v[132:133], v[100:101], s[6:7], v[132:133] op_sel_hi:[1,0,1]
	v_pk_fma_f32 v[138:139], v[106:107], s[6:7], v[138:139] op_sel_hi:[1,0,1]
	v_pk_fma_f32 v[136:137], v[104:105], s[6:7], v[136:137] op_sel_hi:[1,0,1]
	v_pk_fma_f32 v[142:143], v[110:111], s[6:7], v[142:143] op_sel_hi:[1,0,1]
	v_pk_fma_f32 v[140:141], v[108:109], s[6:7], v[140:141] op_sel_hi:[1,0,1]
	s_mov_b64 s[0:1], 0

; #define SBAR() __builtin_amdgcn_sched_barrier(0)
; __device__ __forceinline__ void partialSM(f32x16& p0, f32x16& p1, float& m_reg, float& mn, float& alpha, int kt0, int qpos, int qw, int hi, const float* tb2, float cL, float cR) {
;     ...
; #pragma unroll
;   for (int r = 0; r < 16; ++r) p0[r] = __builtin_amdgcn_exp2f(p0[r]);
; }
; __device__ __forceinline__ void finishSM(f32x16& p0, f32x16& p1, float alpha, float& l_reg, bf16x8& pa0, bf16x8& pa1, bf16x8& pa2, bf16x8& pa3) {
; #pragma unroll
;   for (int r = 0; r < 16; ++r) p1[r] = __builtin_amdgcn_exp2f(p1[r]);
;   float ps = 0;
; #pragma unroll
;   for (int r = 0; r < 16; ++r) ps += p0[r];
; #pragma unroll
;   for (int r = 0; r < 16; ++r) ps += p1[r];
;   { auto rr = __builtin_amdgcn_permlane32_swap(__float_as_uint(ps), __float_as_uint(ps), false, false);
;     ps = __uint_as_float(rr[0]) + __uint_as_float(rr[1]); }
;   l_reg = l_reg * alpha + ps;
;     ...
;   PK4(p0, 0, pa0); PK4(p0, 8, pa1); PK4(p1, 0, pa2); PK4(p1, 8, pa3);
;     ...
; }
; __device__ __forceinline__ void qkt(f32x16& p0, f32x16& p1, const char* Ks, const bf16x8* qr, int r32, int hi) {
;   bf16x8 ka[4], kb[4];
; #pragma unroll
;   for (int d0 = 0; d0 < 4; ++d0) { const int cb = (d0 * 16 + hi * 8) * 2;
;     ka[d0] = *reinterpret_cast<const bf16x8*>(Ks + KSWZ64(r32, cb)); kb[d0] = *reinterpret_cast<const bf16x8*>(Ks + KSWZ64(32 + r32, cb)); }
;   asm volatile("s_waitcnt lgkmcnt(0)" ::: "memory"); SBAR();
;   p0 = f32x16{}; p1 = f32x16{};
; #pragma unroll
;   for (int d0 = 0; d0 < 4; ++d0) {
;     p0 = __builtin_amdgcn_mfma_f32_32x32x16_bf16(ka[d0], qr[d0], p0, 0, 0, 0);
;     p1 = __builtin_amdgcn_mfma_f32_32x32x16_bf16(kb[d0], qr[d0], p1, 0, 0, 0); }
.LBB0_382:
	s_add_i32 s0, s4, 0
	v_exp_f32_e32 v196, v80
	v_add_u32_e32 v80, s0, v193
	s_barrier
	s_waitcnt vmcnt(2)
	ds_write_b128 v80, v[168:171]
	s_waitcnt vmcnt(1)
	ds_write_b128 v80, v[172:175] offset:8192
	v_lshl_add_u32 v80, s45, 13, v200
	v_exp_f32_e32 v197, v81
	v_exp_f32_e32 v234, v82
	v_exp_f32_e32 v235, v83
	v_exp_f32_e32 v237, v84
	v_exp_f32_e32 v238, v85
	v_exp_f32_e32 v244, v86
	v_exp_f32_e32 v245, v87
	v_exp_f32_e32 v246, v88
	v_exp_f32_e32 v247, v89
	v_exp_f32_e32 v248, v90
	v_exp_f32_e32 v249, v91
	v_exp_f32_e32 v250, v92
	v_exp_f32_e32 v251, v93
	v_exp_f32_e32 v198, v94
	v_exp_f32_e32 v199, v95
	s_waitcnt vmcnt(0)
	ds_write_b128 v80, v[176:179] offset:49152
	s_lshl_b32 s0, s49, 13
	s_add_i32 s0, s0, 0
	v_add_u32_e32 v84, s0, v203
	v_add_u32_e32 v92, s0, v206
	v_add_u32_e32 v96, s0, v208
	ds_read_b128 v[80:83], v84 offset:49152
	ds_read_b128 v[84:87], v84 offset:53248
	ds_read_b128 v[88:91], v92 offset:49152
	ds_read_b128 v[92:95], v92 offset:53248
	ds_read_b128 v[220:223], v96 offset:49152
	ds_read_b128 v[224:227], v96 offset:53248
	v_add_u32_e32 v96, s0, v209
	ds_read_b128 v[228:231], v96 offset:49152
	ds_read_b128 v[240:243], v96 offset:53248
	s_waitcnt lgkmcnt(0)
	s_waitcnt lgkmcnt(7)
	v_mfma_f32_32x32x16_bf16 v[112:127], v[80:83], v[164:167], 0
	v_add_f32_e32 v80, v197, v196
	v_add_f32_e32 v80, v234, v80
	v_add_f32_e32 v80, v235, v80
	v_add_f32_e32 v80, v237, v80
	v_add_f32_e32 v80, v238, v80
	v_add_f32_e32 v80, v244, v80
	s_waitcnt lgkmcnt(6)
	v_mfma_f32_32x32x16_bf16 v[96:111], v[84:87], v[164:167], 0
	v_add_f32_e32 v80, v245, v80
	v_add_f32_e32 v80, v246, v80
	v_add_f32_e32 v80, v247, v80
	v_add_f32_e32 v80, v248, v80
	v_add_f32_e32 v80, v249, v80
	v_exp_f32_e32 v128, v128
	v_add_f32_e32 v80, v250, v80
	s_waitcnt lgkmcnt(5)
	v_mfma_f32_32x32x16_bf16 v[112:127], v[88:91], v[160:163], v[112:127]
	v_exp_f32_e32 v129, v129
	v_add_f32_e32 v80, v251, v80
	v_exp_f32_e32 v130, v130
	v_add_f32_e32 v80, v198, v80
	v_exp_f32_e32 v131, v131
	v_add_f32_e32 v80, v199, v80
	v_exp_f32_e32 v132, v132
	s_waitcnt lgkmcnt(4)
	v_mfma_f32_32x32x16_bf16 v[96:111], v[92:95], v[160:163], v[96:111]
	v_add_f32_e32 v80, v128, v80
	v_exp_f32_e32 v133, v133
	v_add_f32_e32 v80, v129, v80
	v_exp_f32_e32 v134, v134
	v_add_f32_e32 v80, v130, v80
	v_exp_f32_e32 v135, v135
	v_add_f32_e32 v80, v131, v80
	s_waitcnt lgkmcnt(3)
	v_mfma_f32_32x32x16_bf16 v[112:127], v[220:223], v[156:159], v[112:127]
	v_exp_f32_e32 v136, v136
	v_add_f32_e32 v80, v132, v80
	v_exp_f32_e32 v137, v137
	v_add_f32_e32 v80, v133, v80
	v_exp_f32_e32 v138, v138
	v_add_f32_e32 v80, v134, v80
	v_exp_f32_e32 v139, v139
	s_waitcnt lgkmcnt(2)
	v_mfma_f32_32x32x16_bf16 v[96:111], v[224:227], v[156:159], v[96:111]
	v_add_f32_e32 v80, v135, v80
	v_exp_f32_e32 v140, v140
	v_add_f32_e32 v80, v136, v80
	v_exp_f32_e32 v141, v141
	v_add_f32_e32 v80, v137, v80
	v_exp_f32_e32 v142, v142
	v_add_f32_e32 v80, v138, v80
	s_waitcnt lgkmcnt(1)
	v_mfma_f32_32x32x16_bf16 v[112:127], v[228:231], v[152:155], v[112:127]
	v_exp_f32_e32 v143, v143
	v_add_f32_e32 v80, v139, v80
	v_add_f32_e32 v80, v140, v80
	v_add_f32_e32 v80, v141, v80
	v_add_f32_e32 v80, v142, v80
	v_add_f32_e32 v219, v143, v80
	v_mov_b32_e32 v220, v219
	s_waitcnt lgkmcnt(0)
	v_mfma_f32_32x32x16_bf16 v[96:111], v[240:243], v[152:155], v[96:111]
	v_cvt_pk_bf16_f32 v80, v196, v197
	v_cvt_pk_bf16_f32 v81, v234, v235
	v_cvt_pk_bf16_f32 v82, v237, v238
	v_cvt_pk_bf16_f32 v83, v244, v245
	v_cvt_pk_bf16_f32 v84, v246, v247
	v_cvt_pk_bf16_f32 v85, v248, v249
	v_cvt_pk_bf16_f32 v86, v250, v251
	v_cvt_pk_bf16_f32 v87, v198, v199
	v_cvt_pk_bf16_f32 v88, v128, v129
	v_cvt_pk_bf16_f32 v89, v130, v131
	v_cvt_pk_bf16_f32 v90, v132, v133
	v_cvt_pk_bf16_f32 v91, v134, v135
	v_cvt_pk_bf16_f32 v92, v136, v137
	v_cvt_pk_bf16_f32 v93, v138, v139
	v_cvt_pk_bf16_f32 v94, v140, v141
	v_cvt_pk_bf16_f32 v95, v142, v143
	v_permlane32_swap_b32_e32 v219, v220
	v_permlane32_swap_b32_e32 v80, v82
	v_permlane32_swap_b32_e32 v81, v83
	v_permlane32_swap_b32_e32 v84, v86
	v_permlane32_swap_b32_e32 v85, v87
	v_permlane32_swap_b32_e32 v88, v90
	v_permlane32_swap_b32_e32 v89, v91
	v_permlane32_swap_b32_e32 v92, v94
	v_permlane32_swap_b32_e32 v93, v95
	s_cmp_lt_u32 s50, 61
	s_cselect_b64 s[0:1], -1, 0
	s_cmp_gt_u32 s50, 60
	s_cbranch_scc1 .LBB0_384
	s_add_u32 s74, s70, 0x18e00000
	s_addc_u32 s75, s71, 0
	global_load_dwordx4 v[168:171], v182, s[74:75] offset:2048
	s_add_u32 s74, s70, 0x18e40000
	s_addc_u32 s75, s71, 0
	global_load_dwordx4 v[172:175], v182, s[74:75] offset:2048
	s_add_u32 s74, s72, 0x18e00000
	s_addc_u32 s75, s73, 0
	global_load_dwordx4 v[176:179], v184, s[74:75] offset:1152

.LBB0_388:
	s_andn2_b64 vcc, exec, s[0:1]
	s_mov_b64 s[0:1], -1
	s_barrier
	s_cbranch_vccnz .LBB0_390
	s_add_i32 s0, s4, 0
	v_add_u32_e32 v98, s0, v193
	s_add_u32 s70, s70, s16
	s_addc_u32 s71, s71, s17
	s_add_u32 s72, s72, s16
	s_addc_u32 s73, s73, s17
	s_addk_i32 s48, 0x80
	v_add_u32_e32 v216, 0x200, v216
	s_add_i32 s50, s50, 2
	s_mov_b64 s[0:1], 0
	v_add_u32_e32 v96, s36, v195
	s_waitcnt vmcnt(2)
	ds_write_b128 v98, v[168:171]
	s_waitcnt vmcnt(1)
	ds_write_b128 v98, v[172:175] offset:8192
	s_waitcnt vmcnt(0)
	ds_write_b128 v96, v[176:179] offset:49152

; __device__ __forceinline__ void finishSM(f32x16& p0, f32x16& p1, float alpha, float& l_reg, bf16x8& pa0, bf16x8& pa1, bf16x8& pa2, bf16x8& pa3) {
; #pragma unroll
;   for (int r = 0; r < 16; ++r) p1[r] = __builtin_amdgcn_exp2f(p1[r]);
;   float ps = 0;
; #pragma unroll
;   for (int r = 0; r < 16; ++r) ps += p0[r];
; #pragma unroll
;   for (int r = 0; r < 16; ++r) ps += p1[r];
;   { auto rr = __builtin_amdgcn_permlane32_swap(__float_as_uint(ps), __float_as_uint(ps), false, false);
;     ps = __uint_as_float(rr[0]) + __uint_as_float(rr[1]); }
;   l_reg = l_reg * alpha + ps;
;     ...
;   PK4(p0, 0, pa0); PK4(p0, 8, pa1); PK4(p1, 0, pa2); PK4(p1, 8, pa3);
;     ...
; }
; __device__ __forceinline__ void qkt(f32x16& p0, f32x16& p1, const char* Ks, const bf16x8* qr, int r32, int hi) {
;   bf16x8 ka[4], kb[4];
; #pragma unroll
;   for (int d0 = 0; d0 < 4; ++d0) { const int cb = (d0 * 16 + hi * 8) * 2;
;     ka[d0] = *reinterpret_cast<const bf16x8*>(Ks + KSWZ64(r32, cb)); kb[d0] = *reinterpret_cast<const bf16x8*>(Ks + KSWZ64(32 + r32, cb)); }
;   asm volatile("s_waitcnt lgkmcnt(0)" ::: "memory"); SBAR();
;   p0 = f32x16{}; p1 = f32x16{};
; #pragma unroll
;   for (int d0 = 0; d0 < 4; ++d0) {
;     p0 = __builtin_amdgcn_mfma_f32_32x32x16_bf16(ka[d0], qr[d0], p0, 0, 0, 0);
;     p1 = __builtin_amdgcn_mfma_f32_32x32x16_bf16(kb[d0], qr[d0], p1, 0, 0, 0); }
; }
; __device__ __forceinline__ int v_st(int k, int c) { const int kk = (k & ~0xC) | ((k & 4) << 1) | ((k & 8) >> 1); return ((kk >> 3) * 4 + (c >> 5)) * 512 + ((kk & 7) * 32 + (c & 31)) * 2; }
; __device__ __forceinline__ int v_rd_base(int lane) { return ((lane & 3) << 3) | (((lane >> 2) & 3) << 6) | (((lane >> 4) & 1) << 5) | (((lane >> 5) & 1) << 8); }
; template <int OFF> __device__ __forceinline__ s16x4 tr_read(int vb) {
;   s16x4 r; asm volatile("ds_read_b64_tr_b16 %0, %1 offset:%2" : "=&v"(r) : "v"(vb), "i"(OFF) : "memory"); return r;
; }
; template <int D0> __device__ __forceinline__ void pv_one(f32x16& od, int vb, bf16x8 pa0, bf16x8 pa1, bf16x8 pa2, bf16x8 pa3) {
;   const s16x4 l0 = tr_read<v_rd_off(D0, 0, 0)>(vb), h0 = tr_read<v_rd_off(D0, 0, 1)>(vb), l1 = tr_read<v_rd_off(D0, 1, 0)>(vb), h1 = tr_read<v_rd_off(D0, 1, 1)>(vb);
;   const s16x4 l2 = tr_read<v_rd_off(D0, 2, 0)>(vb), h2 = tr_read<v_rd_off(D0, 2, 1)>(vb), l3 = tr_read<v_rd_off(D0, 3, 0)>(vb), h3 = tr_read<v_rd_off(D0, 3, 1)>(vb);
.LBB0_392:
	ds_read_b128 v[96:99], v202 offset:49152
	ds_read_b128 v[100:103], v202 offset:53248
	ds_read_b128 v[136:139], v204 offset:49152
	ds_read_b128 v[140:143], v204 offset:53248
	s_waitcnt vmcnt(0)
	ds_read_b128 v[176:179], v205 offset:49152
	ds_read_b128 v[182:185], v205 offset:53248
	ds_read_b128 v[186:189], v207 offset:49152
	ds_read_b128 v[202:205], v207 offset:53248
	s_waitcnt lgkmcnt(0)
	v_exp_f32_e32 v193, v80
	v_add_f32_e32 v80, v175, v173
	s_waitcnt lgkmcnt(7)
	v_mfma_f32_32x32x16_bf16 v[112:127], v[96:99], v[164:167], 0
	v_add_f32_e32 v80, v171, v80
	v_add_f32_e32 v80, v174, v80
	v_add_f32_e32 v80, v169, v80
	v_add_f32_e32 v80, v172, v80
	v_add_f32_e32 v80, v168, v80
	v_add_f32_e32 v80, v170, v80
	v_add_f32_e32 v80, v133, v80
	s_waitcnt lgkmcnt(6)
	v_mfma_f32_32x32x16_bf16 v[96:111], v[100:103], v[164:167], 0
	v_add_f32_e32 v80, v135, v80
	v_add_f32_e32 v80, v131, v80
	v_add_f32_e32 v80, v134, v80
	v_add_f32_e32 v80, v129, v80
	v_exp_f32_e32 v194, v81
	v_add_f32_e32 v80, v132, v80
	v_exp_f32_e32 v195, v82
	s_waitcnt lgkmcnt(5)
	v_mfma_f32_32x32x16_bf16 v[112:127], v[136:139], v[160:163], v[112:127]
	v_add_f32_e32 v80, v128, v80
	v_exp_f32_e32 v196, v83
	v_add_f32_e32 v80, v130, v80
	v_exp_f32_e32 v197, v84
	v_add_f32_e32 v80, v193, v80
	v_exp_f32_e32 v200, v85
	v_add_f32_e32 v80, v194, v80
	s_waitcnt lgkmcnt(4)
	v_mfma_f32_32x32x16_bf16 v[96:111], v[140:143], v[160:163], v[96:111]
	v_exp_f32_e32 v206, v86
	v_add_f32_e32 v80, v195, v80
	v_exp_f32_e32 v207, v87
	v_add_f32_e32 v80, v196, v80
	v_exp_f32_e32 v208, v88
	v_add_f32_e32 v80, v197, v80
	v_exp_f32_e32 v209, v89
	s_waitcnt lgkmcnt(3)
	v_mfma_f32_32x32x16_bf16 v[112:127], v[176:179], v[156:159], v[112:127]
	v_add_f32_e32 v80, v200, v80
	v_exp_f32_e32 v216, v90
	v_add_f32_e32 v80, v206, v80
	v_exp_f32_e32 v217, v91
	v_add_f32_e32 v80, v207, v80
	v_exp_f32_e32 v218, v92
	v_add_f32_e32 v80, v208, v80
	s_waitcnt lgkmcnt(2)
	v_mfma_f32_32x32x16_bf16 v[96:111], v[182:185], v[156:159], v[96:111]
	v_exp_f32_e32 v164, v93
	v_add_f32_e32 v80, v209, v80
	v_exp_f32_e32 v165, v94
	v_add_f32_e32 v80, v216, v80
	v_exp_f32_e32 v95, v95
	v_add_f32_e32 v80, v217, v80
	v_add_f32_e32 v80, v218, v80
	s_waitcnt lgkmcnt(1)
	v_mfma_f32_32x32x16_bf16 v[112:127], v[186:189], v[152:155], v[112:127]
	v_add_f32_e32 v80, v164, v80
	v_add_f32_e32 v80, v165, v80
	v_add_f32_e32 v156, v95, v80
	v_mov_b32_e32 v157, v156
	v_cvt_pk_bf16_f32 v80, v173, v175
	v_cvt_pk_bf16_f32 v81, v171, v174
	v_cvt_pk_bf16_f32 v82, v169, v172
	s_waitcnt lgkmcnt(0)
	v_mfma_f32_32x32x16_bf16 v[96:111], v[202:205], v[152:155], v[96:111]
	v_cvt_pk_bf16_f32 v83, v168, v170
	v_cvt_pk_bf16_f32 v84, v133, v135
	v_cvt_pk_bf16_f32 v85, v131, v134
	v_cvt_pk_bf16_f32 v86, v129, v132
	v_cvt_pk_bf16_f32 v87, v128, v130
	v_cvt_pk_bf16_f32 v88, v193, v194
	v_cvt_pk_bf16_f32 v89, v195, v196
	v_cvt_pk_bf16_f32 v90, v197, v200
	v_cvt_pk_bf16_f32 v91, v206, v207
	v_cvt_pk_bf16_f32 v92, v208, v209
	v_cvt_pk_bf16_f32 v93, v216, v217
	v_cvt_pk_bf16_f32 v94, v218, v164
	v_cvt_pk_bf16_f32 v95, v165, v95
	v_permlane32_swap_b32_e32 v156, v157
	v_permlane32_swap_b32_e32 v80, v82
	v_permlane32_swap_b32_e32 v81, v83
	v_permlane32_swap_b32_e32 v84, v86
	v_permlane32_swap_b32_e32 v85, v87
	v_permlane32_swap_b32_e32 v88, v90
	v_permlane32_swap_b32_e32 v89, v91
	v_permlane32_swap_b32_e32 v92, v94
	v_permlane32_swap_b32_e32 v93, v95
	s_cmp_lg_u32 0, -1
	s_cselect_b32 s0, 0, 0
	s_add_i32 s0, s0, 0x8000
	v_add_u32_e32 v152, s0, v214
	ds_read_b64_tr_b16 v[128:129], v152 offset:0
	ds_read_b64_tr_b16 v[130:131], v152 offset:0x800
	ds_read_b64_tr_b16 v[132:133], v152 offset:0x1000
	ds_read_b64_tr_b16 v[134:135], v152 offset:0x1800
	ds_read_b64_tr_b16 v[136:137], v152 offset:0x2000
	ds_read_b64_tr_b16 v[138:139], v152 offset:0x2800
	ds_read_b64_tr_b16 v[140:141], v152 offset:0x3000
	ds_read_b64_tr_b16 v[142:143], v152 offset:0x3800
	s_waitcnt lgkmcnt(0)
	s_nop 0
	v_mfma_f32_32x32x16_bf16 v[0:15], v[80:83], v[128:131], v[0:15]
	ds_read_b64_tr_b16 v[128:129], v152 offset:0x200
	ds_read_b64_tr_b16 v[130:131], v152 offset:0xa00
	v_mfma_f32_32x32x16_bf16 v[0:15], v[84:87], v[132:135], v[0:15]
	ds_read_b64_tr_b16 v[132:133], v152 offset:0x1200
	ds_read_b64_tr_b16 v[134:135], v152 offset:0x1a00
	v_mfma_f32_32x32x16_bf16 v[0:15], v[88:91], v[136:139], v[0:15]
	ds_read_b64_tr_b16 v[136:137], v152 offset:0x2200
	ds_read_b64_tr_b16 v[138:139], v152 offset:0x2a00
	v_mfma_f32_32x32x16_bf16 v[0:15], v[92:95], v[140:143], v[0:15]
	ds_read_b64_tr_b16 v[140:141], v152 offset:0x3200
	ds_read_b64_tr_b16 v[142:143], v152 offset:0x3a00
	s_waitcnt lgkmcnt(0)
	v_mfma_f32_32x32x16_bf16 v[16:31], v[80:83], v[128:131], v[16:31]
	ds_read_b64_tr_b16 v[128:129], v152 offset:0x400
	ds_read_b64_tr_b16 v[130:131], v152 offset:0xc00
	v_mfma_f32_32x32x16_bf16 v[16:31], v[84:87], v[132:135], v[16:31]
	ds_read_b64_tr_b16 v[132:133], v152 offset:0x1400
	ds_read_b64_tr_b16 v[134:135], v152 offset:0x1c00
	v_mfma_f32_32x32x16_bf16 v[16:31], v[88:91], v[136:139], v[16:31]
	ds_read_b64_tr_b16 v[136:137], v152 offset:0x2400
	ds_read_b64_tr_b16 v[138:139], v152 offset:0x2c00
	v_mfma_f32_32x32x16_bf16 v[16:31], v[92:95], v[140:143], v[16:31]
	ds_read_b64_tr_b16 v[140:141], v152 offset:0x3400
	ds_read_b64_tr_b16 v[142:143], v152 offset:0x3c00
	s_waitcnt lgkmcnt(0)
	v_mfma_f32_32x32x16_bf16 v[32:47], v[80:83], v[128:131], v[32:47]
	ds_read_b64_tr_b16 v[128:129], v152 offset:0x600
	ds_read_b64_tr_b16 v[130:131], v152 offset:0xe00
	v_mfma_f32_32x32x16_bf16 v[32:47], v[84:87], v[132:135], v[32:47]
	ds_read_b64_tr_b16 v[132:133], v152 offset:0x1600
	ds_read_b64_tr_b16 v[134:135], v152 offset:0x1e00
	v_mfma_f32_32x32x16_bf16 v[32:47], v[88:91], v[136:139], v[32:47]
	ds_read_b64_tr_b16 v[136:137], v152 offset:0x2600
	ds_read_b64_tr_b16 v[138:139], v152 offset:0x2e00
	v_mfma_f32_32x32x16_bf16 v[32:47], v[92:95], v[140:143], v[32:47]
	ds_read_b64_tr_b16 v[140:141], v152 offset:0x3600
	ds_read_b64_tr_b16 v[142:143], v152 offset:0x3e00
	s_waitcnt lgkmcnt(0)
	v_mfma_f32_32x32x16_bf16 v[48:63], v[80:83], v[128:131], v[48:63]
	s_add_i32 s2, s39, 0xffffefa6
	s_mov_b64 s[0:1], -1
	s_cmp_gt_u32 s2, 0xfffffeec
	v_mfma_f32_32x32x16_bf16 v[48:63], v[84:87], v[132:135], v[48:63]
	v_mfma_f32_32x32x16_bf16 v[48:63], v[88:91], v[136:139], v[48:63]
	v_mfma_f32_32x32x16_bf16 v[48:63], v[92:95], v[140:143], v[48:63]
	s_cbranch_scc0 .Lfastp_0
; __device__ __forceinline__ void partialSM(f32x16& p0, f32x16& p1, float& m_reg, float& mn, float& alpha, int kt0, int qpos, int qw, int hi, const float* tb2, float cL, float cR) {
;     ...
;     const float* tp = tb2 + (kt0 - qpos + 192 + 4 * hi);
; #pragma unroll
;     for (int r4 = 0; r4 < 4; ++r4) {
;       float ta[4], tb[4];
; #pragma unroll
;       for (int i = 0; i < 4; ++i) { ta[i] = tp[8 * r4 + i] - m_reg; tb[i] = tp[32 + 8 * r4 + i] - m_reg; }
; #pragma unroll
;       for (int i = 0; i < 4; ++i) { p0[4 * r4 + i] = fmaf(p0[4 * r4 + i], C1, ta[i]); p1[4 * r4 + i] = fmaf(p1[4 * r4 + i], C1, tb[i]); }
	v_sub_u32_e32 v80, 0xfc0, v192
	s_add_i32 s0, 0, 0x12b00
	v_lshlrev_b32_e32 v80, 2, v80
	v_add3_u32 v140, s0, v180, v80
	ds_read2_b32 v[80:81], v140 offset1:1
	ds_read2_b32 v[128:129], v140 offset0:32 offset1:33
	ds_read2_b32 v[130:131], v140 offset0:34 offset1:35
	ds_read2_b32 v[82:83], v140 offset0:2 offset1:3
	ds_read2_b32 v[84:85], v140 offset0:8 offset1:9
	ds_read2_b32 v[132:133], v140 offset0:40 offset1:41
	ds_read2_b32 v[134:135], v140 offset0:42 offset1:43
	ds_read2_b32 v[86:87], v140 offset0:10 offset1:11
	ds_read2_b32 v[88:89], v140 offset0:16 offset1:17
	ds_read2_b32 v[136:137], v140 offset0:48 offset1:49
	ds_read2_b32 v[138:139], v140 offset0:50 offset1:51
	ds_read2_b32 v[90:91], v140 offset0:18 offset1:19
	ds_read2_b32 v[92:93], v140 offset0:24 offset1:25
	ds_read2_b32 v[94:95], v140 offset0:56 offset1:57
	s_waitcnt lgkmcnt(5)
	v_sub_f32_e32 v89, v89, v75
	s_waitcnt lgkmcnt(4)
	v_sub_f32_e32 v137, v137, v75
	v_sub_f32_e32 v88, v88, v72
	s_waitcnt lgkmcnt(1)
	v_sub_f32_e32 v93, v93, v79
	s_waitcnt lgkmcnt(0)
	v_sub_f32_e32 v79, v95, v79
	v_sub_f32_e32 v92, v92, v78
	v_sub_f32_e32 v78, v94, v78
	ds_read2_b32 v[94:95], v140 offset0:26 offset1:27
	ds_read2_b32 v[140:141], v140 offset0:58 offset1:59
	v_sub_f32_e32 v91, v91, v73
	v_sub_f32_e32 v90, v90, v74
	s_waitcnt lgkmcnt(1)
	v_sub_f32_e32 v95, v95, v77
	s_waitcnt lgkmcnt(0)
	v_sub_f32_e32 v77, v141, v77
	v_sub_f32_e32 v94, v94, v76
	v_sub_f32_e32 v76, v140, v76
	v_sub_f32_e32 v85, v85, v69
	v_sub_f32_e32 v84, v84, v68
	v_sub_f32_e32 v87, v87, v71
	v_sub_f32_e32 v86, v86, v70
	v_sub_f32_e32 v81, v81, v65
	v_sub_f32_e32 v80, v80, v64
	v_sub_f32_e32 v83, v83, v67
	v_sub_f32_e32 v82, v82, v66
	v_sub_f32_e32 v136, v136, v72
	v_sub_f32_e32 v73, v139, v73
	v_sub_f32_e32 v72, v138, v74
	v_sub_f32_e32 v69, v133, v69
	v_sub_f32_e32 v68, v132, v68
	v_sub_f32_e32 v71, v135, v71
	v_sub_f32_e32 v70, v134, v70
	v_sub_f32_e32 v75, v129, v65
	v_sub_f32_e32 v74, v128, v64
	v_sub_f32_e32 v67, v131, v67
	v_sub_f32_e32 v66, v130, v66
	v_pk_fma_f32 v[82:83], v[114:115], s[6:7], v[82:83] op_sel_hi:[1,0,1]
	v_pk_fma_f32 v[80:81], v[112:113], s[6:7], v[80:81] op_sel_hi:[1,0,1]
	v_pk_fma_f32 v[86:87], v[118:119], s[6:7], v[86:87] op_sel_hi:[1,0,1]
	v_pk_fma_f32 v[84:85], v[116:117], s[6:7], v[84:85] op_sel_hi:[1,0,1]
	v_pk_fma_f32 v[90:91], v[122:123], s[6:7], v[90:91] op_sel_hi:[1,0,1]
	v_pk_fma_f32 v[88:89], v[120:121], s[6:7], v[88:89] op_sel_hi:[1,0,1]
	v_pk_fma_f32 v[94:95], v[126:127], s[6:7], v[94:95] op_sel_hi:[1,0,1]
	v_pk_fma_f32 v[92:93], v[124:125], s[6:7], v[92:93] op_sel_hi:[1,0,1]
	v_pk_fma_f32 v[130:131], v[98:99], s[6:7], v[66:67] op_sel_hi:[1,0,1]
	v_pk_fma_f32 v[128:129], v[96:97], s[6:7], v[74:75] op_sel_hi:[1,0,1]
	v_pk_fma_f32 v[134:135], v[102:103], s[6:7], v[70:71] op_sel_hi:[1,0,1]
	v_pk_fma_f32 v[132:133], v[100:101], s[6:7], v[68:69] op_sel_hi:[1,0,1]
	v_pk_fma_f32 v[138:139], v[106:107], s[6:7], v[72:73] op_sel_hi:[1,0,1]
	v_pk_fma_f32 v[136:137], v[104:105], s[6:7], v[136:137] op_sel_hi:[1,0,1]
	v_pk_fma_f32 v[142:143], v[110:111], s[6:7], v[76:77] op_sel_hi:[1,0,1]
	v_pk_fma_f32 v[140:141], v[108:109], s[6:7], v[78:79] op_sel_hi:[1,0,1]
	s_mov_b64 s[0:1], 0
